# k19 plus GEMM load segments reordered to issue their 8 LDS fragment reads first after the barrier, DMA address and m0 setup after them
# speedup vs baseline: 1.0064x; 1.0064x over previous
; #define PG8_STAGE(bufoff, gbase, voff) do { _Pragma("unroll") for (int _i = 0; _i < 2; ++_i) \
;         __builtin_amdgcn_global_load_lds((const unsigned*)((const char*)(gbase) + (voff)[_i]), (PG8_LAS unsigned*)(lds + (bufoff) + ldsw + _i * 8192), 16, 0, 0); } while (0)
; #define PG8_LDA(dst, b, h) do { _Pragma("unroll") for (int m = 0; m < 4; ++m) _Pragma("unroll") for (int k = 0; k < 2; ++k) dst[m][k] = *(const PG8_LAS bf16x8*)(lds + PG8_SA(b, h) + aoff + m * 2048 + k * 1024); } while (0)
; #define PG8_LDB(dst, b, h) do { _Pragma("unroll") for (int n = 0; n < 2; ++n) _Pragma("unroll") for (int k = 0; k < 2; ++k) dst[n][k] = *(const PG8_LAS bf16x8*)(lds + PG8_SB(b, h) + boff + n * 2048 + k * 1024); } while (0)
; #define PG8_MMA(ai, bj, At, Bt) do { __builtin_amdgcn_s_setprio(1); _Pragma("unroll") for (int m = 0; m < 4; ++m) _Pragma("unroll") for (int n = 0; n < 2; ++n) _Pragma("unroll") for (int k = 0; k < 2; ++k) \
;         acc[ai][bj][m][n] = __builtin_amdgcn_mfma_f32_16x16x32_bf16(Bt[n][k], At[m][k], acc[ai][bj][m][n], 0, 0, 0); __builtin_amdgcn_s_setprio(0); } while (0)
; #define PG8_WAIT_V(n) asm volatile("s_waitcnt vmcnt(" #n ")" ::: "memory")
; #define PG8_WAIT_L(n) asm volatile("s_waitcnt lgkmcnt(" #n ")" ::: "memory")
; #define PG8_BAR __builtin_amdgcn_s_barrier()
; #define PG8_SCHED __builtin_amdgcn_sched_barrier(0)
; template <class Epi, class Sched, bool ALIGN_EPI = false, bool SP2 = false>
; __device__ __forceinline__ void gemm_phase(PG8_LAS unsigned char* lds, const Gemm g, const Sched& S, const Epi& E, const int wv0) {
;     ...
;             PG8_LDB(B0, 0, 0); PG8_LDB(B1, 0, 1); PG8_SCHED; PG8_LDA(At, 0, 0); PG8_STAGE(PG8_SA(1, 1), a1 + hstepA, voffA);
;             PG8_WAIT_V(8); PG8_WAIT_L(0); PG8_BAR; PG8_MMA(0, 0, At, B0); PG8_MMA(0, 1, At, B1); PG8_BAR; PG8_SCHED;
;             PG8_LDA(At, 0, 1); PG8_STAGE(PG8_SB(0, 0), b2, voffB); PG8_STAGE(PG8_SB(0, 1), b2 + hstepB, voffB); PG8_STAGE(PG8_SA(0, 0), a2, voffA);
;             PG8_WAIT_V(8); PG8_WAIT_L(0); PG8_BAR; PG8_MMA(1, 0, At, B0); PG8_MMA(1, 1, At, B1); PG8_BAR; PG8_SCHED;
.LBB0_82:
	ds_read_b128 v[156:159], v152
	ds_read_b128 v[160:163], v152 offset:1024
	ds_read_b128 v[164:167], v152 offset:2048
	ds_read_b128 v[168:171], v152 offset:3072
	ds_read_b128 v[172:175], v153
	ds_read_b128 v[176:179], v153 offset:1024
	ds_read_b128 v[180:183], v153 offset:2048
	ds_read_b128 v[184:187], v153 offset:3072
	s_add_u32 s34, s30, 0xfff80080
	s_addc_u32 s35, s31, -1
	s_cmp_eq_u32 s38, 28
	s_cselect_b32 s37, s25, s35
	s_cselect_b32 s36, s24, s34
	s_cselect_b32 s35, s27, s23
	s_cselect_b32 s34, s26, s21
	v_lshl_add_u64 v[146:147], s[30:31], 0, v[140:141]
	s_add_i32 m0, s29, 0xc000
	ds_read_b128 v[188:191], v154
	ds_read_b128 v[192:195], v154 offset:1024
	ds_read_b128 v[196:199], v154 offset:2048
	ds_read_b128 v[200:203], v154 offset:3072
	ds_read_b128 v[206:209], v154 offset:4096
	ds_read_b128 v[210:213], v154 offset:5120
	ds_read_b128 v[214:217], v154 offset:6144
	ds_read_b128 v[218:221], v154 offset:7168
	global_load_lds_dwordx4 v[146:147], off
	v_lshl_add_u64 v[146:147], s[30:31], 0, v[138:139]
	s_add_i32 m0, s29, 0xe000
	s_nop 0
	global_load_lds_dwordx4 v[146:147], off
	s_waitcnt vmcnt(8)
	s_waitcnt lgkmcnt(0)
	s_barrier
	v_mfma_f32_16x16x32_bf16 v[124:127], v[156:159], v[188:191], v[124:127]
	v_mfma_f32_16x16x32_bf16 v[120:123], v[164:167], v[188:191], v[120:123]
	v_mfma_f32_16x16x32_bf16 v[116:119], v[156:159], v[196:199], v[116:119]
	v_mfma_f32_16x16x32_bf16 v[108:111], v[164:167], v[196:199], v[108:111]
	v_mfma_f32_16x16x32_bf16 v[100:103], v[156:159], v[206:209], v[100:103]
	v_mfma_f32_16x16x32_bf16 v[92:95], v[164:167], v[206:209], v[92:95]
	v_mfma_f32_16x16x32_bf16 v[84:87], v[156:159], v[214:217], v[84:87]
	v_mfma_f32_16x16x32_bf16 v[76:79], v[164:167], v[214:217], v[76:79]
	v_mfma_f32_16x16x32_bf16 v[124:127], v[160:163], v[192:195], v[124:127]
	v_mfma_f32_16x16x32_bf16 v[120:123], v[168:171], v[192:195], v[120:123]
	v_mfma_f32_16x16x32_bf16 v[116:119], v[160:163], v[200:203], v[116:119]
	v_mfma_f32_16x16x32_bf16 v[108:111], v[168:171], v[200:203], v[108:111]
	v_mfma_f32_16x16x32_bf16 v[100:103], v[160:163], v[210:213], v[100:103]
	v_mfma_f32_16x16x32_bf16 v[92:95], v[168:171], v[210:213], v[92:95]
	v_mfma_f32_16x16x32_bf16 v[84:87], v[160:163], v[218:221], v[84:87]
	v_mfma_f32_16x16x32_bf16 v[76:79], v[168:171], v[218:221], v[76:79]
	v_mfma_f32_16x16x32_bf16 v[112:115], v[172:175], v[188:191], v[112:115]
	v_mfma_f32_16x16x32_bf16 v[104:107], v[180:183], v[188:191], v[104:107]
	v_mfma_f32_16x16x32_bf16 v[96:99], v[172:175], v[196:199], v[96:99]
	v_mfma_f32_16x16x32_bf16 v[88:91], v[180:183], v[196:199], v[88:91]
	v_mfma_f32_16x16x32_bf16 v[80:83], v[172:175], v[206:209], v[80:83]
	v_mfma_f32_16x16x32_bf16 v[72:75], v[180:183], v[206:209], v[72:75]
	v_mfma_f32_16x16x32_bf16 v[68:71], v[172:175], v[214:217], v[68:71]
	v_mfma_f32_16x16x32_bf16 v[64:67], v[180:183], v[214:217], v[64:67]
	v_mfma_f32_16x16x32_bf16 v[112:115], v[176:179], v[192:195], v[112:115]
	v_mfma_f32_16x16x32_bf16 v[104:107], v[184:187], v[192:195], v[104:107]
	v_mfma_f32_16x16x32_bf16 v[96:99], v[176:179], v[200:203], v[96:99]
	v_mfma_f32_16x16x32_bf16 v[88:91], v[184:187], v[200:203], v[88:91]
	v_mfma_f32_16x16x32_bf16 v[80:83], v[176:179], v[210:213], v[80:83]
	v_mfma_f32_16x16x32_bf16 v[72:75], v[184:187], v[210:213], v[72:75]
	v_mfma_f32_16x16x32_bf16 v[68:71], v[176:179], v[218:221], v[68:71]
	v_mfma_f32_16x16x32_bf16 v[64:67], v[184:187], v[218:221], v[64:67]
	s_barrier
	ds_read_b128 v[188:191], v154 offset:16384
	ds_read_b128 v[192:195], v154 offset:17408
	ds_read_b128 v[196:199], v154 offset:18432
	ds_read_b128 v[200:203], v154 offset:19456
	ds_read_b128 v[206:209], v154 offset:20480
	ds_read_b128 v[210:213], v154 offset:21504
	ds_read_b128 v[214:217], v154 offset:22528
	ds_read_b128 v[218:221], v154 offset:23552
	s_add_i32 s39, s62, s47
	s_mov_b32 m0, s39
	v_lshl_add_u64 v[146:147], s[34:35], 0, v[132:133]
	global_load_lds_dwordx4 v[146:147], off
	s_add_i32 m0, s39, 0x2000
	s_add_u32 s68, s34, 0x80000
	v_lshl_add_u64 v[222:223], s[34:35], 0, v[128:129]
	s_addc_u32 s69, s35, 0
	s_add_i32 s39, s63, s47
	global_load_lds_dwordx4 v[222:223], off
	v_lshl_add_u64 v[224:225], s[68:69], 0, v[132:133]
	s_mov_b32 m0, s39
	v_lshl_add_u64 v[226:227], s[36:37], 0, v[130:131]
	global_load_lds_dwordx4 v[224:225], off
	v_lshl_add_u64 v[224:225], s[68:69], 0, v[128:129]
	s_add_i32 m0, s39, 0x2000
	s_nop 0
	global_load_lds_dwordx4 v[224:225], off
	v_lshl_add_u64 v[224:225], s[36:37], 0, v[134:135]
	s_mov_b32 m0, s29
	s_nop 0
	global_load_lds_dwordx4 v[224:225], off
	s_mov_b32 m0, s49
	s_nop 0
	global_load_lds_dwordx4 v[226:227], off
	s_waitcnt vmcnt(8)
	s_waitcnt lgkmcnt(0)
	s_barrier
; #define PG8_STAGE(bufoff, gbase, voff) do { _Pragma("unroll") for (int _i = 0; _i < 2; ++_i) \
;         __builtin_amdgcn_global_load_lds((const unsigned*)((const char*)(gbase) + (voff)[_i]), (PG8_LAS unsigned*)(lds + (bufoff) + ldsw + _i * 8192), 16, 0, 0); } while (0)
; #define PG8_LDA(dst, b, h) do { _Pragma("unroll") for (int m = 0; m < 4; ++m) _Pragma("unroll") for (int k = 0; k < 2; ++k) dst[m][k] = *(const PG8_LAS bf16x8*)(lds + PG8_SA(b, h) + aoff + m * 2048 + k * 1024); } while (0)
; #define PG8_LDB(dst, b, h) do { _Pragma("unroll") for (int n = 0; n < 2; ++n) _Pragma("unroll") for (int k = 0; k < 2; ++k) dst[n][k] = *(const PG8_LAS bf16x8*)(lds + PG8_SB(b, h) + boff + n * 2048 + k * 1024); } while (0)
; #define PG8_MMA(ai, bj, At, Bt) do { __builtin_amdgcn_s_setprio(1); _Pragma("unroll") for (int m = 0; m < 4; ++m) _Pragma("unroll") for (int n = 0; n < 2; ++n) _Pragma("unroll") for (int k = 0; k < 2; ++k) \
;         acc[ai][bj][m][n] = __builtin_amdgcn_mfma_f32_16x16x32_bf16(Bt[n][k], At[m][k], acc[ai][bj][m][n], 0, 0, 0); __builtin_amdgcn_s_setprio(0); } while (0)
; #define PG8_WAIT_V(n) asm volatile("s_waitcnt vmcnt(" #n ")" ::: "memory")
; #define PG8_WAIT_L(n) asm volatile("s_waitcnt lgkmcnt(" #n ")" ::: "memory")
; #define PG8_BAR __builtin_amdgcn_s_barrier()
; #define PG8_SCHED __builtin_amdgcn_sched_barrier(0)
; template <class Epi, class Sched, bool ALIGN_EPI = false, bool SP2 = false>
; __device__ __forceinline__ void gemm_phase(PG8_LAS unsigned char* lds, const Gemm g, const Sched& S, const Epi& E, const int wv0) {
;     ...
;             PG8_WAIT_V(8); PG8_WAIT_L(0); PG8_BAR; PG8_MMA(1, 0, At, B0); PG8_MMA(1, 1, At, B1); PG8_BAR; PG8_SCHED;
;             PG8_LDB(B0, 1, 0); PG8_LDB(B1, 1, 1); PG8_SCHED; PG8_LDA(At, 1, 0); PG8_STAGE(PG8_SA(0, 1), a2 + hstepA, voffA);
;             PG8_WAIT_V(8); PG8_WAIT_L(0); PG8_BAR; PG8_MMA(0, 0, At, B0); PG8_MMA(0, 1, At, B1); PG8_BAR; PG8_SCHED;
	v_mfma_f32_16x16x32_bf16 v[60:63], v[156:159], v[188:191], v[60:63]
	v_mfma_f32_16x16x32_bf16 v[56:59], v[164:167], v[188:191], v[56:59]
	v_mfma_f32_16x16x32_bf16 v[52:55], v[156:159], v[196:199], v[52:55]
	v_mfma_f32_16x16x32_bf16 v[44:47], v[164:167], v[196:199], v[44:47]
	v_mfma_f32_16x16x32_bf16 v[36:39], v[156:159], v[206:209], v[36:39]
	v_mfma_f32_16x16x32_bf16 v[28:31], v[164:167], v[206:209], v[28:31]
	v_mfma_f32_16x16x32_bf16 v[20:23], v[156:159], v[214:217], v[20:23]
	v_mfma_f32_16x16x32_bf16 v[12:15], v[164:167], v[214:217], v[12:15]
	v_mfma_f32_16x16x32_bf16 v[60:63], v[160:163], v[192:195], v[60:63]
	v_mfma_f32_16x16x32_bf16 v[56:59], v[168:171], v[192:195], v[56:59]
	v_mfma_f32_16x16x32_bf16 v[52:55], v[160:163], v[200:203], v[52:55]
	v_mfma_f32_16x16x32_bf16 v[44:47], v[168:171], v[200:203], v[44:47]
	v_mfma_f32_16x16x32_bf16 v[36:39], v[160:163], v[210:213], v[36:39]
	v_mfma_f32_16x16x32_bf16 v[28:31], v[168:171], v[210:213], v[28:31]
	v_mfma_f32_16x16x32_bf16 v[20:23], v[160:163], v[218:221], v[20:23]
	v_mfma_f32_16x16x32_bf16 v[12:15], v[168:171], v[218:221], v[12:15]
	v_mfma_f32_16x16x32_bf16 v[48:51], v[172:175], v[188:191], v[48:51]
	v_mfma_f32_16x16x32_bf16 v[40:43], v[180:183], v[188:191], v[40:43]
	v_mfma_f32_16x16x32_bf16 v[32:35], v[172:175], v[196:199], v[32:35]
	v_mfma_f32_16x16x32_bf16 v[24:27], v[180:183], v[196:199], v[24:27]
	v_mfma_f32_16x16x32_bf16 v[16:19], v[172:175], v[206:209], v[16:19]
	v_mfma_f32_16x16x32_bf16 v[8:11], v[180:183], v[206:209], v[8:11]
	v_mfma_f32_16x16x32_bf16 v[4:7], v[172:175], v[214:217], v[4:7]
	v_mfma_f32_16x16x32_bf16 v[0:3], v[180:183], v[214:217], v[0:3]
	v_mfma_f32_16x16x32_bf16 v[48:51], v[176:179], v[192:195], v[48:51]
	v_mfma_f32_16x16x32_bf16 v[40:43], v[184:187], v[192:195], v[40:43]
	v_mfma_f32_16x16x32_bf16 v[32:35], v[176:179], v[200:203], v[32:35]
	v_mfma_f32_16x16x32_bf16 v[24:27], v[184:187], v[200:203], v[24:27]
	v_mfma_f32_16x16x32_bf16 v[16:19], v[176:179], v[210:213], v[16:19]
	v_mfma_f32_16x16x32_bf16 v[8:11], v[184:187], v[210:213], v[8:11]
	v_mfma_f32_16x16x32_bf16 v[4:7], v[176:179], v[218:221], v[4:7]
	v_mfma_f32_16x16x32_bf16 v[0:3], v[184:187], v[218:221], v[0:3]
	s_barrier
	s_add_i32 s39, 0, 0x18000
	v_add_u32_e32 v155, s39, v150
	s_add_i32 s68, 0, 0x1c000
	ds_read_b128 v[156:159], v155
	ds_read_b128 v[160:163], v155 offset:1024
	ds_read_b128 v[164:167], v155 offset:2048
	ds_read_b128 v[168:171], v155 offset:3072
	v_add_u32_e32 v155, s68, v150
	ds_read_b128 v[172:175], v155
	ds_read_b128 v[176:179], v155 offset:1024
	ds_read_b128 v[180:183], v155 offset:2048
	ds_read_b128 v[184:187], v155 offset:3072
	s_add_u32 s36, s36, 0x80000
	s_addc_u32 s37, s37, 0
	s_mov_b32 m0, s50
	v_lshl_add_u64 v[228:229], s[36:37], 0, v[134:135]
	ds_read_b128 v[188:191], v154 offset:32768
	ds_read_b128 v[192:195], v154 offset:33792
	ds_read_b128 v[196:199], v154 offset:34816
	ds_read_b128 v[200:203], v154 offset:35840
	ds_read_b128 v[206:209], v154 offset:36864
	ds_read_b128 v[210:213], v154 offset:37888
	ds_read_b128 v[214:217], v154 offset:38912
	ds_read_b128 v[218:221], v154 offset:39936
	global_load_lds_dwordx4 v[228:229], off
	v_lshl_add_u64 v[228:229], s[36:37], 0, v[130:131]
	s_mov_b32 m0, s51
	s_nop 0
	global_load_lds_dwordx4 v[228:229], off
	s_waitcnt vmcnt(8)
	s_waitcnt lgkmcnt(0)
	s_barrier
	v_mfma_f32_16x16x32_bf16 v[124:127], v[156:159], v[188:191], v[124:127]
	v_mfma_f32_16x16x32_bf16 v[120:123], v[164:167], v[188:191], v[120:123]
	v_mfma_f32_16x16x32_bf16 v[116:119], v[156:159], v[196:199], v[116:119]
	v_mfma_f32_16x16x32_bf16 v[108:111], v[164:167], v[196:199], v[108:111]
	v_mfma_f32_16x16x32_bf16 v[100:103], v[156:159], v[206:209], v[100:103]
	v_mfma_f32_16x16x32_bf16 v[92:95], v[164:167], v[206:209], v[92:95]
	v_mfma_f32_16x16x32_bf16 v[84:87], v[156:159], v[214:217], v[84:87]
	v_mfma_f32_16x16x32_bf16 v[76:79], v[164:167], v[214:217], v[76:79]
	v_mfma_f32_16x16x32_bf16 v[124:127], v[160:163], v[192:195], v[124:127]
	v_mfma_f32_16x16x32_bf16 v[120:123], v[168:171], v[192:195], v[120:123]
	v_mfma_f32_16x16x32_bf16 v[116:119], v[160:163], v[200:203], v[116:119]
	v_mfma_f32_16x16x32_bf16 v[108:111], v[168:171], v[200:203], v[108:111]
	v_mfma_f32_16x16x32_bf16 v[100:103], v[160:163], v[210:213], v[100:103]
	v_mfma_f32_16x16x32_bf16 v[92:95], v[168:171], v[210:213], v[92:95]
	v_mfma_f32_16x16x32_bf16 v[84:87], v[160:163], v[218:221], v[84:87]
	v_mfma_f32_16x16x32_bf16 v[76:79], v[168:171], v[218:221], v[76:79]
	v_mfma_f32_16x16x32_bf16 v[112:115], v[172:175], v[188:191], v[112:115]
	v_mfma_f32_16x16x32_bf16 v[104:107], v[180:183], v[188:191], v[104:107]
	v_mfma_f32_16x16x32_bf16 v[96:99], v[172:175], v[196:199], v[96:99]
	v_mfma_f32_16x16x32_bf16 v[88:91], v[180:183], v[196:199], v[88:91]
	v_mfma_f32_16x16x32_bf16 v[80:83], v[172:175], v[206:209], v[80:83]
	v_mfma_f32_16x16x32_bf16 v[72:75], v[180:183], v[206:209], v[72:75]
	v_mfma_f32_16x16x32_bf16 v[68:71], v[172:175], v[214:217], v[68:71]
	v_mfma_f32_16x16x32_bf16 v[64:67], v[180:183], v[214:217], v[64:67]
	v_mfma_f32_16x16x32_bf16 v[112:115], v[176:179], v[192:195], v[112:115]
	v_mfma_f32_16x16x32_bf16 v[104:107], v[184:187], v[192:195], v[104:107]
	v_mfma_f32_16x16x32_bf16 v[96:99], v[176:179], v[200:203], v[96:99]
	v_mfma_f32_16x16x32_bf16 v[88:91], v[184:187], v[200:203], v[88:91]
	v_mfma_f32_16x16x32_bf16 v[80:83], v[176:179], v[210:213], v[80:83]
	v_mfma_f32_16x16x32_bf16 v[72:75], v[184:187], v[210:213], v[72:75]
	v_mfma_f32_16x16x32_bf16 v[68:71], v[176:179], v[218:221], v[68:71]
	v_mfma_f32_16x16x32_bf16 v[64:67], v[184:187], v[218:221], v[64:67]
	s_barrier
; #define PG8_STAGE(bufoff, gbase, voff) do { _Pragma("unroll") for (int _i = 0; _i < 2; ++_i) \
;         __builtin_amdgcn_global_load_lds((const unsigned*)((const char*)(gbase) + (voff)[_i]), (PG8_LAS unsigned*)(lds + (bufoff) + ldsw + _i * 8192), 16, 0, 0); } while (0)
; #define PG8_LDA(dst, b, h) do { _Pragma("unroll") for (int m = 0; m < 4; ++m) _Pragma("unroll") for (int k = 0; k < 2; ++k) dst[m][k] = *(const PG8_LAS bf16x8*)(lds + PG8_SA(b, h) + aoff + m * 2048 + k * 1024); } while (0)
; #define PG8_LDB(dst, b, h) do { _Pragma("unroll") for (int n = 0; n < 2; ++n) _Pragma("unroll") for (int k = 0; k < 2; ++k) dst[n][k] = *(const PG8_LAS bf16x8*)(lds + PG8_SB(b, h) + boff + n * 2048 + k * 1024); } while (0)
; template <class Epi, class Sched, bool ALIGN_EPI = false, bool SP2 = false>
; __device__ __forceinline__ void gemm_phase(PG8_LAS unsigned char* lds, const Gemm g, const Sched& S, const Epi& E, const int wv0) {
;     ...
;         for (int t = 0; t < nt; t += 2) {
;             const bool last = (t == nt - 2);
;             const char* a1 = cA + (size_t)(t + 1) * kstep;
;             const char* a2 = last ? nA : cA + (size_t)(t + 2) * kstep; const char* b2 = last ? nB : cB + (size_t)(t + 2) * kstep;
;             const char* a3 = a2 + kstep; const char* b3 = b2 + kstep;
;             if constexpr (SP2) {
;             PG8_LDB(B0, 0, 0); PG8_LDB(B1, 0, 1); PG8_SCHED; PG8_LDA(At, 0, 0); PG8_STAGE(PG8_SA(1, 1), a1 + hstepA, voffA);
;             PG8_WAIT_V(8); PG8_WAIT_L(0); PG8_BAR; PG8_MMA(0, 0, At, B0); PG8_MMA(0, 1, At, B1); PG8_BAR; PG8_SCHED;
;             PG8_LDA(At, 0, 1); PG8_STAGE(PG8_SB(0, 0), b2, voffB); PG8_STAGE(PG8_SB(0, 1), b2 + hstepB, voffB); PG8_STAGE(PG8_SA(0, 0), a2, voffA);
;             PG8_WAIT_V(8); PG8_WAIT_L(0); PG8_BAR; PG8_MMA(1, 0, At, B0); PG8_MMA(1, 1, At, B1); PG8_BAR; PG8_SCHED;
;             PG8_LDB(B0, 1, 0); PG8_LDB(B1, 1, 1); PG8_SCHED; PG8_LDA(At, 1, 0); PG8_STAGE(PG8_SA(0, 1), a2 + hstepA, voffA);
;             PG8_WAIT_V(8); PG8_WAIT_L(0); PG8_BAR; PG8_MMA(0, 0, At, B0); PG8_MMA(0, 1, At, B1); PG8_BAR; PG8_SCHED;
;             PG8_LDA(At, 1, 1); PG8_STAGE(PG8_SB(1, 0), b3, voffB); PG8_STAGE(PG8_SB(1, 1), b3 + hstepB, voffB); PG8_STAGE(PG8_SA(1, 0), a3, voffA);
;             PG8_WAIT_V(8); PG8_WAIT_L(0); PG8_BAR; PG8_MMA(1, 0, At, B0); PG8_MMA(1, 1, At, B1); PG8_BAR; PG8_SCHED;
	ds_read_b128 v[188:191], v154 offset:49152
	ds_read_b128 v[192:195], v154 offset:50176
	ds_read_b128 v[196:199], v154 offset:51200
	ds_read_b128 v[200:203], v154 offset:52224
	ds_read_b128 v[206:209], v154 offset:53248
	ds_read_b128 v[210:213], v154 offset:54272
	ds_read_b128 v[214:217], v154 offset:55296
	ds_read_b128 v[218:221], v154 offset:56320
	s_add_i32 s36, s39, s47
	s_mov_b32 m0, s36
	v_lshl_add_u64 v[146:147], v[146:147], 0, s[14:15]
	global_load_lds_dwordx4 v[146:147], off
	s_add_i32 m0, s36, 0x2000
	s_add_u32 s34, s34, 0x80080
	v_lshl_add_u64 v[146:147], v[222:223], 0, s[14:15]
	s_addc_u32 s35, s35, 0
	s_add_i32 s36, s68, s47
	global_load_lds_dwordx4 v[146:147], off
	v_lshl_add_u64 v[146:147], s[34:35], 0, v[132:133]
	s_mov_b32 m0, s36
	s_nop 0
	global_load_lds_dwordx4 v[146:147], off
	v_lshl_add_u64 v[146:147], s[34:35], 0, v[128:129]
	s_add_i32 m0, s36, 0x2000
	s_nop 0
	global_load_lds_dwordx4 v[146:147], off
	v_lshl_add_u64 v[146:147], v[224:225], 0, s[14:15]
	s_mov_b32 m0, s58
	s_nop 0
	global_load_lds_dwordx4 v[146:147], off
	v_lshl_add_u64 v[146:147], v[226:227], 0, s[14:15]
	s_mov_b32 m0, s59
	s_nop 0
	global_load_lds_dwordx4 v[146:147], off
	s_waitcnt vmcnt(8)
	s_waitcnt lgkmcnt(0)
	s_barrier
	v_mfma_f32_16x16x32_bf16 v[60:63], v[156:159], v[188:191], v[60:63]
	v_mfma_f32_16x16x32_bf16 v[56:59], v[164:167], v[188:191], v[56:59]
	v_mfma_f32_16x16x32_bf16 v[52:55], v[156:159], v[196:199], v[52:55]
	v_mfma_f32_16x16x32_bf16 v[44:47], v[164:167], v[196:199], v[44:47]
	v_mfma_f32_16x16x32_bf16 v[36:39], v[156:159], v[206:209], v[36:39]
	v_mfma_f32_16x16x32_bf16 v[28:31], v[164:167], v[206:209], v[28:31]
	v_mfma_f32_16x16x32_bf16 v[20:23], v[156:159], v[214:217], v[20:23]
	v_mfma_f32_16x16x32_bf16 v[12:15], v[164:167], v[214:217], v[12:15]
	v_mfma_f32_16x16x32_bf16 v[60:63], v[160:163], v[192:195], v[60:63]
	v_mfma_f32_16x16x32_bf16 v[56:59], v[168:171], v[192:195], v[56:59]
	v_mfma_f32_16x16x32_bf16 v[52:55], v[160:163], v[200:203], v[52:55]
	v_mfma_f32_16x16x32_bf16 v[44:47], v[168:171], v[200:203], v[44:47]
	v_mfma_f32_16x16x32_bf16 v[36:39], v[160:163], v[210:213], v[36:39]
	v_mfma_f32_16x16x32_bf16 v[28:31], v[168:171], v[210:213], v[28:31]
	v_mfma_f32_16x16x32_bf16 v[20:23], v[160:163], v[218:221], v[20:23]
	v_mfma_f32_16x16x32_bf16 v[12:15], v[168:171], v[218:221], v[12:15]
	v_mfma_f32_16x16x32_bf16 v[48:51], v[172:175], v[188:191], v[48:51]
	v_mfma_f32_16x16x32_bf16 v[40:43], v[180:183], v[188:191], v[40:43]
	v_mfma_f32_16x16x32_bf16 v[32:35], v[172:175], v[196:199], v[32:35]
	v_mfma_f32_16x16x32_bf16 v[24:27], v[180:183], v[196:199], v[24:27]
	v_mfma_f32_16x16x32_bf16 v[16:19], v[172:175], v[206:209], v[16:19]
	v_mfma_f32_16x16x32_bf16 v[8:11], v[180:183], v[206:209], v[8:11]
	v_mfma_f32_16x16x32_bf16 v[4:7], v[172:175], v[214:217], v[4:7]
	v_mfma_f32_16x16x32_bf16 v[0:3], v[180:183], v[214:217], v[0:3]
	v_mfma_f32_16x16x32_bf16 v[48:51], v[176:179], v[192:195], v[48:51]
	v_mfma_f32_16x16x32_bf16 v[40:43], v[184:187], v[192:195], v[40:43]
	v_mfma_f32_16x16x32_bf16 v[32:35], v[176:179], v[200:203], v[32:35]
	v_mfma_f32_16x16x32_bf16 v[24:27], v[184:187], v[200:203], v[24:27]
	v_mfma_f32_16x16x32_bf16 v[16:19], v[176:179], v[210:213], v[16:19]
	v_mfma_f32_16x16x32_bf16 v[8:11], v[184:187], v[210:213], v[8:11]
	v_mfma_f32_16x16x32_bf16 v[4:7], v[176:179], v[218:221], v[4:7]
	v_mfma_f32_16x16x32_bf16 v[0:3], v[184:187], v[218:221], v[0:3]
	s_barrier
	s_add_i32 s38, s38, 2
	s_add_u32 s21, s21, 0x100
	s_addc_u32 s23, s23, 0
	s_add_u32 s30, s30, 0x100
	s_addc_u32 s31, s31, 0
	s_cmp_gt_u32 s38, 29
	s_cbranch_scc0 .LBB0_82
	s_and_b64 vcc, exec, s[18:19]
	s_cbranch_vccz .LBB0_85
	s_barrier

; #define PG8_STAGE(bufoff, gbase, voff) do { _Pragma("unroll") for (int _i = 0; _i < 2; ++_i) \
;         __builtin_amdgcn_global_load_lds((const unsigned*)((const char*)(gbase) + (voff)[_i]), (PG8_LAS unsigned*)(lds + (bufoff) + ldsw + _i * 8192), 16, 0, 0); } while (0)
; #define PG8_LDA(dst, b, h) do { _Pragma("unroll") for (int m = 0; m < 4; ++m) _Pragma("unroll") for (int k = 0; k < 2; ++k) dst[m][k] = *(const PG8_LAS bf16x8*)(lds + PG8_SA(b, h) + aoff + m * 2048 + k * 1024); } while (0)
; #define PG8_LDB(dst, b, h) do { _Pragma("unroll") for (int n = 0; n < 2; ++n) _Pragma("unroll") for (int k = 0; k < 2; ++k) dst[n][k] = *(const PG8_LAS bf16x8*)(lds + PG8_SB(b, h) + boff + n * 2048 + k * 1024); } while (0)
; #define PG8_MMA(ai, bj, At, Bt) do { __builtin_amdgcn_s_setprio(1); _Pragma("unroll") for (int m = 0; m < 4; ++m) _Pragma("unroll") for (int n = 0; n < 2; ++n) _Pragma("unroll") for (int k = 0; k < 2; ++k) \
;         acc[ai][bj][m][n] = __builtin_amdgcn_mfma_f32_16x16x32_bf16(Bt[n][k], At[m][k], acc[ai][bj][m][n], 0, 0, 0); __builtin_amdgcn_s_setprio(0); } while (0)
; #define PG8_WAIT_V(n) asm volatile("s_waitcnt vmcnt(" #n ")" ::: "memory")
; #define PG8_WAIT_L(n) asm volatile("s_waitcnt lgkmcnt(" #n ")" ::: "memory")
; #define PG8_BAR __builtin_amdgcn_s_barrier()
; template <class Epi, class Sched, bool ALIGN_EPI = false, bool SP2 = false>
; __device__ __forceinline__ void gemm_phase(PG8_LAS unsigned char* lds, const Gemm g, const Sched& S, const Epi& E, const int wv0) {
;     ...
;             const bool last = (t == nt - 2);
;             const char* a1 = cA + (size_t)(t + 1) * kstep;
;             const char* a2 = last ? nA : cA + (size_t)(t + 2) * kstep; const char* b2 = last ? nB : cB + (size_t)(t + 2) * kstep;
;             const char* a3 = a2 + kstep; const char* b3 = b2 + kstep;
;             if constexpr (SP2) {
;             PG8_LDB(B0, 0, 0); PG8_LDB(B1, 0, 1); PG8_SCHED; PG8_LDA(At, 0, 0); PG8_STAGE(PG8_SA(1, 1), a1 + hstepA, voffA);
;             PG8_WAIT_V(8); PG8_WAIT_L(0); PG8_BAR; PG8_MMA(0, 0, At, B0); PG8_MMA(0, 1, At, B1); PG8_BAR; PG8_SCHED;
;             PG8_LDA(At, 0, 1); PG8_STAGE(PG8_SB(0, 0), b2, voffB); PG8_STAGE(PG8_SB(0, 1), b2 + hstepB, voffB); PG8_STAGE(PG8_SA(0, 0), a2, voffA);
;             PG8_WAIT_V(8); PG8_WAIT_L(0); PG8_BAR; PG8_MMA(1, 0, At, B0); PG8_MMA(1, 1, At, B1); PG8_BAR; PG8_SCHED;
.LBB0_494:
	v_add_u32_e32 v158, s61, v207
	v_add_u32_e32 v174, s62, v207
	ds_read_b128 v[146:149], v158
	ds_read_b128 v[150:153], v158 offset:1024
	ds_read_b128 v[154:157], v158 offset:2048
	ds_read_b128 v[158:161], v158 offset:3072
	ds_read_b128 v[162:165], v174
	ds_read_b128 v[166:169], v174 offset:1024
	ds_read_b128 v[170:173], v174 offset:2048
	ds_read_b128 v[174:177], v174 offset:3072
	s_add_u32 s41, s38, 0xfffc0080
	s_addc_u32 s44, s39, -1
	s_cmp_eq_u32 s29, 12
	s_cselect_b32 s47, s5, s44
	s_cselect_b32 s46, s4, s41
	s_cselect_b32 s45, s37, s27
	s_cselect_b32 s44, s36, s25
	v_lshl_add_u64 v[202:203], s[38:39], 0, v[140:141]
	s_add_i32 m0, s55, 0xc000
	ds_read_b128 v[178:181], v209
	ds_read_b128 v[182:185], v209 offset:1024
	ds_read_b128 v[186:189], v209 offset:2048
	ds_read_b128 v[190:193], v209 offset:3072
	ds_read_b128 v[194:197], v209 offset:4096
	ds_read_b128 v[198:201], v209 offset:5120
	ds_read_b128 v[210:213], v209 offset:6144
	ds_read_b128 v[214:217], v209 offset:7168
	global_load_lds_dwordx4 v[202:203], off
	v_lshl_add_u64 v[202:203], s[38:39], 0, v[138:139]
	s_add_i32 m0, s55, 0xe000
	s_nop 0
	global_load_lds_dwordx4 v[202:203], off
	s_waitcnt vmcnt(8)
	s_waitcnt lgkmcnt(0)
	s_barrier
	v_mfma_f32_16x16x32_bf16 v[124:127], v[146:149], v[178:181], v[124:127]
	v_mfma_f32_16x16x32_bf16 v[120:123], v[154:157], v[178:181], v[120:123]
	v_mfma_f32_16x16x32_bf16 v[108:111], v[146:149], v[186:189], v[108:111]
	v_mfma_f32_16x16x32_bf16 v[104:107], v[154:157], v[186:189], v[104:107]
	v_mfma_f32_16x16x32_bf16 v[92:95], v[146:149], v[194:197], v[92:95]
	v_mfma_f32_16x16x32_bf16 v[88:91], v[154:157], v[194:197], v[88:91]
	v_mfma_f32_16x16x32_bf16 v[76:79], v[146:149], v[210:213], v[76:79]
	v_mfma_f32_16x16x32_bf16 v[72:75], v[154:157], v[210:213], v[72:75]
	v_mfma_f32_16x16x32_bf16 v[124:127], v[150:153], v[182:185], v[124:127]
	v_mfma_f32_16x16x32_bf16 v[120:123], v[158:161], v[182:185], v[120:123]
	v_mfma_f32_16x16x32_bf16 v[108:111], v[150:153], v[190:193], v[108:111]
	v_mfma_f32_16x16x32_bf16 v[104:107], v[158:161], v[190:193], v[104:107]
	v_mfma_f32_16x16x32_bf16 v[92:95], v[150:153], v[198:201], v[92:95]
	v_mfma_f32_16x16x32_bf16 v[88:91], v[158:161], v[198:201], v[88:91]
	v_mfma_f32_16x16x32_bf16 v[76:79], v[150:153], v[214:217], v[76:79]
	v_mfma_f32_16x16x32_bf16 v[72:75], v[158:161], v[214:217], v[72:75]
	v_mfma_f32_16x16x32_bf16 v[116:119], v[162:165], v[178:181], v[116:119]
	v_mfma_f32_16x16x32_bf16 v[112:115], v[170:173], v[178:181], v[112:115]
	v_mfma_f32_16x16x32_bf16 v[100:103], v[162:165], v[186:189], v[100:103]
	v_mfma_f32_16x16x32_bf16 v[96:99], v[170:173], v[186:189], v[96:99]
	v_mfma_f32_16x16x32_bf16 v[84:87], v[162:165], v[194:197], v[84:87]
	v_mfma_f32_16x16x32_bf16 v[80:83], v[170:173], v[194:197], v[80:83]
	v_mfma_f32_16x16x32_bf16 v[68:71], v[162:165], v[210:213], v[68:71]
	v_mfma_f32_16x16x32_bf16 v[64:67], v[170:173], v[210:213], v[64:67]
	v_mfma_f32_16x16x32_bf16 v[116:119], v[166:169], v[182:185], v[116:119]
	v_mfma_f32_16x16x32_bf16 v[112:115], v[174:177], v[182:185], v[112:115]
	v_mfma_f32_16x16x32_bf16 v[100:103], v[166:169], v[190:193], v[100:103]
	v_mfma_f32_16x16x32_bf16 v[96:99], v[174:177], v[190:193], v[96:99]
	v_mfma_f32_16x16x32_bf16 v[84:87], v[166:169], v[198:201], v[84:87]
	v_mfma_f32_16x16x32_bf16 v[80:83], v[174:177], v[198:201], v[80:83]
	v_mfma_f32_16x16x32_bf16 v[68:71], v[166:169], v[214:217], v[68:71]
	v_mfma_f32_16x16x32_bf16 v[64:67], v[174:177], v[214:217], v[64:67]
	s_barrier
	ds_read_b128 v[178:181], v209 offset:16384
	ds_read_b128 v[182:185], v209 offset:17408
	ds_read_b128 v[186:189], v209 offset:18432
	ds_read_b128 v[190:193], v209 offset:19456
	ds_read_b128 v[194:197], v209 offset:20480
	ds_read_b128 v[198:201], v209 offset:21504
	ds_read_b128 v[210:213], v209 offset:22528
	ds_read_b128 v[214:217], v209 offset:23552
	s_add_i32 s41, s61, s54
	s_mov_b32 m0, s41
	v_lshl_add_u64 v[202:203], s[44:45], 0, v[130:131]
	global_load_lds_dwordx4 v[202:203], off
	s_add_i32 m0, s41, 0x2000
	s_add_u32 s64, s44, 0x40000
	v_lshl_add_u64 v[218:219], s[44:45], 0, v[134:135]
	s_addc_u32 s65, s45, 0
	s_add_i32 s41, s62, s54
	global_load_lds_dwordx4 v[218:219], off
	v_lshl_add_u64 v[220:221], s[64:65], 0, v[130:131]
	s_mov_b32 m0, s41
	v_lshl_add_u64 v[222:223], s[46:47], 0, v[132:133]
	global_load_lds_dwordx4 v[220:221], off
	v_lshl_add_u64 v[220:221], s[64:65], 0, v[134:135]
	s_add_i32 m0, s41, 0x2000
	s_nop 0
	global_load_lds_dwordx4 v[220:221], off
	v_lshl_add_u64 v[220:221], s[46:47], 0, v[128:129]
	s_mov_b32 m0, s55
	s_nop 0
	global_load_lds_dwordx4 v[220:221], off
	s_mov_b32 m0, s56
	s_nop 0
	global_load_lds_dwordx4 v[222:223], off
	s_waitcnt vmcnt(8)
	s_waitcnt lgkmcnt(0)
	s_barrier
; #define PG8_STAGE(bufoff, gbase, voff) do { _Pragma("unroll") for (int _i = 0; _i < 2; ++_i) \
;         __builtin_amdgcn_global_load_lds((const unsigned*)((const char*)(gbase) + (voff)[_i]), (PG8_LAS unsigned*)(lds + (bufoff) + ldsw + _i * 8192), 16, 0, 0); } while (0)
; #define PG8_LDA(dst, b, h) do { _Pragma("unroll") for (int m = 0; m < 4; ++m) _Pragma("unroll") for (int k = 0; k < 2; ++k) dst[m][k] = *(const PG8_LAS bf16x8*)(lds + PG8_SA(b, h) + aoff + m * 2048 + k * 1024); } while (0)
; #define PG8_LDB(dst, b, h) do { _Pragma("unroll") for (int n = 0; n < 2; ++n) _Pragma("unroll") for (int k = 0; k < 2; ++k) dst[n][k] = *(const PG8_LAS bf16x8*)(lds + PG8_SB(b, h) + boff + n * 2048 + k * 1024); } while (0)
; #define PG8_MMA(ai, bj, At, Bt) do { __builtin_amdgcn_s_setprio(1); _Pragma("unroll") for (int m = 0; m < 4; ++m) _Pragma("unroll") for (int n = 0; n < 2; ++n) _Pragma("unroll") for (int k = 0; k < 2; ++k) \
;         acc[ai][bj][m][n] = __builtin_amdgcn_mfma_f32_16x16x32_bf16(Bt[n][k], At[m][k], acc[ai][bj][m][n], 0, 0, 0); __builtin_amdgcn_s_setprio(0); } while (0)
; #define PG8_WAIT_V(n) asm volatile("s_waitcnt vmcnt(" #n ")" ::: "memory")
; #define PG8_WAIT_L(n) asm volatile("s_waitcnt lgkmcnt(" #n ")" ::: "memory")
; #define PG8_BAR __builtin_amdgcn_s_barrier()
; #define PG8_SCHED __builtin_amdgcn_sched_barrier(0)
; template <class Epi, class Sched, bool ALIGN_EPI = false, bool SP2 = false>
; __device__ __forceinline__ void gemm_phase(PG8_LAS unsigned char* lds, const Gemm g, const Sched& S, const Epi& E, const int wv0) {
;     ...
;             PG8_WAIT_V(8); PG8_WAIT_L(0); PG8_BAR; PG8_MMA(1, 0, At, B0); PG8_MMA(1, 1, At, B1); PG8_BAR; PG8_SCHED;
;             PG8_LDB(B0, 1, 0); PG8_LDB(B1, 1, 1); PG8_SCHED; PG8_LDA(At, 1, 0); PG8_STAGE(PG8_SA(0, 1), a2 + hstepA, voffA);
;             PG8_WAIT_V(8); PG8_WAIT_L(0); PG8_BAR; PG8_MMA(0, 0, At, B0); PG8_MMA(0, 1, At, B1); PG8_BAR; PG8_SCHED;
	v_mfma_f32_16x16x32_bf16 v[60:63], v[146:149], v[178:181], v[60:63]
	v_mfma_f32_16x16x32_bf16 v[56:59], v[154:157], v[178:181], v[56:59]
	v_mfma_f32_16x16x32_bf16 v[44:47], v[146:149], v[186:189], v[44:47]
	v_mfma_f32_16x16x32_bf16 v[40:43], v[154:157], v[186:189], v[40:43]
	v_mfma_f32_16x16x32_bf16 v[28:31], v[146:149], v[194:197], v[28:31]
	v_mfma_f32_16x16x32_bf16 v[24:27], v[154:157], v[194:197], v[24:27]
	v_mfma_f32_16x16x32_bf16 v[12:15], v[146:149], v[210:213], v[12:15]
	v_mfma_f32_16x16x32_bf16 v[8:11], v[154:157], v[210:213], v[8:11]
	v_mfma_f32_16x16x32_bf16 v[60:63], v[150:153], v[182:185], v[60:63]
	v_mfma_f32_16x16x32_bf16 v[56:59], v[158:161], v[182:185], v[56:59]
	v_mfma_f32_16x16x32_bf16 v[44:47], v[150:153], v[190:193], v[44:47]
	v_mfma_f32_16x16x32_bf16 v[40:43], v[158:161], v[190:193], v[40:43]
	v_mfma_f32_16x16x32_bf16 v[28:31], v[150:153], v[198:201], v[28:31]
	v_mfma_f32_16x16x32_bf16 v[24:27], v[158:161], v[198:201], v[24:27]
	v_mfma_f32_16x16x32_bf16 v[12:15], v[150:153], v[214:217], v[12:15]
	v_mfma_f32_16x16x32_bf16 v[8:11], v[158:161], v[214:217], v[8:11]
	v_mfma_f32_16x16x32_bf16 v[52:55], v[162:165], v[178:181], v[52:55]
	v_mfma_f32_16x16x32_bf16 v[48:51], v[170:173], v[178:181], v[48:51]
	v_mfma_f32_16x16x32_bf16 v[36:39], v[162:165], v[186:189], v[36:39]
	v_mfma_f32_16x16x32_bf16 v[32:35], v[170:173], v[186:189], v[32:35]
	v_mfma_f32_16x16x32_bf16 v[20:23], v[162:165], v[194:197], v[20:23]
	v_mfma_f32_16x16x32_bf16 v[16:19], v[170:173], v[194:197], v[16:19]
	v_mfma_f32_16x16x32_bf16 v[4:7], v[162:165], v[210:213], v[4:7]
	v_mfma_f32_16x16x32_bf16 v[0:3], v[170:173], v[210:213], v[0:3]
	v_mfma_f32_16x16x32_bf16 v[52:55], v[166:169], v[182:185], v[52:55]
	v_mfma_f32_16x16x32_bf16 v[48:51], v[174:177], v[182:185], v[48:51]
	v_mfma_f32_16x16x32_bf16 v[36:39], v[166:169], v[190:193], v[36:39]
	v_mfma_f32_16x16x32_bf16 v[32:35], v[174:177], v[190:193], v[32:35]
	v_mfma_f32_16x16x32_bf16 v[20:23], v[166:169], v[198:201], v[20:23]
	v_mfma_f32_16x16x32_bf16 v[16:19], v[174:177], v[198:201], v[16:19]
	v_mfma_f32_16x16x32_bf16 v[4:7], v[166:169], v[214:217], v[4:7]
	v_mfma_f32_16x16x32_bf16 v[0:3], v[174:177], v[214:217], v[0:3]
	s_barrier
	s_add_i32 s41, 0, 0x18000
	s_add_i32 s64, 0, 0x1c000
	v_add_u32_e32 v158, s41, v207
	v_add_u32_e32 v174, s64, v207
	ds_read_b128 v[146:149], v158
	ds_read_b128 v[150:153], v158 offset:1024
	ds_read_b128 v[154:157], v158 offset:2048
	ds_read_b128 v[158:161], v158 offset:3072
	ds_read_b128 v[162:165], v174
	ds_read_b128 v[166:169], v174 offset:1024
	ds_read_b128 v[170:173], v174 offset:2048
	ds_read_b128 v[174:177], v174 offset:3072
	s_add_u32 s46, s46, 0x40000
	s_addc_u32 s47, s47, 0
	s_mov_b32 m0, s57
	v_lshl_add_u64 v[224:225], s[46:47], 0, v[128:129]
	ds_read_b128 v[178:181], v209 offset:32768
	ds_read_b128 v[182:185], v209 offset:33792
	ds_read_b128 v[186:189], v209 offset:34816
	ds_read_b128 v[190:193], v209 offset:35840
	ds_read_b128 v[194:197], v209 offset:36864
	ds_read_b128 v[198:201], v209 offset:37888
	ds_read_b128 v[210:213], v209 offset:38912
	ds_read_b128 v[214:217], v209 offset:39936
	global_load_lds_dwordx4 v[224:225], off
	v_lshl_add_u64 v[224:225], s[46:47], 0, v[132:133]
	s_mov_b32 m0, s58
	s_nop 0
	global_load_lds_dwordx4 v[224:225], off
	s_waitcnt vmcnt(8)
	s_waitcnt lgkmcnt(0)
	s_barrier
	v_mfma_f32_16x16x32_bf16 v[124:127], v[146:149], v[178:181], v[124:127]
	v_mfma_f32_16x16x32_bf16 v[120:123], v[154:157], v[178:181], v[120:123]
	v_mfma_f32_16x16x32_bf16 v[108:111], v[146:149], v[186:189], v[108:111]
	v_mfma_f32_16x16x32_bf16 v[104:107], v[154:157], v[186:189], v[104:107]
	v_mfma_f32_16x16x32_bf16 v[92:95], v[146:149], v[194:197], v[92:95]
	v_mfma_f32_16x16x32_bf16 v[88:91], v[154:157], v[194:197], v[88:91]
	v_mfma_f32_16x16x32_bf16 v[76:79], v[146:149], v[210:213], v[76:79]
	v_mfma_f32_16x16x32_bf16 v[72:75], v[154:157], v[210:213], v[72:75]
	v_mfma_f32_16x16x32_bf16 v[124:127], v[150:153], v[182:185], v[124:127]
	v_mfma_f32_16x16x32_bf16 v[120:123], v[158:161], v[182:185], v[120:123]
	v_mfma_f32_16x16x32_bf16 v[108:111], v[150:153], v[190:193], v[108:111]
	v_mfma_f32_16x16x32_bf16 v[104:107], v[158:161], v[190:193], v[104:107]
	v_mfma_f32_16x16x32_bf16 v[92:95], v[150:153], v[198:201], v[92:95]
	v_mfma_f32_16x16x32_bf16 v[88:91], v[158:161], v[198:201], v[88:91]
	v_mfma_f32_16x16x32_bf16 v[76:79], v[150:153], v[214:217], v[76:79]
	v_mfma_f32_16x16x32_bf16 v[72:75], v[158:161], v[214:217], v[72:75]
	v_mfma_f32_16x16x32_bf16 v[116:119], v[162:165], v[178:181], v[116:119]
	v_mfma_f32_16x16x32_bf16 v[112:115], v[170:173], v[178:181], v[112:115]
	v_mfma_f32_16x16x32_bf16 v[100:103], v[162:165], v[186:189], v[100:103]
	v_mfma_f32_16x16x32_bf16 v[96:99], v[170:173], v[186:189], v[96:99]
	v_mfma_f32_16x16x32_bf16 v[84:87], v[162:165], v[194:197], v[84:87]
	v_mfma_f32_16x16x32_bf16 v[80:83], v[170:173], v[194:197], v[80:83]
	v_mfma_f32_16x16x32_bf16 v[68:71], v[162:165], v[210:213], v[68:71]
	v_mfma_f32_16x16x32_bf16 v[64:67], v[170:173], v[210:213], v[64:67]
	v_mfma_f32_16x16x32_bf16 v[116:119], v[166:169], v[182:185], v[116:119]
	v_mfma_f32_16x16x32_bf16 v[112:115], v[174:177], v[182:185], v[112:115]
	v_mfma_f32_16x16x32_bf16 v[100:103], v[166:169], v[190:193], v[100:103]
	v_mfma_f32_16x16x32_bf16 v[96:99], v[174:177], v[190:193], v[96:99]
	v_mfma_f32_16x16x32_bf16 v[84:87], v[166:169], v[198:201], v[84:87]
	v_mfma_f32_16x16x32_bf16 v[80:83], v[174:177], v[198:201], v[80:83]
	v_mfma_f32_16x16x32_bf16 v[68:71], v[166:169], v[214:217], v[68:71]
	v_mfma_f32_16x16x32_bf16 v[64:67], v[174:177], v[214:217], v[64:67]
	s_barrier
; #define PG8_STAGE(bufoff, gbase, voff) do { _Pragma("unroll") for (int _i = 0; _i < 2; ++_i) \
;         __builtin_amdgcn_global_load_lds((const unsigned*)((const char*)(gbase) + (voff)[_i]), (PG8_LAS unsigned*)(lds + (bufoff) + ldsw + _i * 8192), 16, 0, 0); } while (0)
; #define PG8_LDA(dst, b, h) do { _Pragma("unroll") for (int m = 0; m < 4; ++m) _Pragma("unroll") for (int k = 0; k < 2; ++k) dst[m][k] = *(const PG8_LAS bf16x8*)(lds + PG8_SA(b, h) + aoff + m * 2048 + k * 1024); } while (0)
; #define PG8_MMA(ai, bj, At, Bt) do { __builtin_amdgcn_s_setprio(1); _Pragma("unroll") for (int m = 0; m < 4; ++m) _Pragma("unroll") for (int n = 0; n < 2; ++n) _Pragma("unroll") for (int k = 0; k < 2; ++k) \
;         acc[ai][bj][m][n] = __builtin_amdgcn_mfma_f32_16x16x32_bf16(Bt[n][k], At[m][k], acc[ai][bj][m][n], 0, 0, 0); __builtin_amdgcn_s_setprio(0); } while (0)
; #define PG8_WAIT_V(n) asm volatile("s_waitcnt vmcnt(" #n ")" ::: "memory")
; #define PG8_WAIT_L(n) asm volatile("s_waitcnt lgkmcnt(" #n ")" ::: "memory")
; #define PG8_BAR __builtin_amdgcn_s_barrier()
; #define PG8_SCHED __builtin_amdgcn_sched_barrier(0)
; template <class Epi, class Sched, bool ALIGN_EPI = false, bool SP2 = false>
; __device__ __forceinline__ void gemm_phase(PG8_LAS unsigned char* lds, const Gemm g, const Sched& S, const Epi& E, const int wv0) {
;     ...
;             PG8_LDA(At, 1, 1); PG8_STAGE(PG8_SB(1, 0), b3, voffB); PG8_STAGE(PG8_SB(1, 1), b3 + hstepB, voffB); PG8_STAGE(PG8_SA(1, 0), a3, voffA);
;             PG8_WAIT_V(8); PG8_WAIT_L(0); PG8_BAR; PG8_MMA(1, 0, At, B0); PG8_MMA(1, 1, At, B1); PG8_BAR; PG8_SCHED;
;     ...
;         if constexpr (ALIGN_EPI) { if (wr == 0) PG8_BAR; }
	s_add_i32 s41, s41, s54
	v_lshl_add_u64 v[202:203], v[202:203], 0, s[10:11]
	s_mov_b32 m0, s41
	ds_read_b128 v[178:181], v209 offset:49152
	ds_read_b128 v[182:185], v209 offset:50176
	ds_read_b128 v[186:189], v209 offset:51200
	ds_read_b128 v[190:193], v209 offset:52224
	ds_read_b128 v[194:197], v209 offset:53248
	ds_read_b128 v[198:201], v209 offset:54272
	ds_read_b128 v[210:213], v209 offset:55296
	ds_read_b128 v[214:217], v209 offset:56320
	global_load_lds_dwordx4 v[202:203], off
	s_add_i32 m0, s41, 0x2000
	s_add_u32 s44, s44, 0x40080
	v_lshl_add_u64 v[202:203], v[218:219], 0, s[10:11]
	s_addc_u32 s45, s45, 0
	s_add_i32 s41, s64, s54
	global_load_lds_dwordx4 v[202:203], off
	v_lshl_add_u64 v[202:203], s[44:45], 0, v[130:131]
	s_mov_b32 m0, s41
	s_nop 0
	global_load_lds_dwordx4 v[202:203], off
	v_lshl_add_u64 v[202:203], s[44:45], 0, v[134:135]
	s_add_i32 m0, s41, 0x2000
	s_nop 0
	global_load_lds_dwordx4 v[202:203], off
	v_lshl_add_u64 v[202:203], v[220:221], 0, s[10:11]
	s_mov_b32 m0, s59
	s_nop 0
	global_load_lds_dwordx4 v[202:203], off
	v_lshl_add_u64 v[202:203], v[222:223], 0, s[10:11]
	s_mov_b32 m0, s60
	s_nop 0
	global_load_lds_dwordx4 v[202:203], off
	s_waitcnt vmcnt(8)
	s_waitcnt lgkmcnt(0)
	s_barrier
	v_mfma_f32_16x16x32_bf16 v[60:63], v[146:149], v[178:181], v[60:63]
	v_mfma_f32_16x16x32_bf16 v[56:59], v[154:157], v[178:181], v[56:59]
	v_mfma_f32_16x16x32_bf16 v[44:47], v[146:149], v[186:189], v[44:47]
	v_mfma_f32_16x16x32_bf16 v[40:43], v[154:157], v[186:189], v[40:43]
	v_mfma_f32_16x16x32_bf16 v[28:31], v[146:149], v[194:197], v[28:31]
	v_mfma_f32_16x16x32_bf16 v[24:27], v[154:157], v[194:197], v[24:27]
	v_mfma_f32_16x16x32_bf16 v[12:15], v[146:149], v[210:213], v[12:15]
	v_mfma_f32_16x16x32_bf16 v[8:11], v[154:157], v[210:213], v[8:11]
	v_mfma_f32_16x16x32_bf16 v[60:63], v[150:153], v[182:185], v[60:63]
	v_mfma_f32_16x16x32_bf16 v[56:59], v[158:161], v[182:185], v[56:59]
	v_mfma_f32_16x16x32_bf16 v[44:47], v[150:153], v[190:193], v[44:47]
	v_mfma_f32_16x16x32_bf16 v[40:43], v[158:161], v[190:193], v[40:43]
	v_mfma_f32_16x16x32_bf16 v[28:31], v[150:153], v[198:201], v[28:31]
	v_mfma_f32_16x16x32_bf16 v[24:27], v[158:161], v[198:201], v[24:27]
	v_mfma_f32_16x16x32_bf16 v[12:15], v[150:153], v[214:217], v[12:15]
	v_mfma_f32_16x16x32_bf16 v[8:11], v[158:161], v[214:217], v[8:11]
	v_mfma_f32_16x16x32_bf16 v[52:55], v[162:165], v[178:181], v[52:55]
	v_mfma_f32_16x16x32_bf16 v[48:51], v[170:173], v[178:181], v[48:51]
	v_mfma_f32_16x16x32_bf16 v[36:39], v[162:165], v[186:189], v[36:39]
	v_mfma_f32_16x16x32_bf16 v[32:35], v[170:173], v[186:189], v[32:35]
	v_mfma_f32_16x16x32_bf16 v[20:23], v[162:165], v[194:197], v[20:23]
	v_mfma_f32_16x16x32_bf16 v[16:19], v[170:173], v[194:197], v[16:19]
	v_mfma_f32_16x16x32_bf16 v[4:7], v[162:165], v[210:213], v[4:7]
	v_mfma_f32_16x16x32_bf16 v[0:3], v[170:173], v[210:213], v[0:3]
	v_mfma_f32_16x16x32_bf16 v[52:55], v[166:169], v[182:185], v[52:55]
	v_mfma_f32_16x16x32_bf16 v[48:51], v[174:177], v[182:185], v[48:51]
	v_mfma_f32_16x16x32_bf16 v[36:39], v[166:169], v[190:193], v[36:39]
	v_mfma_f32_16x16x32_bf16 v[32:35], v[174:177], v[190:193], v[32:35]
	v_mfma_f32_16x16x32_bf16 v[20:23], v[166:169], v[198:201], v[20:23]
	v_mfma_f32_16x16x32_bf16 v[16:19], v[174:177], v[198:201], v[16:19]
	v_mfma_f32_16x16x32_bf16 v[4:7], v[166:169], v[214:217], v[4:7]
	v_mfma_f32_16x16x32_bf16 v[0:3], v[174:177], v[214:217], v[0:3]
	s_barrier
	s_add_i32 s29, s29, 2
	s_add_u32 s25, s25, 0x100
	s_addc_u32 s27, s27, 0
	s_add_u32 s38, s38, 0x100
	s_addc_u32 s39, s39, 0
	s_cmp_gt_u32 s29, 13
	s_cbranch_scc0 .LBB0_494
	s_and_b64 vcc, exec, s[12:13]
	s_cbranch_vccz .LBB0_497
	s_barrier

; #define PG8_STAGE(bufoff, gbase, voff) do { _Pragma("unroll") for (int _i = 0; _i < 2; ++_i) \
;         __builtin_amdgcn_global_load_lds((const unsigned*)((const char*)(gbase) + (voff)[_i]), (PG8_LAS unsigned*)(lds + (bufoff) + ldsw + _i * 8192), 16, 0, 0); } while (0)
; #define PG8_LDA(dst, b, h) do { _Pragma("unroll") for (int m = 0; m < 4; ++m) _Pragma("unroll") for (int k = 0; k < 2; ++k) dst[m][k] = *(const PG8_LAS bf16x8*)(lds + PG8_SA(b, h) + aoff + m * 2048 + k * 1024); } while (0)
; #define PG8_LDB(dst, b, h) do { _Pragma("unroll") for (int n = 0; n < 2; ++n) _Pragma("unroll") for (int k = 0; k < 2; ++k) dst[n][k] = *(const PG8_LAS bf16x8*)(lds + PG8_SB(b, h) + boff + n * 2048 + k * 1024); } while (0)
; #define PG8_MMA(ai, bj, At, Bt) do { __builtin_amdgcn_s_setprio(1); _Pragma("unroll") for (int m = 0; m < 4; ++m) _Pragma("unroll") for (int n = 0; n < 2; ++n) _Pragma("unroll") for (int k = 0; k < 2; ++k) \
;         acc[ai][bj][m][n] = __builtin_amdgcn_mfma_f32_16x16x32_bf16(Bt[n][k], At[m][k], acc[ai][bj][m][n], 0, 0, 0); __builtin_amdgcn_s_setprio(0); } while (0)
; #define PG8_WAIT_V(n) asm volatile("s_waitcnt vmcnt(" #n ")" ::: "memory")
; #define PG8_WAIT_L(n) asm volatile("s_waitcnt lgkmcnt(" #n ")" ::: "memory")
; #define PG8_BAR __builtin_amdgcn_s_barrier()
; template <class Epi, class Sched, bool ALIGN_EPI = false, bool SP2 = false>
; __device__ __forceinline__ void gemm_phase(PG8_LAS unsigned char* lds, const Gemm g, const Sched& S, const Epi& E, const int wv0) {
;     ...
;             const bool last = (t == nt - 2);
;             const char* a1 = cA + (size_t)(t + 1) * kstep;
;             const char* a2 = last ? nA : cA + (size_t)(t + 2) * kstep; const char* b2 = last ? nB : cB + (size_t)(t + 2) * kstep;
;             const char* a3 = a2 + kstep; const char* b3 = b2 + kstep;
;             if constexpr (SP2) {
;             PG8_LDB(B0, 0, 0); PG8_LDB(B1, 0, 1); PG8_SCHED; PG8_LDA(At, 0, 0); PG8_STAGE(PG8_SA(1, 1), a1 + hstepA, voffA);
;             PG8_WAIT_V(8); PG8_WAIT_L(0); PG8_BAR; PG8_MMA(0, 0, At, B0); PG8_MMA(0, 1, At, B1); PG8_BAR; PG8_SCHED;
;             PG8_LDA(At, 0, 1); PG8_STAGE(PG8_SB(0, 0), b2, voffB); PG8_STAGE(PG8_SB(0, 1), b2 + hstepB, voffB); PG8_STAGE(PG8_SA(0, 0), a2, voffA);
;             PG8_WAIT_V(8); PG8_WAIT_L(0); PG8_BAR; PG8_MMA(1, 0, At, B0); PG8_MMA(1, 1, At, B1); PG8_BAR; PG8_SCHED;
.LBB0_667:
	ds_read_b128 v[144:147], v153
	ds_read_b128 v[156:159], v153 offset:1024
	ds_read_b128 v[160:163], v153 offset:2048
	ds_read_b128 v[164:167], v153 offset:3072
	ds_read_b128 v[168:171], v154
	ds_read_b128 v[172:175], v154 offset:1024
	ds_read_b128 v[176:179], v154 offset:2048
	ds_read_b128 v[180:183], v154 offset:3072
	s_add_u32 s24, s22, 0xfff80080
	s_addc_u32 s25, s23, -1
	s_cmp_eq_u32 s50, 28
	s_cselect_b32 s27, s17, s25
	s_cselect_b32 s26, s16, s24
	s_cselect_b32 s25, s19, s15
	s_cselect_b32 s24, s18, s13
	v_lshl_add_u64 v[148:149], s[22:23], 0, v[138:139]
	s_add_i32 m0, s21, 0xc000
	ds_read_b128 v[184:187], v155
	ds_read_b128 v[188:191], v155 offset:1024
	ds_read_b128 v[192:195], v155 offset:2048
	ds_read_b128 v[196:199], v155 offset:3072
	ds_read_b128 v[200:203], v155 offset:4096
	ds_read_b128 v[206:209], v155 offset:5120
	ds_read_b128 v[210:213], v155 offset:6144
	ds_read_b128 v[214:217], v155 offset:7168
	global_load_lds_dwordx4 v[148:149], off
	v_lshl_add_u64 v[148:149], s[22:23], 0, v[136:137]
	s_add_i32 m0, s21, 0xe000
	s_nop 0
	global_load_lds_dwordx4 v[148:149], off
	s_waitcnt vmcnt(8)
	s_waitcnt lgkmcnt(0)
	s_barrier
	v_mfma_f32_16x16x32_bf16 v[124:127], v[144:147], v[184:187], v[124:127]
	v_mfma_f32_16x16x32_bf16 v[120:123], v[160:163], v[184:187], v[120:123]
	v_mfma_f32_16x16x32_bf16 v[116:119], v[144:147], v[192:195], v[116:119]
	v_mfma_f32_16x16x32_bf16 v[112:115], v[160:163], v[192:195], v[112:115]
	v_mfma_f32_16x16x32_bf16 v[92:95], v[144:147], v[200:203], v[92:95]
	v_mfma_f32_16x16x32_bf16 v[88:91], v[160:163], v[200:203], v[88:91]
	v_mfma_f32_16x16x32_bf16 v[84:87], v[144:147], v[210:213], v[84:87]
	v_mfma_f32_16x16x32_bf16 v[80:83], v[160:163], v[210:213], v[80:83]
	v_mfma_f32_16x16x32_bf16 v[124:127], v[156:159], v[188:191], v[124:127]
	v_mfma_f32_16x16x32_bf16 v[120:123], v[164:167], v[188:191], v[120:123]
	v_mfma_f32_16x16x32_bf16 v[116:119], v[156:159], v[196:199], v[116:119]
	v_mfma_f32_16x16x32_bf16 v[112:115], v[164:167], v[196:199], v[112:115]
	v_mfma_f32_16x16x32_bf16 v[92:95], v[156:159], v[206:209], v[92:95]
	v_mfma_f32_16x16x32_bf16 v[88:91], v[164:167], v[206:209], v[88:91]
	v_mfma_f32_16x16x32_bf16 v[84:87], v[156:159], v[214:217], v[84:87]
	v_mfma_f32_16x16x32_bf16 v[80:83], v[164:167], v[214:217], v[80:83]
	v_mfma_f32_16x16x32_bf16 v[108:111], v[168:171], v[184:187], v[108:111]
	v_mfma_f32_16x16x32_bf16 v[104:107], v[176:179], v[184:187], v[104:107]
	v_mfma_f32_16x16x32_bf16 v[100:103], v[168:171], v[192:195], v[100:103]
	v_mfma_f32_16x16x32_bf16 v[96:99], v[176:179], v[192:195], v[96:99]
	v_mfma_f32_16x16x32_bf16 v[76:79], v[168:171], v[200:203], v[76:79]
	v_mfma_f32_16x16x32_bf16 v[72:75], v[176:179], v[200:203], v[72:75]
	v_mfma_f32_16x16x32_bf16 v[68:71], v[168:171], v[210:213], v[68:71]
	v_mfma_f32_16x16x32_bf16 v[64:67], v[176:179], v[210:213], v[64:67]
	v_mfma_f32_16x16x32_bf16 v[108:111], v[172:175], v[188:191], v[108:111]
	v_mfma_f32_16x16x32_bf16 v[104:107], v[180:183], v[188:191], v[104:107]
	v_mfma_f32_16x16x32_bf16 v[100:103], v[172:175], v[196:199], v[100:103]
	v_mfma_f32_16x16x32_bf16 v[96:99], v[180:183], v[196:199], v[96:99]
	v_mfma_f32_16x16x32_bf16 v[76:79], v[172:175], v[206:209], v[76:79]
	v_mfma_f32_16x16x32_bf16 v[72:75], v[180:183], v[206:209], v[72:75]
	v_mfma_f32_16x16x32_bf16 v[68:71], v[172:175], v[214:217], v[68:71]
	v_mfma_f32_16x16x32_bf16 v[64:67], v[180:183], v[214:217], v[64:67]
	s_barrier
	ds_read_b128 v[184:187], v155 offset:16384
	ds_read_b128 v[188:191], v155 offset:17408
	ds_read_b128 v[192:195], v155 offset:18432
	ds_read_b128 v[196:199], v155 offset:19456
	ds_read_b128 v[200:203], v155 offset:20480
	ds_read_b128 v[206:209], v155 offset:21504
	ds_read_b128 v[210:213], v155 offset:22528
	ds_read_b128 v[214:217], v155 offset:23552
	s_add_i32 s51, s47, s37
	s_mov_b32 m0, s51
	v_lshl_add_u64 v[148:149], s[24:25], 0, v[130:131]
	global_load_lds_dwordx4 v[148:149], off
	s_add_i32 m0, s51, 0x2000
	s_add_u32 s52, s24, 0x80000
	v_lshl_add_u64 v[218:219], s[24:25], 0, v[134:135]
	s_addc_u32 s53, s25, 0
	s_add_i32 s51, s48, s37
	global_load_lds_dwordx4 v[218:219], off
	v_lshl_add_u64 v[220:221], s[52:53], 0, v[130:131]
	s_mov_b32 m0, s51
	v_lshl_add_u64 v[222:223], s[26:27], 0, v[132:133]
	global_load_lds_dwordx4 v[220:221], off
	v_lshl_add_u64 v[220:221], s[52:53], 0, v[134:135]
	s_add_i32 m0, s51, 0x2000
	s_nop 0
	global_load_lds_dwordx4 v[220:221], off
	v_lshl_add_u64 v[220:221], s[26:27], 0, v[128:129]
	s_mov_b32 m0, s21
	s_nop 0
	global_load_lds_dwordx4 v[220:221], off
	s_mov_b32 m0, s38
	s_nop 0
	global_load_lds_dwordx4 v[222:223], off
	s_waitcnt vmcnt(8)
	s_waitcnt lgkmcnt(0)
	s_barrier
; #define PG8_STAGE(bufoff, gbase, voff) do { _Pragma("unroll") for (int _i = 0; _i < 2; ++_i) \
;         __builtin_amdgcn_global_load_lds((const unsigned*)((const char*)(gbase) + (voff)[_i]), (PG8_LAS unsigned*)(lds + (bufoff) + ldsw + _i * 8192), 16, 0, 0); } while (0)
; #define PG8_LDA(dst, b, h) do { _Pragma("unroll") for (int m = 0; m < 4; ++m) _Pragma("unroll") for (int k = 0; k < 2; ++k) dst[m][k] = *(const PG8_LAS bf16x8*)(lds + PG8_SA(b, h) + aoff + m * 2048 + k * 1024); } while (0)
; #define PG8_LDB(dst, b, h) do { _Pragma("unroll") for (int n = 0; n < 2; ++n) _Pragma("unroll") for (int k = 0; k < 2; ++k) dst[n][k] = *(const PG8_LAS bf16x8*)(lds + PG8_SB(b, h) + boff + n * 2048 + k * 1024); } while (0)
; #define PG8_MMA(ai, bj, At, Bt) do { __builtin_amdgcn_s_setprio(1); _Pragma("unroll") for (int m = 0; m < 4; ++m) _Pragma("unroll") for (int n = 0; n < 2; ++n) _Pragma("unroll") for (int k = 0; k < 2; ++k) \
;         acc[ai][bj][m][n] = __builtin_amdgcn_mfma_f32_16x16x32_bf16(Bt[n][k], At[m][k], acc[ai][bj][m][n], 0, 0, 0); __builtin_amdgcn_s_setprio(0); } while (0)
; #define PG8_WAIT_V(n) asm volatile("s_waitcnt vmcnt(" #n ")" ::: "memory")
; #define PG8_WAIT_L(n) asm volatile("s_waitcnt lgkmcnt(" #n ")" ::: "memory")
; #define PG8_BAR __builtin_amdgcn_s_barrier()
; #define PG8_SCHED __builtin_amdgcn_sched_barrier(0)
; template <class Epi, class Sched, bool ALIGN_EPI = false, bool SP2 = false>
; __device__ __forceinline__ void gemm_phase(PG8_LAS unsigned char* lds, const Gemm g, const Sched& S, const Epi& E, const int wv0) {
;     ...
;             PG8_WAIT_V(8); PG8_WAIT_L(0); PG8_BAR; PG8_MMA(1, 0, At, B0); PG8_MMA(1, 1, At, B1); PG8_BAR; PG8_SCHED;
;             PG8_LDB(B0, 1, 0); PG8_LDB(B1, 1, 1); PG8_SCHED; PG8_LDA(At, 1, 0); PG8_STAGE(PG8_SA(0, 1), a2 + hstepA, voffA);
;             PG8_WAIT_V(8); PG8_WAIT_L(0); PG8_BAR; PG8_MMA(0, 0, At, B0); PG8_MMA(0, 1, At, B1); PG8_BAR; PG8_SCHED;
	v_mfma_f32_16x16x32_bf16 v[60:63], v[144:147], v[184:187], v[60:63]
	v_mfma_f32_16x16x32_bf16 v[56:59], v[160:163], v[184:187], v[56:59]
	v_mfma_f32_16x16x32_bf16 v[52:55], v[144:147], v[192:195], v[52:55]
	v_mfma_f32_16x16x32_bf16 v[48:51], v[160:163], v[192:195], v[48:51]
	v_mfma_f32_16x16x32_bf16 v[28:31], v[144:147], v[200:203], v[28:31]
	v_mfma_f32_16x16x32_bf16 v[24:27], v[160:163], v[200:203], v[24:27]
	v_mfma_f32_16x16x32_bf16 v[20:23], v[144:147], v[210:213], v[20:23]
	v_mfma_f32_16x16x32_bf16 v[16:19], v[160:163], v[210:213], v[16:19]
	v_mfma_f32_16x16x32_bf16 v[60:63], v[156:159], v[188:191], v[60:63]
	v_mfma_f32_16x16x32_bf16 v[56:59], v[164:167], v[188:191], v[56:59]
	v_mfma_f32_16x16x32_bf16 v[52:55], v[156:159], v[196:199], v[52:55]
	v_mfma_f32_16x16x32_bf16 v[48:51], v[164:167], v[196:199], v[48:51]
	v_mfma_f32_16x16x32_bf16 v[28:31], v[156:159], v[206:209], v[28:31]
	v_mfma_f32_16x16x32_bf16 v[24:27], v[164:167], v[206:209], v[24:27]
	v_mfma_f32_16x16x32_bf16 v[20:23], v[156:159], v[214:217], v[20:23]
	v_mfma_f32_16x16x32_bf16 v[16:19], v[164:167], v[214:217], v[16:19]
	v_mfma_f32_16x16x32_bf16 v[44:47], v[168:171], v[184:187], v[44:47]
	v_mfma_f32_16x16x32_bf16 v[40:43], v[176:179], v[184:187], v[40:43]
	v_mfma_f32_16x16x32_bf16 v[36:39], v[168:171], v[192:195], v[36:39]
	v_mfma_f32_16x16x32_bf16 v[32:35], v[176:179], v[192:195], v[32:35]
	v_mfma_f32_16x16x32_bf16 v[12:15], v[168:171], v[200:203], v[12:15]
	v_mfma_f32_16x16x32_bf16 v[8:11], v[176:179], v[200:203], v[8:11]
	v_mfma_f32_16x16x32_bf16 v[4:7], v[168:171], v[210:213], v[4:7]
	v_mfma_f32_16x16x32_bf16 v[0:3], v[176:179], v[210:213], v[0:3]
	v_mfma_f32_16x16x32_bf16 v[44:47], v[172:175], v[188:191], v[44:47]
	v_mfma_f32_16x16x32_bf16 v[40:43], v[180:183], v[188:191], v[40:43]
	v_mfma_f32_16x16x32_bf16 v[36:39], v[172:175], v[196:199], v[36:39]
	v_mfma_f32_16x16x32_bf16 v[32:35], v[180:183], v[196:199], v[32:35]
	v_mfma_f32_16x16x32_bf16 v[12:15], v[172:175], v[206:209], v[12:15]
	v_mfma_f32_16x16x32_bf16 v[8:11], v[180:183], v[206:209], v[8:11]
	v_mfma_f32_16x16x32_bf16 v[4:7], v[172:175], v[214:217], v[4:7]
	v_mfma_f32_16x16x32_bf16 v[0:3], v[180:183], v[214:217], v[0:3]
	s_barrier
	s_add_i32 s51, 0, 0x18000
	s_add_i32 s52, 0, 0x1c000
	v_add_u32_e32 v164, s51, v151
	v_add_u32_e32 v180, s52, v151
	ds_read_b128 v[144:147], v164
	ds_read_b128 v[156:159], v164 offset:1024
	ds_read_b128 v[160:163], v164 offset:2048
	ds_read_b128 v[164:167], v164 offset:3072
	ds_read_b128 v[168:171], v180
	ds_read_b128 v[172:175], v180 offset:1024
	ds_read_b128 v[176:179], v180 offset:2048
	ds_read_b128 v[180:183], v180 offset:3072
	s_add_u32 s26, s26, 0x80000
	s_addc_u32 s27, s27, 0
	s_mov_b32 m0, s39
	v_lshl_add_u64 v[224:225], s[26:27], 0, v[128:129]
	ds_read_b128 v[184:187], v155 offset:32768
	ds_read_b128 v[188:191], v155 offset:33792
	ds_read_b128 v[192:195], v155 offset:34816
	ds_read_b128 v[196:199], v155 offset:35840
	ds_read_b128 v[200:203], v155 offset:36864
	ds_read_b128 v[206:209], v155 offset:37888
	ds_read_b128 v[210:213], v155 offset:38912
	ds_read_b128 v[214:217], v155 offset:39936
	global_load_lds_dwordx4 v[224:225], off
	v_lshl_add_u64 v[224:225], s[26:27], 0, v[132:133]
	s_mov_b32 m0, s40
	s_nop 0
	global_load_lds_dwordx4 v[224:225], off
	s_waitcnt vmcnt(8)
	s_waitcnt lgkmcnt(0)
	s_barrier
	v_mfma_f32_16x16x32_bf16 v[124:127], v[144:147], v[184:187], v[124:127]
	v_mfma_f32_16x16x32_bf16 v[120:123], v[160:163], v[184:187], v[120:123]
	v_mfma_f32_16x16x32_bf16 v[116:119], v[144:147], v[192:195], v[116:119]
	v_mfma_f32_16x16x32_bf16 v[112:115], v[160:163], v[192:195], v[112:115]
	v_mfma_f32_16x16x32_bf16 v[92:95], v[144:147], v[200:203], v[92:95]
	v_mfma_f32_16x16x32_bf16 v[88:91], v[160:163], v[200:203], v[88:91]
	v_mfma_f32_16x16x32_bf16 v[84:87], v[144:147], v[210:213], v[84:87]
	v_mfma_f32_16x16x32_bf16 v[80:83], v[160:163], v[210:213], v[80:83]
	v_mfma_f32_16x16x32_bf16 v[124:127], v[156:159], v[188:191], v[124:127]
	v_mfma_f32_16x16x32_bf16 v[120:123], v[164:167], v[188:191], v[120:123]
	v_mfma_f32_16x16x32_bf16 v[116:119], v[156:159], v[196:199], v[116:119]
	v_mfma_f32_16x16x32_bf16 v[112:115], v[164:167], v[196:199], v[112:115]
	v_mfma_f32_16x16x32_bf16 v[92:95], v[156:159], v[206:209], v[92:95]
	v_mfma_f32_16x16x32_bf16 v[88:91], v[164:167], v[206:209], v[88:91]
	v_mfma_f32_16x16x32_bf16 v[84:87], v[156:159], v[214:217], v[84:87]
	v_mfma_f32_16x16x32_bf16 v[80:83], v[164:167], v[214:217], v[80:83]
	v_mfma_f32_16x16x32_bf16 v[108:111], v[168:171], v[184:187], v[108:111]
	v_mfma_f32_16x16x32_bf16 v[104:107], v[176:179], v[184:187], v[104:107]
	v_mfma_f32_16x16x32_bf16 v[100:103], v[168:171], v[192:195], v[100:103]
	v_mfma_f32_16x16x32_bf16 v[96:99], v[176:179], v[192:195], v[96:99]
	v_mfma_f32_16x16x32_bf16 v[76:79], v[168:171], v[200:203], v[76:79]
	v_mfma_f32_16x16x32_bf16 v[72:75], v[176:179], v[200:203], v[72:75]
	v_mfma_f32_16x16x32_bf16 v[68:71], v[168:171], v[210:213], v[68:71]
	v_mfma_f32_16x16x32_bf16 v[64:67], v[176:179], v[210:213], v[64:67]
	v_mfma_f32_16x16x32_bf16 v[108:111], v[172:175], v[188:191], v[108:111]
	v_mfma_f32_16x16x32_bf16 v[104:107], v[180:183], v[188:191], v[104:107]
	v_mfma_f32_16x16x32_bf16 v[100:103], v[172:175], v[196:199], v[100:103]
	v_mfma_f32_16x16x32_bf16 v[96:99], v[180:183], v[196:199], v[96:99]
	v_mfma_f32_16x16x32_bf16 v[76:79], v[172:175], v[206:209], v[76:79]
	v_mfma_f32_16x16x32_bf16 v[72:75], v[180:183], v[206:209], v[72:75]
	v_mfma_f32_16x16x32_bf16 v[68:71], v[172:175], v[214:217], v[68:71]
	v_mfma_f32_16x16x32_bf16 v[64:67], v[180:183], v[214:217], v[64:67]
	s_barrier
; #define PG8_STAGE(bufoff, gbase, voff) do { _Pragma("unroll") for (int _i = 0; _i < 2; ++_i) \
;         __builtin_amdgcn_global_load_lds((const unsigned*)((const char*)(gbase) + (voff)[_i]), (PG8_LAS unsigned*)(lds + (bufoff) + ldsw + _i * 8192), 16, 0, 0); } while (0)
; #define PG8_LDA(dst, b, h) do { _Pragma("unroll") for (int m = 0; m < 4; ++m) _Pragma("unroll") for (int k = 0; k < 2; ++k) dst[m][k] = *(const PG8_LAS bf16x8*)(lds + PG8_SA(b, h) + aoff + m * 2048 + k * 1024); } while (0)
; #define PG8_MMA(ai, bj, At, Bt) do { __builtin_amdgcn_s_setprio(1); _Pragma("unroll") for (int m = 0; m < 4; ++m) _Pragma("unroll") for (int n = 0; n < 2; ++n) _Pragma("unroll") for (int k = 0; k < 2; ++k) \
;         acc[ai][bj][m][n] = __builtin_amdgcn_mfma_f32_16x16x32_bf16(Bt[n][k], At[m][k], acc[ai][bj][m][n], 0, 0, 0); __builtin_amdgcn_s_setprio(0); } while (0)
; #define PG8_WAIT_V(n) asm volatile("s_waitcnt vmcnt(" #n ")" ::: "memory")
; #define PG8_WAIT_L(n) asm volatile("s_waitcnt lgkmcnt(" #n ")" ::: "memory")
; #define PG8_BAR __builtin_amdgcn_s_barrier()
; #define PG8_SCHED __builtin_amdgcn_sched_barrier(0)
; template <class Epi, class Sched, bool ALIGN_EPI = false, bool SP2 = false>
; __device__ __forceinline__ void gemm_phase(PG8_LAS unsigned char* lds, const Gemm g, const Sched& S, const Epi& E, const int wv0) {
;     ...
;             PG8_LDA(At, 1, 1); PG8_STAGE(PG8_SB(1, 0), b3, voffB); PG8_STAGE(PG8_SB(1, 1), b3 + hstepB, voffB); PG8_STAGE(PG8_SA(1, 0), a3, voffA);
;             PG8_WAIT_V(8); PG8_WAIT_L(0); PG8_BAR; PG8_MMA(1, 0, At, B0); PG8_MMA(1, 1, At, B1); PG8_BAR; PG8_SCHED;
;     ...
;         if constexpr (ALIGN_EPI) { if (wr == 0) PG8_BAR; }
	ds_read_b128 v[184:187], v155 offset:49152
	ds_read_b128 v[188:191], v155 offset:50176
	ds_read_b128 v[192:195], v155 offset:51200
	ds_read_b128 v[196:199], v155 offset:52224
	ds_read_b128 v[200:203], v155 offset:53248
	ds_read_b128 v[206:209], v155 offset:54272
	ds_read_b128 v[210:213], v155 offset:55296
	ds_read_b128 v[214:217], v155 offset:56320
	s_add_i32 s26, s51, s37
	s_mov_b32 m0, s26
	v_lshl_add_u64 v[148:149], v[148:149], 0, s[8:9]
	global_load_lds_dwordx4 v[148:149], off
	s_add_i32 m0, s26, 0x2000
	s_add_u32 s24, s24, 0x80080
	v_lshl_add_u64 v[148:149], v[218:219], 0, s[8:9]
	s_addc_u32 s25, s25, 0
	s_add_i32 s26, s52, s37
	global_load_lds_dwordx4 v[148:149], off
	v_lshl_add_u64 v[148:149], s[24:25], 0, v[130:131]
	s_mov_b32 m0, s26
	s_nop 0
	global_load_lds_dwordx4 v[148:149], off
	v_lshl_add_u64 v[148:149], s[24:25], 0, v[134:135]
	s_add_i32 m0, s26, 0x2000
	s_nop 0
	global_load_lds_dwordx4 v[148:149], off
	v_lshl_add_u64 v[148:149], v[220:221], 0, s[8:9]
	s_mov_b32 m0, s44
	s_nop 0
	global_load_lds_dwordx4 v[148:149], off
	v_lshl_add_u64 v[148:149], v[222:223], 0, s[8:9]
	s_mov_b32 m0, s45
	s_nop 0
	global_load_lds_dwordx4 v[148:149], off
	s_waitcnt vmcnt(8)
	s_waitcnt lgkmcnt(0)
	s_barrier
	v_mfma_f32_16x16x32_bf16 v[60:63], v[144:147], v[184:187], v[60:63]
	v_mfma_f32_16x16x32_bf16 v[56:59], v[160:163], v[184:187], v[56:59]
	v_mfma_f32_16x16x32_bf16 v[52:55], v[144:147], v[192:195], v[52:55]
	v_mfma_f32_16x16x32_bf16 v[48:51], v[160:163], v[192:195], v[48:51]
	v_mfma_f32_16x16x32_bf16 v[28:31], v[144:147], v[200:203], v[28:31]
	v_mfma_f32_16x16x32_bf16 v[24:27], v[160:163], v[200:203], v[24:27]
	v_mfma_f32_16x16x32_bf16 v[20:23], v[144:147], v[210:213], v[20:23]
	v_mfma_f32_16x16x32_bf16 v[16:19], v[160:163], v[210:213], v[16:19]
	v_mfma_f32_16x16x32_bf16 v[60:63], v[156:159], v[188:191], v[60:63]
	v_mfma_f32_16x16x32_bf16 v[56:59], v[164:167], v[188:191], v[56:59]
	v_mfma_f32_16x16x32_bf16 v[52:55], v[156:159], v[196:199], v[52:55]
	v_mfma_f32_16x16x32_bf16 v[48:51], v[164:167], v[196:199], v[48:51]
	v_mfma_f32_16x16x32_bf16 v[28:31], v[156:159], v[206:209], v[28:31]
	v_mfma_f32_16x16x32_bf16 v[24:27], v[164:167], v[206:209], v[24:27]
	v_mfma_f32_16x16x32_bf16 v[20:23], v[156:159], v[214:217], v[20:23]
	v_mfma_f32_16x16x32_bf16 v[16:19], v[164:167], v[214:217], v[16:19]
	v_mfma_f32_16x16x32_bf16 v[44:47], v[168:171], v[184:187], v[44:47]
	v_mfma_f32_16x16x32_bf16 v[40:43], v[176:179], v[184:187], v[40:43]
	v_mfma_f32_16x16x32_bf16 v[36:39], v[168:171], v[192:195], v[36:39]
	v_mfma_f32_16x16x32_bf16 v[32:35], v[176:179], v[192:195], v[32:35]
	v_mfma_f32_16x16x32_bf16 v[12:15], v[168:171], v[200:203], v[12:15]
	v_mfma_f32_16x16x32_bf16 v[8:11], v[176:179], v[200:203], v[8:11]
	v_mfma_f32_16x16x32_bf16 v[4:7], v[168:171], v[210:213], v[4:7]
	v_mfma_f32_16x16x32_bf16 v[0:3], v[176:179], v[210:213], v[0:3]
	v_mfma_f32_16x16x32_bf16 v[44:47], v[172:175], v[188:191], v[44:47]
	v_mfma_f32_16x16x32_bf16 v[40:43], v[180:183], v[188:191], v[40:43]
	v_mfma_f32_16x16x32_bf16 v[36:39], v[172:175], v[196:199], v[36:39]
	v_mfma_f32_16x16x32_bf16 v[32:35], v[180:183], v[196:199], v[32:35]
	v_mfma_f32_16x16x32_bf16 v[12:15], v[172:175], v[206:209], v[12:15]
	v_mfma_f32_16x16x32_bf16 v[8:11], v[180:183], v[206:209], v[8:11]
	v_mfma_f32_16x16x32_bf16 v[4:7], v[172:175], v[214:217], v[4:7]
	v_mfma_f32_16x16x32_bf16 v[0:3], v[180:183], v[214:217], v[0:3]
	s_barrier
	s_add_i32 s50, s50, 2
	s_add_u32 s13, s13, 0x100
	s_addc_u32 s15, s15, 0
	s_add_u32 s22, s22, 0x100
	s_addc_u32 s23, s23, 0
	s_cmp_gt_u32 s50, 29
	s_cbranch_scc0 .LBB0_667
	s_and_b64 vcc, exec, s[10:11]
	s_cbranch_vccz .LBB0_670
	s_barrier

; #define PG8_STAGE(bufoff, gbase, voff) do { _Pragma("unroll") for (int _i = 0; _i < 2; ++_i) \
;         __builtin_amdgcn_global_load_lds((const unsigned*)((const char*)(gbase) + (voff)[_i]), (PG8_LAS unsigned*)(lds + (bufoff) + ldsw + _i * 8192), 16, 0, 0); } while (0)
; #define PG8_LDA(dst, b, h) do { _Pragma("unroll") for (int m = 0; m < 4; ++m) _Pragma("unroll") for (int k = 0; k < 2; ++k) dst[m][k] = *(const PG8_LAS bf16x8*)(lds + PG8_SA(b, h) + aoff + m * 2048 + k * 1024); } while (0)
; #define PG8_LDB(dst, b, h) do { _Pragma("unroll") for (int n = 0; n < 2; ++n) _Pragma("unroll") for (int k = 0; k < 2; ++k) dst[n][k] = *(const PG8_LAS bf16x8*)(lds + PG8_SB(b, h) + boff + n * 2048 + k * 1024); } while (0)
; #define PG8_MMA(ai, bj, At, Bt) do { __builtin_amdgcn_s_setprio(1); _Pragma("unroll") for (int m = 0; m < 4; ++m) _Pragma("unroll") for (int n = 0; n < 2; ++n) _Pragma("unroll") for (int k = 0; k < 2; ++k) \
;         acc[ai][bj][m][n] = __builtin_amdgcn_mfma_f32_16x16x32_bf16(Bt[n][k], At[m][k], acc[ai][bj][m][n], 0, 0, 0); __builtin_amdgcn_s_setprio(0); } while (0)
; #define PG8_WAIT_V(n) asm volatile("s_waitcnt vmcnt(" #n ")" ::: "memory")
; #define PG8_WAIT_L(n) asm volatile("s_waitcnt lgkmcnt(" #n ")" ::: "memory")
; #define PG8_BAR __builtin_amdgcn_s_barrier()
; template <class Epi, class Sched, bool ALIGN_EPI = false, bool SP2 = false>
; __device__ __forceinline__ void gemm_phase(PG8_LAS unsigned char* lds, const Gemm g, const Sched& S, const Epi& E, const int wv0) {
;     ...
;             const bool last = (t == nt - 2);
;             const char* a1 = cA + (size_t)(t + 1) * kstep;
;             const char* a2 = last ? nA : cA + (size_t)(t + 2) * kstep; const char* b2 = last ? nB : cB + (size_t)(t + 2) * kstep;
;             const char* a3 = a2 + kstep; const char* b3 = b2 + kstep;
;             if constexpr (SP2) {
;             PG8_LDB(B0, 0, 0); PG8_LDB(B1, 0, 1); PG8_SCHED; PG8_LDA(At, 0, 0); PG8_STAGE(PG8_SA(1, 1), a1 + hstepA, voffA);
;             PG8_WAIT_V(8); PG8_WAIT_L(0); PG8_BAR; PG8_MMA(0, 0, At, B0); PG8_MMA(0, 1, At, B1); PG8_BAR; PG8_SCHED;
;             PG8_LDA(At, 0, 1); PG8_STAGE(PG8_SB(0, 0), b2, voffB); PG8_STAGE(PG8_SB(0, 1), b2 + hstepB, voffB); PG8_STAGE(PG8_SA(0, 0), a2, voffA);
;             PG8_WAIT_V(8); PG8_WAIT_L(0); PG8_BAR; PG8_MMA(1, 0, At, B0); PG8_MMA(1, 1, At, B1); PG8_BAR; PG8_SCHED;
.LBB0_790:
	ds_read_b128 v[152:155], v149
	ds_read_b128 v[156:159], v149 offset:1024
	ds_read_b128 v[160:163], v149 offset:2048
	ds_read_b128 v[164:167], v149 offset:3072
	ds_read_b128 v[168:171], v150
	ds_read_b128 v[172:175], v150 offset:1024
	ds_read_b128 v[176:179], v150 offset:2048
	ds_read_b128 v[180:183], v150 offset:3072
	s_add_u32 s22, s20, 0xfff80080
	s_addc_u32 s23, s21, -1
	s_cmp_eq_u32 s50, 28
	s_cselect_b32 s25, s15, s23
	s_cselect_b32 s24, s14, s22
	s_cselect_b32 s23, s17, s13
	s_cselect_b32 s22, s16, s11
	v_lshl_add_u64 v[144:145], s[20:21], 0, v[138:139]
	s_add_i32 m0, s19, 0xc000
	ds_read_b128 v[184:187], v151
	ds_read_b128 v[188:191], v151 offset:1024
	ds_read_b128 v[192:195], v151 offset:2048
	ds_read_b128 v[196:199], v151 offset:3072
	ds_read_b128 v[200:203], v151 offset:4096
	ds_read_b128 v[206:209], v151 offset:5120
	ds_read_b128 v[210:213], v151 offset:6144
	ds_read_b128 v[214:217], v151 offset:7168
	global_load_lds_dwordx4 v[144:145], off
	v_lshl_add_u64 v[144:145], s[20:21], 0, v[136:137]
	s_add_i32 m0, s19, 0xe000
	s_nop 0
	global_load_lds_dwordx4 v[144:145], off
	s_waitcnt vmcnt(8)
	s_waitcnt lgkmcnt(0)
	s_barrier
	v_mfma_f32_16x16x32_bf16 v[124:127], v[152:155], v[184:187], v[124:127]
	v_mfma_f32_16x16x32_bf16 v[120:123], v[160:163], v[184:187], v[120:123]
	v_mfma_f32_16x16x32_bf16 v[108:111], v[152:155], v[192:195], v[108:111]
	v_mfma_f32_16x16x32_bf16 v[104:107], v[160:163], v[192:195], v[104:107]
	v_mfma_f32_16x16x32_bf16 v[92:95], v[152:155], v[200:203], v[92:95]
	v_mfma_f32_16x16x32_bf16 v[88:91], v[160:163], v[200:203], v[88:91]
	v_mfma_f32_16x16x32_bf16 v[76:79], v[152:155], v[210:213], v[76:79]
	v_mfma_f32_16x16x32_bf16 v[72:75], v[160:163], v[210:213], v[72:75]
	v_mfma_f32_16x16x32_bf16 v[124:127], v[156:159], v[188:191], v[124:127]
	v_mfma_f32_16x16x32_bf16 v[120:123], v[164:167], v[188:191], v[120:123]
	v_mfma_f32_16x16x32_bf16 v[108:111], v[156:159], v[196:199], v[108:111]
	v_mfma_f32_16x16x32_bf16 v[104:107], v[164:167], v[196:199], v[104:107]
	v_mfma_f32_16x16x32_bf16 v[92:95], v[156:159], v[206:209], v[92:95]
	v_mfma_f32_16x16x32_bf16 v[88:91], v[164:167], v[206:209], v[88:91]
	v_mfma_f32_16x16x32_bf16 v[76:79], v[156:159], v[214:217], v[76:79]
	v_mfma_f32_16x16x32_bf16 v[72:75], v[164:167], v[214:217], v[72:75]
	v_mfma_f32_16x16x32_bf16 v[116:119], v[168:171], v[184:187], v[116:119]
	v_mfma_f32_16x16x32_bf16 v[112:115], v[176:179], v[184:187], v[112:115]
	v_mfma_f32_16x16x32_bf16 v[100:103], v[168:171], v[192:195], v[100:103]
	v_mfma_f32_16x16x32_bf16 v[96:99], v[176:179], v[192:195], v[96:99]
	v_mfma_f32_16x16x32_bf16 v[84:87], v[168:171], v[200:203], v[84:87]
	v_mfma_f32_16x16x32_bf16 v[80:83], v[176:179], v[200:203], v[80:83]
	v_mfma_f32_16x16x32_bf16 v[68:71], v[168:171], v[210:213], v[68:71]
	v_mfma_f32_16x16x32_bf16 v[64:67], v[176:179], v[210:213], v[64:67]
	v_mfma_f32_16x16x32_bf16 v[116:119], v[172:175], v[188:191], v[116:119]
	v_mfma_f32_16x16x32_bf16 v[112:115], v[180:183], v[188:191], v[112:115]
	v_mfma_f32_16x16x32_bf16 v[100:103], v[172:175], v[196:199], v[100:103]
	v_mfma_f32_16x16x32_bf16 v[96:99], v[180:183], v[196:199], v[96:99]
	v_mfma_f32_16x16x32_bf16 v[84:87], v[172:175], v[206:209], v[84:87]
	v_mfma_f32_16x16x32_bf16 v[80:83], v[180:183], v[206:209], v[80:83]
	v_mfma_f32_16x16x32_bf16 v[68:71], v[172:175], v[214:217], v[68:71]
	v_mfma_f32_16x16x32_bf16 v[64:67], v[180:183], v[214:217], v[64:67]
	s_barrier
	ds_read_b128 v[184:187], v151 offset:16384
	ds_read_b128 v[188:191], v151 offset:17408
	ds_read_b128 v[192:195], v151 offset:18432
	ds_read_b128 v[196:199], v151 offset:19456
	ds_read_b128 v[200:203], v151 offset:20480
	ds_read_b128 v[206:209], v151 offset:21504
	ds_read_b128 v[210:213], v151 offset:22528
	ds_read_b128 v[214:217], v151 offset:23552
	s_add_i32 s51, s46, s35
	s_mov_b32 m0, s51
	v_lshl_add_u64 v[144:145], s[22:23], 0, v[132:133]
	global_load_lds_dwordx4 v[144:145], off
	s_add_i32 m0, s51, 0x2000
	s_add_u32 s52, s22, 0x80000
	v_lshl_add_u64 v[218:219], s[22:23], 0, v[128:129]
	s_addc_u32 s53, s23, 0
	s_add_i32 s51, s47, s35
	global_load_lds_dwordx4 v[218:219], off
	v_lshl_add_u64 v[220:221], s[52:53], 0, v[132:133]
	s_mov_b32 m0, s51
	v_lshl_add_u64 v[222:223], s[24:25], 0, v[130:131]
	global_load_lds_dwordx4 v[220:221], off
	v_lshl_add_u64 v[220:221], s[52:53], 0, v[128:129]
	s_add_i32 m0, s51, 0x2000
	s_nop 0
	global_load_lds_dwordx4 v[220:221], off
	v_lshl_add_u64 v[220:221], s[24:25], 0, v[134:135]
	s_mov_b32 m0, s19
	s_nop 0
	global_load_lds_dwordx4 v[220:221], off
	s_mov_b32 m0, s37
	s_nop 0
	global_load_lds_dwordx4 v[222:223], off
	s_waitcnt vmcnt(8)
	s_waitcnt lgkmcnt(0)
	s_barrier
; #define PG8_STAGE(bufoff, gbase, voff) do { _Pragma("unroll") for (int _i = 0; _i < 2; ++_i) \
;         __builtin_amdgcn_global_load_lds((const unsigned*)((const char*)(gbase) + (voff)[_i]), (PG8_LAS unsigned*)(lds + (bufoff) + ldsw + _i * 8192), 16, 0, 0); } while (0)
; #define PG8_LDA(dst, b, h) do { _Pragma("unroll") for (int m = 0; m < 4; ++m) _Pragma("unroll") for (int k = 0; k < 2; ++k) dst[m][k] = *(const PG8_LAS bf16x8*)(lds + PG8_SA(b, h) + aoff + m * 2048 + k * 1024); } while (0)
; #define PG8_LDB(dst, b, h) do { _Pragma("unroll") for (int n = 0; n < 2; ++n) _Pragma("unroll") for (int k = 0; k < 2; ++k) dst[n][k] = *(const PG8_LAS bf16x8*)(lds + PG8_SB(b, h) + boff + n * 2048 + k * 1024); } while (0)
; #define PG8_MMA(ai, bj, At, Bt) do { __builtin_amdgcn_s_setprio(1); _Pragma("unroll") for (int m = 0; m < 4; ++m) _Pragma("unroll") for (int n = 0; n < 2; ++n) _Pragma("unroll") for (int k = 0; k < 2; ++k) \
;         acc[ai][bj][m][n] = __builtin_amdgcn_mfma_f32_16x16x32_bf16(Bt[n][k], At[m][k], acc[ai][bj][m][n], 0, 0, 0); __builtin_amdgcn_s_setprio(0); } while (0)
; #define PG8_WAIT_V(n) asm volatile("s_waitcnt vmcnt(" #n ")" ::: "memory")
; #define PG8_WAIT_L(n) asm volatile("s_waitcnt lgkmcnt(" #n ")" ::: "memory")
; #define PG8_BAR __builtin_amdgcn_s_barrier()
; #define PG8_SCHED __builtin_amdgcn_sched_barrier(0)
; template <class Epi, class Sched, bool ALIGN_EPI = false, bool SP2 = false>
; __device__ __forceinline__ void gemm_phase(PG8_LAS unsigned char* lds, const Gemm g, const Sched& S, const Epi& E, const int wv0) {
;     ...
;             PG8_WAIT_V(8); PG8_WAIT_L(0); PG8_BAR; PG8_MMA(1, 0, At, B0); PG8_MMA(1, 1, At, B1); PG8_BAR; PG8_SCHED;
;             PG8_LDB(B0, 1, 0); PG8_LDB(B1, 1, 1); PG8_SCHED; PG8_LDA(At, 1, 0); PG8_STAGE(PG8_SA(0, 1), a2 + hstepA, voffA);
;             PG8_WAIT_V(8); PG8_WAIT_L(0); PG8_BAR; PG8_MMA(0, 0, At, B0); PG8_MMA(0, 1, At, B1); PG8_BAR; PG8_SCHED;
	v_mfma_f32_16x16x32_bf16 v[60:63], v[152:155], v[184:187], v[60:63]
	v_mfma_f32_16x16x32_bf16 v[56:59], v[160:163], v[184:187], v[56:59]
	v_mfma_f32_16x16x32_bf16 v[44:47], v[152:155], v[192:195], v[44:47]
	v_mfma_f32_16x16x32_bf16 v[40:43], v[160:163], v[192:195], v[40:43]
	v_mfma_f32_16x16x32_bf16 v[28:31], v[152:155], v[200:203], v[28:31]
	v_mfma_f32_16x16x32_bf16 v[24:27], v[160:163], v[200:203], v[24:27]
	v_mfma_f32_16x16x32_bf16 v[12:15], v[152:155], v[210:213], v[12:15]
	v_mfma_f32_16x16x32_bf16 v[8:11], v[160:163], v[210:213], v[8:11]
	v_mfma_f32_16x16x32_bf16 v[60:63], v[156:159], v[188:191], v[60:63]
	v_mfma_f32_16x16x32_bf16 v[56:59], v[164:167], v[188:191], v[56:59]
	v_mfma_f32_16x16x32_bf16 v[44:47], v[156:159], v[196:199], v[44:47]
	v_mfma_f32_16x16x32_bf16 v[40:43], v[164:167], v[196:199], v[40:43]
	v_mfma_f32_16x16x32_bf16 v[28:31], v[156:159], v[206:209], v[28:31]
	v_mfma_f32_16x16x32_bf16 v[24:27], v[164:167], v[206:209], v[24:27]
	v_mfma_f32_16x16x32_bf16 v[12:15], v[156:159], v[214:217], v[12:15]
	v_mfma_f32_16x16x32_bf16 v[8:11], v[164:167], v[214:217], v[8:11]
	v_mfma_f32_16x16x32_bf16 v[52:55], v[168:171], v[184:187], v[52:55]
	v_mfma_f32_16x16x32_bf16 v[48:51], v[176:179], v[184:187], v[48:51]
	v_mfma_f32_16x16x32_bf16 v[36:39], v[168:171], v[192:195], v[36:39]
	v_mfma_f32_16x16x32_bf16 v[32:35], v[176:179], v[192:195], v[32:35]
	v_mfma_f32_16x16x32_bf16 v[20:23], v[168:171], v[200:203], v[20:23]
	v_mfma_f32_16x16x32_bf16 v[16:19], v[176:179], v[200:203], v[16:19]
	v_mfma_f32_16x16x32_bf16 v[4:7], v[168:171], v[210:213], v[4:7]
	v_mfma_f32_16x16x32_bf16 v[0:3], v[176:179], v[210:213], v[0:3]
	v_mfma_f32_16x16x32_bf16 v[52:55], v[172:175], v[188:191], v[52:55]
	v_mfma_f32_16x16x32_bf16 v[48:51], v[180:183], v[188:191], v[48:51]
	v_mfma_f32_16x16x32_bf16 v[36:39], v[172:175], v[196:199], v[36:39]
	v_mfma_f32_16x16x32_bf16 v[32:35], v[180:183], v[196:199], v[32:35]
	v_mfma_f32_16x16x32_bf16 v[20:23], v[172:175], v[206:209], v[20:23]
	v_mfma_f32_16x16x32_bf16 v[16:19], v[180:183], v[206:209], v[16:19]
	v_mfma_f32_16x16x32_bf16 v[4:7], v[172:175], v[214:217], v[4:7]
	v_mfma_f32_16x16x32_bf16 v[0:3], v[180:183], v[214:217], v[0:3]
	s_barrier
	s_add_i32 s51, 0, 0x18000
	s_add_i32 s52, 0, 0x1c000
	v_add_u32_e32 v164, s51, v147
	v_add_u32_e32 v180, s52, v147
	ds_read_b128 v[152:155], v164
	ds_read_b128 v[156:159], v164 offset:1024
	ds_read_b128 v[160:163], v164 offset:2048
	ds_read_b128 v[164:167], v164 offset:3072
	ds_read_b128 v[168:171], v180
	ds_read_b128 v[172:175], v180 offset:1024
	ds_read_b128 v[176:179], v180 offset:2048
	ds_read_b128 v[180:183], v180 offset:3072
	s_add_u32 s24, s24, 0x80000
	s_addc_u32 s25, s25, 0
	s_mov_b32 m0, s38
	v_lshl_add_u64 v[224:225], s[24:25], 0, v[134:135]
	ds_read_b128 v[184:187], v151 offset:32768
	ds_read_b128 v[188:191], v151 offset:33792
	ds_read_b128 v[192:195], v151 offset:34816
	ds_read_b128 v[196:199], v151 offset:35840
	ds_read_b128 v[200:203], v151 offset:36864
	ds_read_b128 v[206:209], v151 offset:37888
	ds_read_b128 v[210:213], v151 offset:38912
	ds_read_b128 v[214:217], v151 offset:39936
	global_load_lds_dwordx4 v[224:225], off
	v_lshl_add_u64 v[224:225], s[24:25], 0, v[130:131]
	s_mov_b32 m0, s39
	s_nop 0
	global_load_lds_dwordx4 v[224:225], off
	s_waitcnt vmcnt(8)
	s_waitcnt lgkmcnt(0)
	s_barrier
	v_mfma_f32_16x16x32_bf16 v[124:127], v[152:155], v[184:187], v[124:127]
	v_mfma_f32_16x16x32_bf16 v[120:123], v[160:163], v[184:187], v[120:123]
	v_mfma_f32_16x16x32_bf16 v[108:111], v[152:155], v[192:195], v[108:111]
	v_mfma_f32_16x16x32_bf16 v[104:107], v[160:163], v[192:195], v[104:107]
	v_mfma_f32_16x16x32_bf16 v[92:95], v[152:155], v[200:203], v[92:95]
	v_mfma_f32_16x16x32_bf16 v[88:91], v[160:163], v[200:203], v[88:91]
	v_mfma_f32_16x16x32_bf16 v[76:79], v[152:155], v[210:213], v[76:79]
	v_mfma_f32_16x16x32_bf16 v[72:75], v[160:163], v[210:213], v[72:75]
	v_mfma_f32_16x16x32_bf16 v[124:127], v[156:159], v[188:191], v[124:127]
	v_mfma_f32_16x16x32_bf16 v[120:123], v[164:167], v[188:191], v[120:123]
	v_mfma_f32_16x16x32_bf16 v[108:111], v[156:159], v[196:199], v[108:111]
	v_mfma_f32_16x16x32_bf16 v[104:107], v[164:167], v[196:199], v[104:107]
	v_mfma_f32_16x16x32_bf16 v[92:95], v[156:159], v[206:209], v[92:95]
	v_mfma_f32_16x16x32_bf16 v[88:91], v[164:167], v[206:209], v[88:91]
	v_mfma_f32_16x16x32_bf16 v[76:79], v[156:159], v[214:217], v[76:79]
	v_mfma_f32_16x16x32_bf16 v[72:75], v[164:167], v[214:217], v[72:75]
	v_mfma_f32_16x16x32_bf16 v[116:119], v[168:171], v[184:187], v[116:119]
	v_mfma_f32_16x16x32_bf16 v[112:115], v[176:179], v[184:187], v[112:115]
	v_mfma_f32_16x16x32_bf16 v[100:103], v[168:171], v[192:195], v[100:103]
	v_mfma_f32_16x16x32_bf16 v[96:99], v[176:179], v[192:195], v[96:99]
	v_mfma_f32_16x16x32_bf16 v[84:87], v[168:171], v[200:203], v[84:87]
	v_mfma_f32_16x16x32_bf16 v[80:83], v[176:179], v[200:203], v[80:83]
	v_mfma_f32_16x16x32_bf16 v[68:71], v[168:171], v[210:213], v[68:71]
	v_mfma_f32_16x16x32_bf16 v[64:67], v[176:179], v[210:213], v[64:67]
	v_mfma_f32_16x16x32_bf16 v[116:119], v[172:175], v[188:191], v[116:119]
	v_mfma_f32_16x16x32_bf16 v[112:115], v[180:183], v[188:191], v[112:115]
	v_mfma_f32_16x16x32_bf16 v[100:103], v[172:175], v[196:199], v[100:103]
	v_mfma_f32_16x16x32_bf16 v[96:99], v[180:183], v[196:199], v[96:99]
	v_mfma_f32_16x16x32_bf16 v[84:87], v[172:175], v[206:209], v[84:87]
	v_mfma_f32_16x16x32_bf16 v[80:83], v[180:183], v[206:209], v[80:83]
	v_mfma_f32_16x16x32_bf16 v[68:71], v[172:175], v[214:217], v[68:71]
	v_mfma_f32_16x16x32_bf16 v[64:67], v[180:183], v[214:217], v[64:67]
	s_barrier
; #define PG8_STAGE(bufoff, gbase, voff) do { _Pragma("unroll") for (int _i = 0; _i < 2; ++_i) \
;         __builtin_amdgcn_global_load_lds((const unsigned*)((const char*)(gbase) + (voff)[_i]), (PG8_LAS unsigned*)(lds + (bufoff) + ldsw + _i * 8192), 16, 0, 0); } while (0)
; #define PG8_LDA(dst, b, h) do { _Pragma("unroll") for (int m = 0; m < 4; ++m) _Pragma("unroll") for (int k = 0; k < 2; ++k) dst[m][k] = *(const PG8_LAS bf16x8*)(lds + PG8_SA(b, h) + aoff + m * 2048 + k * 1024); } while (0)
; #define PG8_MMA(ai, bj, At, Bt) do { __builtin_amdgcn_s_setprio(1); _Pragma("unroll") for (int m = 0; m < 4; ++m) _Pragma("unroll") for (int n = 0; n < 2; ++n) _Pragma("unroll") for (int k = 0; k < 2; ++k) \
;         acc[ai][bj][m][n] = __builtin_amdgcn_mfma_f32_16x16x32_bf16(Bt[n][k], At[m][k], acc[ai][bj][m][n], 0, 0, 0); __builtin_amdgcn_s_setprio(0); } while (0)
; #define PG8_WAIT_V(n) asm volatile("s_waitcnt vmcnt(" #n ")" ::: "memory")
; #define PG8_WAIT_L(n) asm volatile("s_waitcnt lgkmcnt(" #n ")" ::: "memory")
; #define PG8_BAR __builtin_amdgcn_s_barrier()
; #define PG8_SCHED __builtin_amdgcn_sched_barrier(0)
; template <class Epi, class Sched, bool ALIGN_EPI = false, bool SP2 = false>
; __device__ __forceinline__ void gemm_phase(PG8_LAS unsigned char* lds, const Gemm g, const Sched& S, const Epi& E, const int wv0) {
;     ...
;             PG8_LDA(At, 1, 1); PG8_STAGE(PG8_SB(1, 0), b3, voffB); PG8_STAGE(PG8_SB(1, 1), b3 + hstepB, voffB); PG8_STAGE(PG8_SA(1, 0), a3, voffA);
;             PG8_WAIT_V(8); PG8_WAIT_L(0); PG8_BAR; PG8_MMA(1, 0, At, B0); PG8_MMA(1, 1, At, B1); PG8_BAR; PG8_SCHED;
;     ...
;         if constexpr (ALIGN_EPI) { if (wr == 0) PG8_BAR; }
	ds_read_b128 v[184:187], v151 offset:49152
	ds_read_b128 v[188:191], v151 offset:50176
	ds_read_b128 v[192:195], v151 offset:51200
	ds_read_b128 v[196:199], v151 offset:52224
	ds_read_b128 v[200:203], v151 offset:53248
	ds_read_b128 v[206:209], v151 offset:54272
	ds_read_b128 v[210:213], v151 offset:55296
	ds_read_b128 v[214:217], v151 offset:56320
	s_add_i32 s24, s51, s35
	s_mov_b32 m0, s24
	v_lshl_add_u64 v[144:145], v[144:145], 0, s[6:7]
	global_load_lds_dwordx4 v[144:145], off
	s_add_i32 m0, s24, 0x2000
	s_add_u32 s22, s22, 0x80080
	v_lshl_add_u64 v[144:145], v[218:219], 0, s[6:7]
	s_addc_u32 s23, s23, 0
	s_add_i32 s24, s52, s35
	global_load_lds_dwordx4 v[144:145], off
	v_lshl_add_u64 v[144:145], s[22:23], 0, v[132:133]
	s_mov_b32 m0, s24
	s_nop 0
	global_load_lds_dwordx4 v[144:145], off
	v_lshl_add_u64 v[144:145], s[22:23], 0, v[128:129]
	s_add_i32 m0, s24, 0x2000
	s_nop 0
	global_load_lds_dwordx4 v[144:145], off
	v_lshl_add_u64 v[144:145], v[220:221], 0, s[6:7]
	s_mov_b32 m0, s41
	s_nop 0
	global_load_lds_dwordx4 v[144:145], off
	v_lshl_add_u64 v[144:145], v[222:223], 0, s[6:7]
	s_mov_b32 m0, s44
	s_nop 0
	global_load_lds_dwordx4 v[144:145], off
	s_waitcnt vmcnt(8)
	s_waitcnt lgkmcnt(0)
	s_barrier
	v_mfma_f32_16x16x32_bf16 v[60:63], v[152:155], v[184:187], v[60:63]
	v_mfma_f32_16x16x32_bf16 v[56:59], v[160:163], v[184:187], v[56:59]
	v_mfma_f32_16x16x32_bf16 v[44:47], v[152:155], v[192:195], v[44:47]
	v_mfma_f32_16x16x32_bf16 v[40:43], v[160:163], v[192:195], v[40:43]
	v_mfma_f32_16x16x32_bf16 v[28:31], v[152:155], v[200:203], v[28:31]
	v_mfma_f32_16x16x32_bf16 v[24:27], v[160:163], v[200:203], v[24:27]
	v_mfma_f32_16x16x32_bf16 v[12:15], v[152:155], v[210:213], v[12:15]
	v_mfma_f32_16x16x32_bf16 v[8:11], v[160:163], v[210:213], v[8:11]
	v_mfma_f32_16x16x32_bf16 v[60:63], v[156:159], v[188:191], v[60:63]
	v_mfma_f32_16x16x32_bf16 v[56:59], v[164:167], v[188:191], v[56:59]
	v_mfma_f32_16x16x32_bf16 v[44:47], v[156:159], v[196:199], v[44:47]
	v_mfma_f32_16x16x32_bf16 v[40:43], v[164:167], v[196:199], v[40:43]
	v_mfma_f32_16x16x32_bf16 v[28:31], v[156:159], v[206:209], v[28:31]
	v_mfma_f32_16x16x32_bf16 v[24:27], v[164:167], v[206:209], v[24:27]
	v_mfma_f32_16x16x32_bf16 v[12:15], v[156:159], v[214:217], v[12:15]
	v_mfma_f32_16x16x32_bf16 v[8:11], v[164:167], v[214:217], v[8:11]
	v_mfma_f32_16x16x32_bf16 v[52:55], v[168:171], v[184:187], v[52:55]
	v_mfma_f32_16x16x32_bf16 v[48:51], v[176:179], v[184:187], v[48:51]
	v_mfma_f32_16x16x32_bf16 v[36:39], v[168:171], v[192:195], v[36:39]
	v_mfma_f32_16x16x32_bf16 v[32:35], v[176:179], v[192:195], v[32:35]
	v_mfma_f32_16x16x32_bf16 v[20:23], v[168:171], v[200:203], v[20:23]
	v_mfma_f32_16x16x32_bf16 v[16:19], v[176:179], v[200:203], v[16:19]
	v_mfma_f32_16x16x32_bf16 v[4:7], v[168:171], v[210:213], v[4:7]
	v_mfma_f32_16x16x32_bf16 v[0:3], v[176:179], v[210:213], v[0:3]
	v_mfma_f32_16x16x32_bf16 v[52:55], v[172:175], v[188:191], v[52:55]
	v_mfma_f32_16x16x32_bf16 v[48:51], v[180:183], v[188:191], v[48:51]
	v_mfma_f32_16x16x32_bf16 v[36:39], v[172:175], v[196:199], v[36:39]
	v_mfma_f32_16x16x32_bf16 v[32:35], v[180:183], v[196:199], v[32:35]
	v_mfma_f32_16x16x32_bf16 v[20:23], v[172:175], v[206:209], v[20:23]
	v_mfma_f32_16x16x32_bf16 v[16:19], v[180:183], v[206:209], v[16:19]
	v_mfma_f32_16x16x32_bf16 v[4:7], v[172:175], v[214:217], v[4:7]
	v_mfma_f32_16x16x32_bf16 v[0:3], v[180:183], v[214:217], v[0:3]
	s_barrier
	s_add_i32 s50, s50, 2
	s_add_u32 s11, s11, 0x100
	s_addc_u32 s13, s13, 0
	s_add_u32 s20, s20, 0x100
	s_addc_u32 s21, s21, 0
	s_cmp_gt_u32 s50, 29
	s_cbranch_scc0 .LBB0_790
	s_and_b64 vcc, exec, s[8:9]
	s_cbranch_vccz .LBB0_793
	s_barrier

; #define PG8_STAGE(bufoff, gbase, voff) do { _Pragma("unroll") for (int _i = 0; _i < 2; ++_i) \
;         __builtin_amdgcn_global_load_lds((const unsigned*)((const char*)(gbase) + (voff)[_i]), (PG8_LAS unsigned*)(lds + (bufoff) + ldsw + _i * 8192), 16, 0, 0); } while (0)
; #define PG8_LDA(dst, b, h) do { _Pragma("unroll") for (int m = 0; m < 4; ++m) _Pragma("unroll") for (int k = 0; k < 2; ++k) dst[m][k] = *(const PG8_LAS bf16x8*)(lds + PG8_SA(b, h) + aoff + m * 2048 + k * 1024); } while (0)
; #define PG8_LDB(dst, b, h) do { _Pragma("unroll") for (int n = 0; n < 2; ++n) _Pragma("unroll") for (int k = 0; k < 2; ++k) dst[n][k] = *(const PG8_LAS bf16x8*)(lds + PG8_SB(b, h) + boff + n * 2048 + k * 1024); } while (0)
; #define PG8_MMA(ai, bj, At, Bt) do { __builtin_amdgcn_s_setprio(1); _Pragma("unroll") for (int m = 0; m < 4; ++m) _Pragma("unroll") for (int n = 0; n < 2; ++n) _Pragma("unroll") for (int k = 0; k < 2; ++k) \
;         acc[ai][bj][m][n] = __builtin_amdgcn_mfma_f32_16x16x32_bf16(Bt[n][k], At[m][k], acc[ai][bj][m][n], 0, 0, 0); __builtin_amdgcn_s_setprio(0); } while (0)
; #define PG8_WAIT_V(n) asm volatile("s_waitcnt vmcnt(" #n ")" ::: "memory")
; #define PG8_WAIT_L(n) asm volatile("s_waitcnt lgkmcnt(" #n ")" ::: "memory")
; #define PG8_BAR __builtin_amdgcn_s_barrier()
; template <class Epi, class Sched, bool ALIGN_EPI = false, bool SP2 = false>
; __device__ __forceinline__ void gemm_phase(PG8_LAS unsigned char* lds, const Gemm g, const Sched& S, const Epi& E, const int wv0) {
;     ...
;             const bool last = (t == nt - 2);
;             const char* a1 = cA + (size_t)(t + 1) * kstep;
;             const char* a2 = last ? nA : cA + (size_t)(t + 2) * kstep; const char* b2 = last ? nB : cB + (size_t)(t + 2) * kstep;
;             const char* a3 = a2 + kstep; const char* b3 = b2 + kstep;
;             if constexpr (SP2) {
;             PG8_LDB(B0, 0, 0); PG8_LDB(B1, 0, 1); PG8_SCHED; PG8_LDA(At, 0, 0); PG8_STAGE(PG8_SA(1, 1), a1 + hstepA, voffA);
;             PG8_WAIT_V(8); PG8_WAIT_L(0); PG8_BAR; PG8_MMA(0, 0, At, B0); PG8_MMA(0, 1, At, B1); PG8_BAR; PG8_SCHED;
;             PG8_LDA(At, 0, 1); PG8_STAGE(PG8_SB(0, 0), b2, voffB); PG8_STAGE(PG8_SB(0, 1), b2 + hstepB, voffB); PG8_STAGE(PG8_SA(0, 0), a2, voffA);
;             PG8_WAIT_V(8); PG8_WAIT_L(0); PG8_BAR; PG8_MMA(1, 0, At, B0); PG8_MMA(1, 1, At, B1); PG8_BAR; PG8_SCHED;
.LBB0_867:
	ds_read_b128 v[144:147], v155
	ds_read_b128 v[148:151], v155 offset:1024
	ds_read_b128 v[158:161], v155 offset:2048
	ds_read_b128 v[162:165], v155 offset:3072
	ds_read_b128 v[166:169], v156
	ds_read_b128 v[170:173], v156 offset:1024
	ds_read_b128 v[174:177], v156 offset:2048
	ds_read_b128 v[178:181], v156 offset:3072
	s_add_u32 s24, s22, 0x100
	s_addc_u32 s25, s23, 0
	s_cmpk_eq_i32 s58, 0x54
	s_cselect_b32 s29, s19, s25
	s_cselect_b32 s28, s18, s24
	s_cselect_b32 s27, s21, s57
	s_cselect_b32 s26, s20, s56
	v_lshl_add_u64 v[202:203], s[22:23], 0, v[138:139]
	s_add_i32 m0, s40, 0xc000
	ds_read_b128 v[182:185], v157
	ds_read_b128 v[186:189], v157 offset:1024
	ds_read_b128 v[190:193], v157 offset:2048
	ds_read_b128 v[194:197], v157 offset:3072
	ds_read_b128 v[198:201], v157 offset:4096
	ds_read_b128 v[206:209], v157 offset:5120
	ds_read_b128 v[210:213], v157 offset:6144
	ds_read_b128 v[214:217], v157 offset:7168
	global_load_lds_dwordx4 v[202:203], off
	v_lshl_add_u64 v[202:203], s[22:23], 0, v[136:137]
	s_add_i32 m0, s40, 0xe000
	s_nop 0
	global_load_lds_dwordx4 v[202:203], off
	s_waitcnt vmcnt(8)
	s_waitcnt lgkmcnt(0)
	s_barrier
	v_mfma_f32_16x16x32_bf16 v[124:127], v[144:147], v[182:185], v[124:127]
	v_mfma_f32_16x16x32_bf16 v[120:123], v[158:161], v[182:185], v[120:123]
	v_mfma_f32_16x16x32_bf16 v[116:119], v[144:147], v[190:193], v[116:119]
	v_mfma_f32_16x16x32_bf16 v[112:115], v[158:161], v[190:193], v[112:115]
	v_mfma_f32_16x16x32_bf16 v[92:95], v[144:147], v[198:201], v[92:95]
	v_mfma_f32_16x16x32_bf16 v[88:91], v[158:161], v[198:201], v[88:91]
	v_mfma_f32_16x16x32_bf16 v[84:87], v[144:147], v[210:213], v[84:87]
	v_mfma_f32_16x16x32_bf16 v[80:83], v[158:161], v[210:213], v[80:83]
	v_mfma_f32_16x16x32_bf16 v[124:127], v[148:151], v[186:189], v[124:127]
	v_mfma_f32_16x16x32_bf16 v[120:123], v[162:165], v[186:189], v[120:123]
	v_mfma_f32_16x16x32_bf16 v[116:119], v[148:151], v[194:197], v[116:119]
	v_mfma_f32_16x16x32_bf16 v[112:115], v[162:165], v[194:197], v[112:115]
	v_mfma_f32_16x16x32_bf16 v[92:95], v[148:151], v[206:209], v[92:95]
	v_mfma_f32_16x16x32_bf16 v[88:91], v[162:165], v[206:209], v[88:91]
	v_mfma_f32_16x16x32_bf16 v[84:87], v[148:151], v[214:217], v[84:87]
	v_mfma_f32_16x16x32_bf16 v[80:83], v[162:165], v[214:217], v[80:83]
	v_mfma_f32_16x16x32_bf16 v[108:111], v[166:169], v[182:185], v[108:111]
	v_mfma_f32_16x16x32_bf16 v[104:107], v[174:177], v[182:185], v[104:107]
	v_mfma_f32_16x16x32_bf16 v[100:103], v[166:169], v[190:193], v[100:103]
	v_mfma_f32_16x16x32_bf16 v[96:99], v[174:177], v[190:193], v[96:99]
	v_mfma_f32_16x16x32_bf16 v[76:79], v[166:169], v[198:201], v[76:79]
	v_mfma_f32_16x16x32_bf16 v[72:75], v[174:177], v[198:201], v[72:75]
	v_mfma_f32_16x16x32_bf16 v[68:71], v[166:169], v[210:213], v[68:71]
	v_mfma_f32_16x16x32_bf16 v[64:67], v[174:177], v[210:213], v[64:67]
	v_mfma_f32_16x16x32_bf16 v[108:111], v[170:173], v[186:189], v[108:111]
	v_mfma_f32_16x16x32_bf16 v[104:107], v[178:181], v[186:189], v[104:107]
	v_mfma_f32_16x16x32_bf16 v[100:103], v[170:173], v[194:197], v[100:103]
	v_mfma_f32_16x16x32_bf16 v[96:99], v[178:181], v[194:197], v[96:99]
	v_mfma_f32_16x16x32_bf16 v[76:79], v[170:173], v[206:209], v[76:79]
	v_mfma_f32_16x16x32_bf16 v[72:75], v[178:181], v[206:209], v[72:75]
	v_mfma_f32_16x16x32_bf16 v[68:71], v[170:173], v[214:217], v[68:71]
	v_mfma_f32_16x16x32_bf16 v[64:67], v[178:181], v[214:217], v[64:67]
	s_barrier
	ds_read_b128 v[182:185], v157 offset:16384
	ds_read_b128 v[186:189], v157 offset:17408
	ds_read_b128 v[190:193], v157 offset:18432
	ds_read_b128 v[194:197], v157 offset:19456
	ds_read_b128 v[198:201], v157 offset:20480
	ds_read_b128 v[206:209], v157 offset:21504
	ds_read_b128 v[210:213], v157 offset:22528
	ds_read_b128 v[214:217], v157 offset:23552
	s_add_i32 s22, s50, s39
	s_mov_b32 m0, s22
	v_lshl_add_u64 v[202:203], s[26:27], 0, v[130:131]
	global_load_lds_dwordx4 v[202:203], off
	s_add_i32 m0, s22, 0x2000
	s_add_u32 s22, s26, 0x160000
	v_lshl_add_u64 v[218:219], s[26:27], 0, v[134:135]
	s_addc_u32 s23, s27, 0
	s_add_i32 s59, s51, s39
	global_load_lds_dwordx4 v[218:219], off
	v_lshl_add_u64 v[220:221], s[22:23], 0, v[130:131]
	s_mov_b32 m0, s59
	v_lshl_add_u64 v[222:223], s[28:29], 0, v[132:133]
	global_load_lds_dwordx4 v[220:221], off
	v_lshl_add_u64 v[220:221], s[22:23], 0, v[134:135]
	s_add_i32 m0, s59, 0x2000
	s_nop 0
	global_load_lds_dwordx4 v[220:221], off
	v_lshl_add_u64 v[220:221], s[28:29], 0, v[128:129]
	s_mov_b32 m0, s40
	s_nop 0
	global_load_lds_dwordx4 v[220:221], off
	s_mov_b32 m0, s41
	s_nop 0
	global_load_lds_dwordx4 v[222:223], off
	s_waitcnt vmcnt(8)
	s_waitcnt lgkmcnt(0)
	s_barrier
; #define PG8_STAGE(bufoff, gbase, voff) do { _Pragma("unroll") for (int _i = 0; _i < 2; ++_i) \
;         __builtin_amdgcn_global_load_lds((const unsigned*)((const char*)(gbase) + (voff)[_i]), (PG8_LAS unsigned*)(lds + (bufoff) + ldsw + _i * 8192), 16, 0, 0); } while (0)
; #define PG8_LDA(dst, b, h) do { _Pragma("unroll") for (int m = 0; m < 4; ++m) _Pragma("unroll") for (int k = 0; k < 2; ++k) dst[m][k] = *(const PG8_LAS bf16x8*)(lds + PG8_SA(b, h) + aoff + m * 2048 + k * 1024); } while (0)
; #define PG8_LDB(dst, b, h) do { _Pragma("unroll") for (int n = 0; n < 2; ++n) _Pragma("unroll") for (int k = 0; k < 2; ++k) dst[n][k] = *(const PG8_LAS bf16x8*)(lds + PG8_SB(b, h) + boff + n * 2048 + k * 1024); } while (0)
; #define PG8_MMA(ai, bj, At, Bt) do { __builtin_amdgcn_s_setprio(1); _Pragma("unroll") for (int m = 0; m < 4; ++m) _Pragma("unroll") for (int n = 0; n < 2; ++n) _Pragma("unroll") for (int k = 0; k < 2; ++k) \
;         acc[ai][bj][m][n] = __builtin_amdgcn_mfma_f32_16x16x32_bf16(Bt[n][k], At[m][k], acc[ai][bj][m][n], 0, 0, 0); __builtin_amdgcn_s_setprio(0); } while (0)
; #define PG8_WAIT_V(n) asm volatile("s_waitcnt vmcnt(" #n ")" ::: "memory")
; #define PG8_WAIT_L(n) asm volatile("s_waitcnt lgkmcnt(" #n ")" ::: "memory")
; #define PG8_BAR __builtin_amdgcn_s_barrier()
; #define PG8_SCHED __builtin_amdgcn_sched_barrier(0)
; template <class Epi, class Sched, bool ALIGN_EPI = false, bool SP2 = false>
; __device__ __forceinline__ void gemm_phase(PG8_LAS unsigned char* lds, const Gemm g, const Sched& S, const Epi& E, const int wv0) {
;     ...
;             PG8_WAIT_V(8); PG8_WAIT_L(0); PG8_BAR; PG8_MMA(1, 0, At, B0); PG8_MMA(1, 1, At, B1); PG8_BAR; PG8_SCHED;
;             PG8_LDB(B0, 1, 0); PG8_LDB(B1, 1, 1); PG8_SCHED; PG8_LDA(At, 1, 0); PG8_STAGE(PG8_SA(0, 1), a2 + hstepA, voffA);
;             PG8_WAIT_V(8); PG8_WAIT_L(0); PG8_BAR; PG8_MMA(0, 0, At, B0); PG8_MMA(0, 1, At, B1); PG8_BAR; PG8_SCHED;
	v_mfma_f32_16x16x32_bf16 v[60:63], v[144:147], v[182:185], v[60:63]
	v_mfma_f32_16x16x32_bf16 v[56:59], v[158:161], v[182:185], v[56:59]
	v_mfma_f32_16x16x32_bf16 v[52:55], v[144:147], v[190:193], v[52:55]
	v_mfma_f32_16x16x32_bf16 v[48:51], v[158:161], v[190:193], v[48:51]
	v_mfma_f32_16x16x32_bf16 v[28:31], v[144:147], v[198:201], v[28:31]
	v_mfma_f32_16x16x32_bf16 v[24:27], v[158:161], v[198:201], v[24:27]
	v_mfma_f32_16x16x32_bf16 v[20:23], v[144:147], v[210:213], v[20:23]
	v_mfma_f32_16x16x32_bf16 v[16:19], v[158:161], v[210:213], v[16:19]
	v_mfma_f32_16x16x32_bf16 v[60:63], v[148:151], v[186:189], v[60:63]
	v_mfma_f32_16x16x32_bf16 v[56:59], v[162:165], v[186:189], v[56:59]
	v_mfma_f32_16x16x32_bf16 v[52:55], v[148:151], v[194:197], v[52:55]
	v_mfma_f32_16x16x32_bf16 v[48:51], v[162:165], v[194:197], v[48:51]
	v_mfma_f32_16x16x32_bf16 v[28:31], v[148:151], v[206:209], v[28:31]
	v_mfma_f32_16x16x32_bf16 v[24:27], v[162:165], v[206:209], v[24:27]
	v_mfma_f32_16x16x32_bf16 v[20:23], v[148:151], v[214:217], v[20:23]
	v_mfma_f32_16x16x32_bf16 v[16:19], v[162:165], v[214:217], v[16:19]
	v_mfma_f32_16x16x32_bf16 v[44:47], v[166:169], v[182:185], v[44:47]
	v_mfma_f32_16x16x32_bf16 v[40:43], v[174:177], v[182:185], v[40:43]
	v_mfma_f32_16x16x32_bf16 v[36:39], v[166:169], v[190:193], v[36:39]
	v_mfma_f32_16x16x32_bf16 v[32:35], v[174:177], v[190:193], v[32:35]
	v_mfma_f32_16x16x32_bf16 v[12:15], v[166:169], v[198:201], v[12:15]
	v_mfma_f32_16x16x32_bf16 v[8:11], v[174:177], v[198:201], v[8:11]
	v_mfma_f32_16x16x32_bf16 v[4:7], v[166:169], v[210:213], v[4:7]
	v_mfma_f32_16x16x32_bf16 v[0:3], v[174:177], v[210:213], v[0:3]
	v_mfma_f32_16x16x32_bf16 v[44:47], v[170:173], v[186:189], v[44:47]
	v_mfma_f32_16x16x32_bf16 v[40:43], v[178:181], v[186:189], v[40:43]
	v_mfma_f32_16x16x32_bf16 v[36:39], v[170:173], v[194:197], v[36:39]
	v_mfma_f32_16x16x32_bf16 v[32:35], v[178:181], v[194:197], v[32:35]
	v_mfma_f32_16x16x32_bf16 v[12:15], v[170:173], v[206:209], v[12:15]
	v_mfma_f32_16x16x32_bf16 v[8:11], v[178:181], v[206:209], v[8:11]
	v_mfma_f32_16x16x32_bf16 v[4:7], v[170:173], v[214:217], v[4:7]
	v_mfma_f32_16x16x32_bf16 v[0:3], v[178:181], v[214:217], v[0:3]
	s_barrier
	s_add_i32 s59, 0, 0x18000
	s_add_i32 s60, 0, 0x1c000
	v_add_u32_e32 v162, s59, v153
	v_add_u32_e32 v178, s60, v153
	ds_read_b128 v[144:147], v162
	ds_read_b128 v[148:151], v162 offset:1024
	ds_read_b128 v[158:161], v162 offset:2048
	ds_read_b128 v[162:165], v162 offset:3072
	ds_read_b128 v[166:169], v178
	ds_read_b128 v[170:173], v178 offset:1024
	ds_read_b128 v[174:177], v178 offset:2048
	ds_read_b128 v[178:181], v178 offset:3072
	s_add_u32 s22, s28, 0x160000
	s_addc_u32 s23, s29, 0
	s_mov_b32 m0, s44
	v_lshl_add_u64 v[224:225], s[22:23], 0, v[128:129]
	ds_read_b128 v[182:185], v157 offset:32768
	ds_read_b128 v[186:189], v157 offset:33792
	ds_read_b128 v[190:193], v157 offset:34816
	ds_read_b128 v[194:197], v157 offset:35840
	ds_read_b128 v[198:201], v157 offset:36864
	ds_read_b128 v[206:209], v157 offset:37888
	ds_read_b128 v[210:213], v157 offset:38912
	ds_read_b128 v[214:217], v157 offset:39936
	global_load_lds_dwordx4 v[224:225], off
	v_lshl_add_u64 v[224:225], s[22:23], 0, v[132:133]
	s_mov_b32 m0, s45
	s_nop 0
	global_load_lds_dwordx4 v[224:225], off
	s_waitcnt vmcnt(8)
	s_waitcnt lgkmcnt(0)
	s_barrier
	v_mfma_f32_16x16x32_bf16 v[124:127], v[144:147], v[182:185], v[124:127]
	v_mfma_f32_16x16x32_bf16 v[120:123], v[158:161], v[182:185], v[120:123]
	v_mfma_f32_16x16x32_bf16 v[116:119], v[144:147], v[190:193], v[116:119]
	v_mfma_f32_16x16x32_bf16 v[112:115], v[158:161], v[190:193], v[112:115]
	v_mfma_f32_16x16x32_bf16 v[92:95], v[144:147], v[198:201], v[92:95]
	v_mfma_f32_16x16x32_bf16 v[88:91], v[158:161], v[198:201], v[88:91]
	v_mfma_f32_16x16x32_bf16 v[84:87], v[144:147], v[210:213], v[84:87]
	v_mfma_f32_16x16x32_bf16 v[80:83], v[158:161], v[210:213], v[80:83]
	v_mfma_f32_16x16x32_bf16 v[124:127], v[148:151], v[186:189], v[124:127]
	v_mfma_f32_16x16x32_bf16 v[120:123], v[162:165], v[186:189], v[120:123]
	v_mfma_f32_16x16x32_bf16 v[116:119], v[148:151], v[194:197], v[116:119]
	v_mfma_f32_16x16x32_bf16 v[112:115], v[162:165], v[194:197], v[112:115]
	v_mfma_f32_16x16x32_bf16 v[92:95], v[148:151], v[206:209], v[92:95]
	v_mfma_f32_16x16x32_bf16 v[88:91], v[162:165], v[206:209], v[88:91]
	v_mfma_f32_16x16x32_bf16 v[84:87], v[148:151], v[214:217], v[84:87]
	v_mfma_f32_16x16x32_bf16 v[80:83], v[162:165], v[214:217], v[80:83]
	v_mfma_f32_16x16x32_bf16 v[108:111], v[166:169], v[182:185], v[108:111]
	v_mfma_f32_16x16x32_bf16 v[104:107], v[174:177], v[182:185], v[104:107]
	v_mfma_f32_16x16x32_bf16 v[100:103], v[166:169], v[190:193], v[100:103]
	v_mfma_f32_16x16x32_bf16 v[96:99], v[174:177], v[190:193], v[96:99]
	v_mfma_f32_16x16x32_bf16 v[76:79], v[166:169], v[198:201], v[76:79]
	v_mfma_f32_16x16x32_bf16 v[72:75], v[174:177], v[198:201], v[72:75]
	v_mfma_f32_16x16x32_bf16 v[68:71], v[166:169], v[210:213], v[68:71]
	v_mfma_f32_16x16x32_bf16 v[64:67], v[174:177], v[210:213], v[64:67]
	v_mfma_f32_16x16x32_bf16 v[108:111], v[170:173], v[186:189], v[108:111]
	v_mfma_f32_16x16x32_bf16 v[104:107], v[178:181], v[186:189], v[104:107]
	v_mfma_f32_16x16x32_bf16 v[100:103], v[170:173], v[194:197], v[100:103]
	v_mfma_f32_16x16x32_bf16 v[96:99], v[178:181], v[194:197], v[96:99]
	v_mfma_f32_16x16x32_bf16 v[76:79], v[170:173], v[206:209], v[76:79]
	v_mfma_f32_16x16x32_bf16 v[72:75], v[178:181], v[206:209], v[72:75]
	v_mfma_f32_16x16x32_bf16 v[68:71], v[170:173], v[214:217], v[68:71]
	v_mfma_f32_16x16x32_bf16 v[64:67], v[178:181], v[214:217], v[64:67]
	s_barrier
; #define PG8_STAGE(bufoff, gbase, voff) do { _Pragma("unroll") for (int _i = 0; _i < 2; ++_i) \
;         __builtin_amdgcn_global_load_lds((const unsigned*)((const char*)(gbase) + (voff)[_i]), (PG8_LAS unsigned*)(lds + (bufoff) + ldsw + _i * 8192), 16, 0, 0); } while (0)
; #define PG8_LDA(dst, b, h) do { _Pragma("unroll") for (int m = 0; m < 4; ++m) _Pragma("unroll") for (int k = 0; k < 2; ++k) dst[m][k] = *(const PG8_LAS bf16x8*)(lds + PG8_SA(b, h) + aoff + m * 2048 + k * 1024); } while (0)
; #define PG8_MMA(ai, bj, At, Bt) do { __builtin_amdgcn_s_setprio(1); _Pragma("unroll") for (int m = 0; m < 4; ++m) _Pragma("unroll") for (int n = 0; n < 2; ++n) _Pragma("unroll") for (int k = 0; k < 2; ++k) \
;         acc[ai][bj][m][n] = __builtin_amdgcn_mfma_f32_16x16x32_bf16(Bt[n][k], At[m][k], acc[ai][bj][m][n], 0, 0, 0); __builtin_amdgcn_s_setprio(0); } while (0)
; #define PG8_WAIT_V(n) asm volatile("s_waitcnt vmcnt(" #n ")" ::: "memory")
; #define PG8_WAIT_L(n) asm volatile("s_waitcnt lgkmcnt(" #n ")" ::: "memory")
; #define PG8_BAR __builtin_amdgcn_s_barrier()
; #define PG8_SCHED __builtin_amdgcn_sched_barrier(0)
; template <class Epi, class Sched, bool ALIGN_EPI = false, bool SP2 = false>
; __device__ __forceinline__ void gemm_phase(PG8_LAS unsigned char* lds, const Gemm g, const Sched& S, const Epi& E, const int wv0) {
;     ...
;             PG8_LDA(At, 1, 1); PG8_STAGE(PG8_SB(1, 0), b3, voffB); PG8_STAGE(PG8_SB(1, 1), b3 + hstepB, voffB); PG8_STAGE(PG8_SA(1, 0), a3, voffA);
;             PG8_WAIT_V(8); PG8_WAIT_L(0); PG8_BAR; PG8_MMA(1, 0, At, B0); PG8_MMA(1, 1, At, B1); PG8_BAR; PG8_SCHED;
;     ...
;         if constexpr (ALIGN_EPI) { if (wr == 0) PG8_BAR; }
	s_add_i32 s22, s59, s39
	v_lshl_add_u64 v[202:203], v[202:203], 0, s[6:7]
	s_mov_b32 m0, s22
	ds_read_b128 v[182:185], v157 offset:49152
	ds_read_b128 v[186:189], v157 offset:50176
	ds_read_b128 v[190:193], v157 offset:51200
	ds_read_b128 v[194:197], v157 offset:52224
	ds_read_b128 v[198:201], v157 offset:53248
	ds_read_b128 v[206:209], v157 offset:54272
	ds_read_b128 v[210:213], v157 offset:55296
	ds_read_b128 v[214:217], v157 offset:56320
	global_load_lds_dwordx4 v[202:203], off
	s_add_i32 m0, s22, 0x2000
	s_add_u32 s22, s26, 0x160080
	v_lshl_add_u64 v[202:203], v[218:219], 0, s[6:7]
	s_addc_u32 s23, s27, 0
	s_add_i32 s26, s60, s39
	global_load_lds_dwordx4 v[202:203], off
	v_lshl_add_u64 v[202:203], s[22:23], 0, v[130:131]
	s_mov_b32 m0, s26
	s_nop 0
	global_load_lds_dwordx4 v[202:203], off
	v_lshl_add_u64 v[202:203], s[22:23], 0, v[134:135]
	s_add_i32 m0, s26, 0x2000
	s_nop 0
	global_load_lds_dwordx4 v[202:203], off
	v_lshl_add_u64 v[202:203], v[220:221], 0, s[6:7]
	s_mov_b32 m0, s47
	s_nop 0
	global_load_lds_dwordx4 v[202:203], off
	v_lshl_add_u64 v[202:203], v[222:223], 0, s[6:7]
	s_mov_b32 m0, s48
	s_nop 0
	global_load_lds_dwordx4 v[202:203], off
	s_waitcnt vmcnt(8)
	s_waitcnt lgkmcnt(0)
	s_barrier
	v_mfma_f32_16x16x32_bf16 v[60:63], v[144:147], v[182:185], v[60:63]
	v_mfma_f32_16x16x32_bf16 v[56:59], v[158:161], v[182:185], v[56:59]
	v_mfma_f32_16x16x32_bf16 v[52:55], v[144:147], v[190:193], v[52:55]
	v_mfma_f32_16x16x32_bf16 v[48:51], v[158:161], v[190:193], v[48:51]
	v_mfma_f32_16x16x32_bf16 v[28:31], v[144:147], v[198:201], v[28:31]
	v_mfma_f32_16x16x32_bf16 v[24:27], v[158:161], v[198:201], v[24:27]
	v_mfma_f32_16x16x32_bf16 v[20:23], v[144:147], v[210:213], v[20:23]
	v_mfma_f32_16x16x32_bf16 v[16:19], v[158:161], v[210:213], v[16:19]
	v_mfma_f32_16x16x32_bf16 v[60:63], v[148:151], v[186:189], v[60:63]
	v_mfma_f32_16x16x32_bf16 v[56:59], v[162:165], v[186:189], v[56:59]
	v_mfma_f32_16x16x32_bf16 v[52:55], v[148:151], v[194:197], v[52:55]
	v_mfma_f32_16x16x32_bf16 v[48:51], v[162:165], v[194:197], v[48:51]
	v_mfma_f32_16x16x32_bf16 v[28:31], v[148:151], v[206:209], v[28:31]
	v_mfma_f32_16x16x32_bf16 v[24:27], v[162:165], v[206:209], v[24:27]
	v_mfma_f32_16x16x32_bf16 v[20:23], v[148:151], v[214:217], v[20:23]
	v_mfma_f32_16x16x32_bf16 v[16:19], v[162:165], v[214:217], v[16:19]
	v_mfma_f32_16x16x32_bf16 v[44:47], v[166:169], v[182:185], v[44:47]
	v_mfma_f32_16x16x32_bf16 v[40:43], v[174:177], v[182:185], v[40:43]
	v_mfma_f32_16x16x32_bf16 v[36:39], v[166:169], v[190:193], v[36:39]
	v_mfma_f32_16x16x32_bf16 v[32:35], v[174:177], v[190:193], v[32:35]
	v_mfma_f32_16x16x32_bf16 v[12:15], v[166:169], v[198:201], v[12:15]
	v_mfma_f32_16x16x32_bf16 v[8:11], v[174:177], v[198:201], v[8:11]
	v_mfma_f32_16x16x32_bf16 v[4:7], v[166:169], v[210:213], v[4:7]
	v_mfma_f32_16x16x32_bf16 v[0:3], v[174:177], v[210:213], v[0:3]
	v_mfma_f32_16x16x32_bf16 v[44:47], v[170:173], v[186:189], v[44:47]
	v_mfma_f32_16x16x32_bf16 v[40:43], v[178:181], v[186:189], v[40:43]
	v_mfma_f32_16x16x32_bf16 v[36:39], v[170:173], v[194:197], v[36:39]
	v_mfma_f32_16x16x32_bf16 v[32:35], v[178:181], v[194:197], v[32:35]
	v_mfma_f32_16x16x32_bf16 v[12:15], v[170:173], v[206:209], v[12:15]
	v_mfma_f32_16x16x32_bf16 v[8:11], v[178:181], v[206:209], v[8:11]
	v_mfma_f32_16x16x32_bf16 v[4:7], v[170:173], v[214:217], v[4:7]
	v_mfma_f32_16x16x32_bf16 v[0:3], v[178:181], v[214:217], v[0:3]
	s_barrier
	s_add_i32 s58, s58, 2
	s_add_u32 s56, s56, 0x100
	s_addc_u32 s57, s57, 0
	s_cmpk_gt_u32 s58, 0x55
	s_mov_b64 s[22:23], s[24:25]
	s_cbranch_scc0 .LBB0_867
	s_and_b64 vcc, exec, s[8:9]
	s_cbranch_vccz .LBB0_870
	s_barrier

; #define PG8_STAGE(bufoff, gbase, voff) do { _Pragma("unroll") for (int _i = 0; _i < 2; ++_i) \
;         __builtin_amdgcn_global_load_lds((const unsigned*)((const char*)(gbase) + (voff)[_i]), (PG8_LAS unsigned*)(lds + (bufoff) + ldsw + _i * 8192), 16, 0, 0); } while (0)
; #define PG8_LDA(dst, b, h) do { _Pragma("unroll") for (int m = 0; m < 4; ++m) _Pragma("unroll") for (int k = 0; k < 2; ++k) dst[m][k] = *(const PG8_LAS bf16x8*)(lds + PG8_SA(b, h) + aoff + m * 2048 + k * 1024); } while (0)
; #define PG8_LDB(dst, b, h) do { _Pragma("unroll") for (int n = 0; n < 2; ++n) _Pragma("unroll") for (int k = 0; k < 2; ++k) dst[n][k] = *(const PG8_LAS bf16x8*)(lds + PG8_SB(b, h) + boff + n * 2048 + k * 1024); } while (0)
; #define PG8_MMA(ai, bj, At, Bt) do { __builtin_amdgcn_s_setprio(1); _Pragma("unroll") for (int m = 0; m < 4; ++m) _Pragma("unroll") for (int n = 0; n < 2; ++n) _Pragma("unroll") for (int k = 0; k < 2; ++k) \
;         acc[ai][bj][m][n] = __builtin_amdgcn_mfma_f32_16x16x32_bf16(Bt[n][k], At[m][k], acc[ai][bj][m][n], 0, 0, 0); __builtin_amdgcn_s_setprio(0); } while (0)
; #define PG8_WAIT_V(n) asm volatile("s_waitcnt vmcnt(" #n ")" ::: "memory")
; #define PG8_WAIT_L(n) asm volatile("s_waitcnt lgkmcnt(" #n ")" ::: "memory")
; #define PG8_BAR __builtin_amdgcn_s_barrier()
; template <class Epi, class Sched, bool ALIGN_EPI = false, bool SP2 = false>
; __device__ __forceinline__ void gemm_phase(PG8_LAS unsigned char* lds, const Gemm g, const Sched& S, const Epi& E, const int wv0) {
;     ...
;             const bool last = (t == nt - 2);
;             const char* a1 = cA + (size_t)(t + 1) * kstep;
;             const char* a2 = last ? nA : cA + (size_t)(t + 2) * kstep; const char* b2 = last ? nB : cB + (size_t)(t + 2) * kstep;
;             const char* a3 = a2 + kstep; const char* b3 = b2 + kstep;
;             if constexpr (SP2) {
;             PG8_LDB(B0, 0, 0); PG8_LDB(B1, 0, 1); PG8_SCHED; PG8_LDA(At, 0, 0); PG8_STAGE(PG8_SA(1, 1), a1 + hstepA, voffA);
;             PG8_WAIT_V(8); PG8_WAIT_L(0); PG8_BAR; PG8_MMA(0, 0, At, B0); PG8_MMA(0, 1, At, B1); PG8_BAR; PG8_SCHED;
;             PG8_LDA(At, 0, 1); PG8_STAGE(PG8_SB(0, 0), b2, voffB); PG8_STAGE(PG8_SB(0, 1), b2 + hstepB, voffB); PG8_STAGE(PG8_SA(0, 0), a2, voffA);
;             PG8_WAIT_V(8); PG8_WAIT_L(0); PG8_BAR; PG8_MMA(1, 0, At, B0); PG8_MMA(1, 1, At, B1); PG8_BAR; PG8_SCHED;
.LBB0_1608:
	ds_read_b128 v[144:147], v155
	ds_read_b128 v[148:151], v155 offset:1024
	ds_read_b128 v[158:161], v155 offset:2048
	ds_read_b128 v[162:165], v155 offset:3072
	ds_read_b128 v[166:169], v156
	ds_read_b128 v[170:173], v156 offset:1024
	ds_read_b128 v[174:177], v156 offset:2048
	ds_read_b128 v[178:181], v156 offset:3072
	s_add_u32 s30, s28, 0xfff80080
	s_addc_u32 s31, s29, -1
	s_cmp_eq_u32 s56, 28
	s_cselect_b32 s35, s23, s31
	s_cselect_b32 s34, s22, s30
	s_cselect_b32 s31, s25, s21
	s_cselect_b32 s30, s24, s19
	v_lshl_add_u64 v[202:203], s[28:29], 0, v[138:139]
	s_add_i32 m0, s27, 0xc000
	ds_read_b128 v[182:185], v157
	ds_read_b128 v[186:189], v157 offset:1024
	ds_read_b128 v[190:193], v157 offset:2048
	ds_read_b128 v[194:197], v157 offset:3072
	ds_read_b128 v[198:201], v157 offset:4096
	ds_read_b128 v[206:209], v157 offset:5120
	ds_read_b128 v[210:213], v157 offset:6144
	ds_read_b128 v[214:217], v157 offset:7168
	global_load_lds_dwordx4 v[202:203], off
	v_lshl_add_u64 v[202:203], s[28:29], 0, v[136:137]
	s_add_i32 m0, s27, 0xe000
	s_nop 0
	global_load_lds_dwordx4 v[202:203], off
	s_waitcnt vmcnt(8)
	s_waitcnt lgkmcnt(0)
	s_barrier
	v_mfma_f32_16x16x32_bf16 v[124:127], v[144:147], v[182:185], v[124:127]
	v_mfma_f32_16x16x32_bf16 v[120:123], v[158:161], v[182:185], v[120:123]
	v_mfma_f32_16x16x32_bf16 v[116:119], v[144:147], v[190:193], v[116:119]
	v_mfma_f32_16x16x32_bf16 v[112:115], v[158:161], v[190:193], v[112:115]
	v_mfma_f32_16x16x32_bf16 v[92:95], v[144:147], v[198:201], v[92:95]
	v_mfma_f32_16x16x32_bf16 v[88:91], v[158:161], v[198:201], v[88:91]
	v_mfma_f32_16x16x32_bf16 v[84:87], v[144:147], v[210:213], v[84:87]
	v_mfma_f32_16x16x32_bf16 v[80:83], v[158:161], v[210:213], v[80:83]
	v_mfma_f32_16x16x32_bf16 v[124:127], v[148:151], v[186:189], v[124:127]
	v_mfma_f32_16x16x32_bf16 v[120:123], v[162:165], v[186:189], v[120:123]
	v_mfma_f32_16x16x32_bf16 v[116:119], v[148:151], v[194:197], v[116:119]
	v_mfma_f32_16x16x32_bf16 v[112:115], v[162:165], v[194:197], v[112:115]
	v_mfma_f32_16x16x32_bf16 v[92:95], v[148:151], v[206:209], v[92:95]
	v_mfma_f32_16x16x32_bf16 v[88:91], v[162:165], v[206:209], v[88:91]
	v_mfma_f32_16x16x32_bf16 v[84:87], v[148:151], v[214:217], v[84:87]
	v_mfma_f32_16x16x32_bf16 v[80:83], v[162:165], v[214:217], v[80:83]
	v_mfma_f32_16x16x32_bf16 v[108:111], v[166:169], v[182:185], v[108:111]
	v_mfma_f32_16x16x32_bf16 v[104:107], v[174:177], v[182:185], v[104:107]
	v_mfma_f32_16x16x32_bf16 v[100:103], v[166:169], v[190:193], v[100:103]
	v_mfma_f32_16x16x32_bf16 v[96:99], v[174:177], v[190:193], v[96:99]
	v_mfma_f32_16x16x32_bf16 v[76:79], v[166:169], v[198:201], v[76:79]
	v_mfma_f32_16x16x32_bf16 v[72:75], v[174:177], v[198:201], v[72:75]
	v_mfma_f32_16x16x32_bf16 v[68:71], v[166:169], v[210:213], v[68:71]
	v_mfma_f32_16x16x32_bf16 v[64:67], v[174:177], v[210:213], v[64:67]
	v_mfma_f32_16x16x32_bf16 v[108:111], v[170:173], v[186:189], v[108:111]
	v_mfma_f32_16x16x32_bf16 v[104:107], v[178:181], v[186:189], v[104:107]
	v_mfma_f32_16x16x32_bf16 v[100:103], v[170:173], v[194:197], v[100:103]
	v_mfma_f32_16x16x32_bf16 v[96:99], v[178:181], v[194:197], v[96:99]
	v_mfma_f32_16x16x32_bf16 v[76:79], v[170:173], v[206:209], v[76:79]
	v_mfma_f32_16x16x32_bf16 v[72:75], v[178:181], v[206:209], v[72:75]
	v_mfma_f32_16x16x32_bf16 v[68:71], v[170:173], v[214:217], v[68:71]
	v_mfma_f32_16x16x32_bf16 v[64:67], v[178:181], v[214:217], v[64:67]
	s_barrier
	ds_read_b128 v[182:185], v157 offset:16384
	ds_read_b128 v[186:189], v157 offset:17408
	ds_read_b128 v[190:193], v157 offset:18432
	ds_read_b128 v[194:197], v157 offset:19456
	ds_read_b128 v[198:201], v157 offset:20480
	ds_read_b128 v[206:209], v157 offset:21504
	ds_read_b128 v[210:213], v157 offset:22528
	ds_read_b128 v[214:217], v157 offset:23552
	s_add_i32 s57, s53, s45
	s_mov_b32 m0, s57
	v_lshl_add_u64 v[202:203], s[30:31], 0, v[130:131]
	global_load_lds_dwordx4 v[202:203], off
	s_add_i32 m0, s57, 0x2000
	s_add_u32 s58, s30, 0x80000
	v_lshl_add_u64 v[218:219], s[30:31], 0, v[134:135]
	s_addc_u32 s59, s31, 0
	s_add_i32 s57, s54, s45
	global_load_lds_dwordx4 v[218:219], off
	v_lshl_add_u64 v[220:221], s[58:59], 0, v[130:131]
	s_mov_b32 m0, s57
	v_lshl_add_u64 v[222:223], s[34:35], 0, v[132:133]
	global_load_lds_dwordx4 v[220:221], off
	v_lshl_add_u64 v[220:221], s[58:59], 0, v[134:135]
	s_add_i32 m0, s57, 0x2000
	s_nop 0
	global_load_lds_dwordx4 v[220:221], off
	v_lshl_add_u64 v[220:221], s[34:35], 0, v[128:129]
	s_mov_b32 m0, s27
	s_nop 0
	global_load_lds_dwordx4 v[220:221], off
	s_mov_b32 m0, s46
	s_nop 0
	global_load_lds_dwordx4 v[222:223], off
	s_waitcnt vmcnt(8)
	s_waitcnt lgkmcnt(0)
	s_barrier
; #define PG8_STAGE(bufoff, gbase, voff) do { _Pragma("unroll") for (int _i = 0; _i < 2; ++_i) \
;         __builtin_amdgcn_global_load_lds((const unsigned*)((const char*)(gbase) + (voff)[_i]), (PG8_LAS unsigned*)(lds + (bufoff) + ldsw + _i * 8192), 16, 0, 0); } while (0)
; #define PG8_LDA(dst, b, h) do { _Pragma("unroll") for (int m = 0; m < 4; ++m) _Pragma("unroll") for (int k = 0; k < 2; ++k) dst[m][k] = *(const PG8_LAS bf16x8*)(lds + PG8_SA(b, h) + aoff + m * 2048 + k * 1024); } while (0)
; #define PG8_LDB(dst, b, h) do { _Pragma("unroll") for (int n = 0; n < 2; ++n) _Pragma("unroll") for (int k = 0; k < 2; ++k) dst[n][k] = *(const PG8_LAS bf16x8*)(lds + PG8_SB(b, h) + boff + n * 2048 + k * 1024); } while (0)
; #define PG8_MMA(ai, bj, At, Bt) do { __builtin_amdgcn_s_setprio(1); _Pragma("unroll") for (int m = 0; m < 4; ++m) _Pragma("unroll") for (int n = 0; n < 2; ++n) _Pragma("unroll") for (int k = 0; k < 2; ++k) \
;         acc[ai][bj][m][n] = __builtin_amdgcn_mfma_f32_16x16x32_bf16(Bt[n][k], At[m][k], acc[ai][bj][m][n], 0, 0, 0); __builtin_amdgcn_s_setprio(0); } while (0)
; #define PG8_WAIT_V(n) asm volatile("s_waitcnt vmcnt(" #n ")" ::: "memory")
; #define PG8_WAIT_L(n) asm volatile("s_waitcnt lgkmcnt(" #n ")" ::: "memory")
; #define PG8_BAR __builtin_amdgcn_s_barrier()
; #define PG8_SCHED __builtin_amdgcn_sched_barrier(0)
; template <class Epi, class Sched, bool ALIGN_EPI = false, bool SP2 = false>
; __device__ __forceinline__ void gemm_phase(PG8_LAS unsigned char* lds, const Gemm g, const Sched& S, const Epi& E, const int wv0) {
;     ...
;             PG8_WAIT_V(8); PG8_WAIT_L(0); PG8_BAR; PG8_MMA(1, 0, At, B0); PG8_MMA(1, 1, At, B1); PG8_BAR; PG8_SCHED;
;             PG8_LDB(B0, 1, 0); PG8_LDB(B1, 1, 1); PG8_SCHED; PG8_LDA(At, 1, 0); PG8_STAGE(PG8_SA(0, 1), a2 + hstepA, voffA);
;             PG8_WAIT_V(8); PG8_WAIT_L(0); PG8_BAR; PG8_MMA(0, 0, At, B0); PG8_MMA(0, 1, At, B1); PG8_BAR; PG8_SCHED;
	v_mfma_f32_16x16x32_bf16 v[60:63], v[144:147], v[182:185], v[60:63]
	v_mfma_f32_16x16x32_bf16 v[56:59], v[158:161], v[182:185], v[56:59]
	v_mfma_f32_16x16x32_bf16 v[52:55], v[144:147], v[190:193], v[52:55]
	v_mfma_f32_16x16x32_bf16 v[48:51], v[158:161], v[190:193], v[48:51]
	v_mfma_f32_16x16x32_bf16 v[28:31], v[144:147], v[198:201], v[28:31]
	v_mfma_f32_16x16x32_bf16 v[24:27], v[158:161], v[198:201], v[24:27]
	v_mfma_f32_16x16x32_bf16 v[20:23], v[144:147], v[210:213], v[20:23]
	v_mfma_f32_16x16x32_bf16 v[16:19], v[158:161], v[210:213], v[16:19]
	v_mfma_f32_16x16x32_bf16 v[60:63], v[148:151], v[186:189], v[60:63]
	v_mfma_f32_16x16x32_bf16 v[56:59], v[162:165], v[186:189], v[56:59]
	v_mfma_f32_16x16x32_bf16 v[52:55], v[148:151], v[194:197], v[52:55]
	v_mfma_f32_16x16x32_bf16 v[48:51], v[162:165], v[194:197], v[48:51]
	v_mfma_f32_16x16x32_bf16 v[28:31], v[148:151], v[206:209], v[28:31]
	v_mfma_f32_16x16x32_bf16 v[24:27], v[162:165], v[206:209], v[24:27]
	v_mfma_f32_16x16x32_bf16 v[20:23], v[148:151], v[214:217], v[20:23]
	v_mfma_f32_16x16x32_bf16 v[16:19], v[162:165], v[214:217], v[16:19]
	v_mfma_f32_16x16x32_bf16 v[44:47], v[166:169], v[182:185], v[44:47]
	v_mfma_f32_16x16x32_bf16 v[40:43], v[174:177], v[182:185], v[40:43]
	v_mfma_f32_16x16x32_bf16 v[36:39], v[166:169], v[190:193], v[36:39]
	v_mfma_f32_16x16x32_bf16 v[32:35], v[174:177], v[190:193], v[32:35]
	v_mfma_f32_16x16x32_bf16 v[12:15], v[166:169], v[198:201], v[12:15]
	v_mfma_f32_16x16x32_bf16 v[8:11], v[174:177], v[198:201], v[8:11]
	v_mfma_f32_16x16x32_bf16 v[4:7], v[166:169], v[210:213], v[4:7]
	v_mfma_f32_16x16x32_bf16 v[0:3], v[174:177], v[210:213], v[0:3]
	v_mfma_f32_16x16x32_bf16 v[44:47], v[170:173], v[186:189], v[44:47]
	v_mfma_f32_16x16x32_bf16 v[40:43], v[178:181], v[186:189], v[40:43]
	v_mfma_f32_16x16x32_bf16 v[36:39], v[170:173], v[194:197], v[36:39]
	v_mfma_f32_16x16x32_bf16 v[32:35], v[178:181], v[194:197], v[32:35]
	v_mfma_f32_16x16x32_bf16 v[12:15], v[170:173], v[206:209], v[12:15]
	v_mfma_f32_16x16x32_bf16 v[8:11], v[178:181], v[206:209], v[8:11]
	v_mfma_f32_16x16x32_bf16 v[4:7], v[170:173], v[214:217], v[4:7]
	v_mfma_f32_16x16x32_bf16 v[0:3], v[178:181], v[214:217], v[0:3]
	s_barrier
	s_add_i32 s57, 0, 0x18000
	s_add_i32 s58, 0, 0x1c000
	v_add_u32_e32 v162, s57, v153
	v_add_u32_e32 v178, s58, v153
	ds_read_b128 v[144:147], v162
	ds_read_b128 v[148:151], v162 offset:1024
	ds_read_b128 v[158:161], v162 offset:2048
	ds_read_b128 v[162:165], v162 offset:3072
	ds_read_b128 v[166:169], v178
	ds_read_b128 v[170:173], v178 offset:1024
	ds_read_b128 v[174:177], v178 offset:2048
	ds_read_b128 v[178:181], v178 offset:3072
	s_add_u32 s34, s34, 0x80000
	s_addc_u32 s35, s35, 0
	s_mov_b32 m0, s47
	v_lshl_add_u64 v[224:225], s[34:35], 0, v[128:129]
	ds_read_b128 v[182:185], v157 offset:32768
	ds_read_b128 v[186:189], v157 offset:33792
	ds_read_b128 v[190:193], v157 offset:34816
	ds_read_b128 v[194:197], v157 offset:35840
	ds_read_b128 v[198:201], v157 offset:36864
	ds_read_b128 v[206:209], v157 offset:37888
	ds_read_b128 v[210:213], v157 offset:38912
	ds_read_b128 v[214:217], v157 offset:39936
	global_load_lds_dwordx4 v[224:225], off
	v_lshl_add_u64 v[224:225], s[34:35], 0, v[132:133]
	s_mov_b32 m0, s48
	s_nop 0
	global_load_lds_dwordx4 v[224:225], off
	s_waitcnt vmcnt(8)
	s_waitcnt lgkmcnt(0)
	s_barrier
	v_mfma_f32_16x16x32_bf16 v[124:127], v[144:147], v[182:185], v[124:127]
	v_mfma_f32_16x16x32_bf16 v[120:123], v[158:161], v[182:185], v[120:123]
	v_mfma_f32_16x16x32_bf16 v[116:119], v[144:147], v[190:193], v[116:119]
	v_mfma_f32_16x16x32_bf16 v[112:115], v[158:161], v[190:193], v[112:115]
	v_mfma_f32_16x16x32_bf16 v[92:95], v[144:147], v[198:201], v[92:95]
	v_mfma_f32_16x16x32_bf16 v[88:91], v[158:161], v[198:201], v[88:91]
	v_mfma_f32_16x16x32_bf16 v[84:87], v[144:147], v[210:213], v[84:87]
	v_mfma_f32_16x16x32_bf16 v[80:83], v[158:161], v[210:213], v[80:83]
	v_mfma_f32_16x16x32_bf16 v[124:127], v[148:151], v[186:189], v[124:127]
	v_mfma_f32_16x16x32_bf16 v[120:123], v[162:165], v[186:189], v[120:123]
	v_mfma_f32_16x16x32_bf16 v[116:119], v[148:151], v[194:197], v[116:119]
	v_mfma_f32_16x16x32_bf16 v[112:115], v[162:165], v[194:197], v[112:115]
	v_mfma_f32_16x16x32_bf16 v[92:95], v[148:151], v[206:209], v[92:95]
	v_mfma_f32_16x16x32_bf16 v[88:91], v[162:165], v[206:209], v[88:91]
	v_mfma_f32_16x16x32_bf16 v[84:87], v[148:151], v[214:217], v[84:87]
	v_mfma_f32_16x16x32_bf16 v[80:83], v[162:165], v[214:217], v[80:83]
	v_mfma_f32_16x16x32_bf16 v[108:111], v[166:169], v[182:185], v[108:111]
	v_mfma_f32_16x16x32_bf16 v[104:107], v[174:177], v[182:185], v[104:107]
	v_mfma_f32_16x16x32_bf16 v[100:103], v[166:169], v[190:193], v[100:103]
	v_mfma_f32_16x16x32_bf16 v[96:99], v[174:177], v[190:193], v[96:99]
	v_mfma_f32_16x16x32_bf16 v[76:79], v[166:169], v[198:201], v[76:79]
	v_mfma_f32_16x16x32_bf16 v[72:75], v[174:177], v[198:201], v[72:75]
	v_mfma_f32_16x16x32_bf16 v[68:71], v[166:169], v[210:213], v[68:71]
	v_mfma_f32_16x16x32_bf16 v[64:67], v[174:177], v[210:213], v[64:67]
	v_mfma_f32_16x16x32_bf16 v[108:111], v[170:173], v[186:189], v[108:111]
	v_mfma_f32_16x16x32_bf16 v[104:107], v[178:181], v[186:189], v[104:107]
	v_mfma_f32_16x16x32_bf16 v[100:103], v[170:173], v[194:197], v[100:103]
	v_mfma_f32_16x16x32_bf16 v[96:99], v[178:181], v[194:197], v[96:99]
	v_mfma_f32_16x16x32_bf16 v[76:79], v[170:173], v[206:209], v[76:79]
	v_mfma_f32_16x16x32_bf16 v[72:75], v[178:181], v[206:209], v[72:75]
	v_mfma_f32_16x16x32_bf16 v[68:71], v[170:173], v[214:217], v[68:71]
	v_mfma_f32_16x16x32_bf16 v[64:67], v[178:181], v[214:217], v[64:67]
	s_barrier
; #define PG8_STAGE(bufoff, gbase, voff) do { _Pragma("unroll") for (int _i = 0; _i < 2; ++_i) \
;         __builtin_amdgcn_global_load_lds((const unsigned*)((const char*)(gbase) + (voff)[_i]), (PG8_LAS unsigned*)(lds + (bufoff) + ldsw + _i * 8192), 16, 0, 0); } while (0)
; #define PG8_LDA(dst, b, h) do { _Pragma("unroll") for (int m = 0; m < 4; ++m) _Pragma("unroll") for (int k = 0; k < 2; ++k) dst[m][k] = *(const PG8_LAS bf16x8*)(lds + PG8_SA(b, h) + aoff + m * 2048 + k * 1024); } while (0)
; #define PG8_MMA(ai, bj, At, Bt) do { __builtin_amdgcn_s_setprio(1); _Pragma("unroll") for (int m = 0; m < 4; ++m) _Pragma("unroll") for (int n = 0; n < 2; ++n) _Pragma("unroll") for (int k = 0; k < 2; ++k) \
;         acc[ai][bj][m][n] = __builtin_amdgcn_mfma_f32_16x16x32_bf16(Bt[n][k], At[m][k], acc[ai][bj][m][n], 0, 0, 0); __builtin_amdgcn_s_setprio(0); } while (0)
; #define PG8_WAIT_V(n) asm volatile("s_waitcnt vmcnt(" #n ")" ::: "memory")
; #define PG8_WAIT_L(n) asm volatile("s_waitcnt lgkmcnt(" #n ")" ::: "memory")
; #define PG8_BAR __builtin_amdgcn_s_barrier()
; #define PG8_SCHED __builtin_amdgcn_sched_barrier(0)
; template <class Epi, class Sched, bool ALIGN_EPI = false, bool SP2 = false>
; __device__ __forceinline__ void gemm_phase(PG8_LAS unsigned char* lds, const Gemm g, const Sched& S, const Epi& E, const int wv0) {
;     ...
;             PG8_LDA(At, 1, 1); PG8_STAGE(PG8_SB(1, 0), b3, voffB); PG8_STAGE(PG8_SB(1, 1), b3 + hstepB, voffB); PG8_STAGE(PG8_SA(1, 0), a3, voffA);
;             PG8_WAIT_V(8); PG8_WAIT_L(0); PG8_BAR; PG8_MMA(1, 0, At, B0); PG8_MMA(1, 1, At, B1); PG8_BAR; PG8_SCHED;
;     ...
;         if constexpr (ALIGN_EPI) { if (wr == 0) PG8_BAR; }
	s_add_i32 s34, s57, s45
	v_lshl_add_u64 v[202:203], v[202:203], 0, s[8:9]
	s_mov_b32 m0, s34
	ds_read_b128 v[182:185], v157 offset:49152
	ds_read_b128 v[186:189], v157 offset:50176
	ds_read_b128 v[190:193], v157 offset:51200
	ds_read_b128 v[194:197], v157 offset:52224
	ds_read_b128 v[198:201], v157 offset:53248
	ds_read_b128 v[206:209], v157 offset:54272
	ds_read_b128 v[210:213], v157 offset:55296
	ds_read_b128 v[214:217], v157 offset:56320
	global_load_lds_dwordx4 v[202:203], off
	s_add_i32 m0, s34, 0x2000
	s_add_u32 s30, s30, 0x80080
	v_lshl_add_u64 v[202:203], v[218:219], 0, s[8:9]
	s_addc_u32 s31, s31, 0
	s_add_i32 s34, s58, s45
	global_load_lds_dwordx4 v[202:203], off
	v_lshl_add_u64 v[202:203], s[30:31], 0, v[130:131]
	s_mov_b32 m0, s34
	s_nop 0
	global_load_lds_dwordx4 v[202:203], off
	v_lshl_add_u64 v[202:203], s[30:31], 0, v[134:135]
	s_add_i32 m0, s34, 0x2000
	s_nop 0
	global_load_lds_dwordx4 v[202:203], off
	v_lshl_add_u64 v[202:203], v[220:221], 0, s[8:9]
	s_mov_b32 m0, s50
	s_nop 0
	global_load_lds_dwordx4 v[202:203], off
	v_lshl_add_u64 v[202:203], v[222:223], 0, s[8:9]
	s_mov_b32 m0, s51
	s_nop 0
	global_load_lds_dwordx4 v[202:203], off
	s_waitcnt vmcnt(8)
	s_waitcnt lgkmcnt(0)
	s_barrier
	v_mfma_f32_16x16x32_bf16 v[60:63], v[144:147], v[182:185], v[60:63]
	v_mfma_f32_16x16x32_bf16 v[56:59], v[158:161], v[182:185], v[56:59]
	v_mfma_f32_16x16x32_bf16 v[52:55], v[144:147], v[190:193], v[52:55]
	v_mfma_f32_16x16x32_bf16 v[48:51], v[158:161], v[190:193], v[48:51]
	v_mfma_f32_16x16x32_bf16 v[28:31], v[144:147], v[198:201], v[28:31]
	v_mfma_f32_16x16x32_bf16 v[24:27], v[158:161], v[198:201], v[24:27]
	v_mfma_f32_16x16x32_bf16 v[20:23], v[144:147], v[210:213], v[20:23]
	v_mfma_f32_16x16x32_bf16 v[16:19], v[158:161], v[210:213], v[16:19]
	v_mfma_f32_16x16x32_bf16 v[60:63], v[148:151], v[186:189], v[60:63]
	v_mfma_f32_16x16x32_bf16 v[56:59], v[162:165], v[186:189], v[56:59]
	v_mfma_f32_16x16x32_bf16 v[52:55], v[148:151], v[194:197], v[52:55]
	v_mfma_f32_16x16x32_bf16 v[48:51], v[162:165], v[194:197], v[48:51]
	v_mfma_f32_16x16x32_bf16 v[28:31], v[148:151], v[206:209], v[28:31]
	v_mfma_f32_16x16x32_bf16 v[24:27], v[162:165], v[206:209], v[24:27]
	v_mfma_f32_16x16x32_bf16 v[20:23], v[148:151], v[214:217], v[20:23]
	v_mfma_f32_16x16x32_bf16 v[16:19], v[162:165], v[214:217], v[16:19]
	v_mfma_f32_16x16x32_bf16 v[44:47], v[166:169], v[182:185], v[44:47]
	v_mfma_f32_16x16x32_bf16 v[40:43], v[174:177], v[182:185], v[40:43]
	v_mfma_f32_16x16x32_bf16 v[36:39], v[166:169], v[190:193], v[36:39]
	v_mfma_f32_16x16x32_bf16 v[32:35], v[174:177], v[190:193], v[32:35]
	v_mfma_f32_16x16x32_bf16 v[12:15], v[166:169], v[198:201], v[12:15]
	v_mfma_f32_16x16x32_bf16 v[8:11], v[174:177], v[198:201], v[8:11]
	v_mfma_f32_16x16x32_bf16 v[4:7], v[166:169], v[210:213], v[4:7]
	v_mfma_f32_16x16x32_bf16 v[0:3], v[174:177], v[210:213], v[0:3]
	v_mfma_f32_16x16x32_bf16 v[44:47], v[170:173], v[186:189], v[44:47]
	v_mfma_f32_16x16x32_bf16 v[40:43], v[178:181], v[186:189], v[40:43]
	v_mfma_f32_16x16x32_bf16 v[36:39], v[170:173], v[194:197], v[36:39]
	v_mfma_f32_16x16x32_bf16 v[32:35], v[178:181], v[194:197], v[32:35]
	v_mfma_f32_16x16x32_bf16 v[12:15], v[170:173], v[206:209], v[12:15]
	v_mfma_f32_16x16x32_bf16 v[8:11], v[178:181], v[206:209], v[8:11]
	v_mfma_f32_16x16x32_bf16 v[4:7], v[170:173], v[214:217], v[4:7]
	v_mfma_f32_16x16x32_bf16 v[0:3], v[178:181], v[214:217], v[0:3]
	s_barrier
	s_add_i32 s56, s56, 2
	s_add_u32 s19, s19, 0x100
	s_addc_u32 s21, s21, 0
	s_add_u32 s28, s28, 0x100
	s_addc_u32 s29, s29, 0
	s_cmp_gt_u32 s56, 29
	s_cbranch_scc0 .LBB0_1608
	s_and_b64 vcc, exec, s[10:11]
	s_cbranch_vccz .LBB0_1611
	s_barrier

; #define PG8_STAGE(bufoff, gbase, voff) do { _Pragma("unroll") for (int _i = 0; _i < 2; ++_i) \
;         __builtin_amdgcn_global_load_lds((const unsigned*)((const char*)(gbase) + (voff)[_i]), (PG8_LAS unsigned*)(lds + (bufoff) + ldsw + _i * 8192), 16, 0, 0); } while (0)
; #define PG8_LDA(dst, b, h) do { _Pragma("unroll") for (int m = 0; m < 4; ++m) _Pragma("unroll") for (int k = 0; k < 2; ++k) dst[m][k] = *(const PG8_LAS bf16x8*)(lds + PG8_SA(b, h) + aoff + m * 2048 + k * 1024); } while (0)
; #define PG8_LDB(dst, b, h) do { _Pragma("unroll") for (int n = 0; n < 2; ++n) _Pragma("unroll") for (int k = 0; k < 2; ++k) dst[n][k] = *(const PG8_LAS bf16x8*)(lds + PG8_SB(b, h) + boff + n * 2048 + k * 1024); } while (0)
; #define PG8_MMA(ai, bj, At, Bt) do { __builtin_amdgcn_s_setprio(1); _Pragma("unroll") for (int m = 0; m < 4; ++m) _Pragma("unroll") for (int n = 0; n < 2; ++n) _Pragma("unroll") for (int k = 0; k < 2; ++k) \
;         acc[ai][bj][m][n] = __builtin_amdgcn_mfma_f32_16x16x32_bf16(Bt[n][k], At[m][k], acc[ai][bj][m][n], 0, 0, 0); __builtin_amdgcn_s_setprio(0); } while (0)
; #define PG8_WAIT_V(n) asm volatile("s_waitcnt vmcnt(" #n ")" ::: "memory")
; #define PG8_WAIT_L(n) asm volatile("s_waitcnt lgkmcnt(" #n ")" ::: "memory")
; #define PG8_BAR __builtin_amdgcn_s_barrier()
; template <class Epi, class Sched, bool ALIGN_EPI = false, bool SP2 = false>
; __device__ __forceinline__ void gemm_phase(PG8_LAS unsigned char* lds, const Gemm g, const Sched& S, const Epi& E, const int wv0) {
;     ...
;             const bool last = (t == nt - 2);
;             const char* a1 = cA + (size_t)(t + 1) * kstep;
;             const char* a2 = last ? nA : cA + (size_t)(t + 2) * kstep; const char* b2 = last ? nB : cB + (size_t)(t + 2) * kstep;
;             const char* a3 = a2 + kstep; const char* b3 = b2 + kstep;
;             if constexpr (SP2) {
;             PG8_LDB(B0, 0, 0); PG8_LDB(B1, 0, 1); PG8_SCHED; PG8_LDA(At, 0, 0); PG8_STAGE(PG8_SA(1, 1), a1 + hstepA, voffA);
;             PG8_WAIT_V(8); PG8_WAIT_L(0); PG8_BAR; PG8_MMA(0, 0, At, B0); PG8_MMA(0, 1, At, B1); PG8_BAR; PG8_SCHED;
;             PG8_LDA(At, 0, 1); PG8_STAGE(PG8_SB(0, 0), b2, voffB); PG8_STAGE(PG8_SB(0, 1), b2 + hstepB, voffB); PG8_STAGE(PG8_SA(0, 0), a2, voffA);
;             PG8_WAIT_V(8); PG8_WAIT_L(0); PG8_BAR; PG8_MMA(1, 0, At, B0); PG8_MMA(1, 1, At, B1); PG8_BAR; PG8_SCHED;
.LBB0_1808:
	ds_read_b128 v[144:147], v153
	ds_read_b128 v[156:159], v153 offset:1024
	ds_read_b128 v[160:163], v153 offset:2048
	ds_read_b128 v[164:167], v153 offset:3072
	ds_read_b128 v[168:171], v154
	ds_read_b128 v[172:175], v154 offset:1024
	ds_read_b128 v[176:179], v154 offset:2048
	ds_read_b128 v[180:183], v154 offset:3072
	s_add_u32 s18, s16, 0x100
	s_addc_u32 s19, s17, 0
	s_cmpk_eq_i32 s48, 0x54
	s_cselect_b32 s23, s13, s19
	s_cselect_b32 s22, s12, s18
	s_cselect_b32 s21, s15, s47
	s_cselect_b32 s20, s14, s46
	v_lshl_add_u64 v[148:149], s[16:17], 0, v[138:139]
	s_add_i32 m0, s30, 0xc000
	ds_read_b128 v[184:187], v155
	ds_read_b128 v[188:191], v155 offset:1024
	ds_read_b128 v[192:195], v155 offset:2048
	ds_read_b128 v[196:199], v155 offset:3072
	ds_read_b128 v[200:203], v155 offset:4096
	ds_read_b128 v[204:207], v155 offset:5120
	ds_read_b128 v[208:211], v155 offset:6144
	ds_read_b128 v[212:215], v155 offset:7168
	global_load_lds_dwordx4 v[148:149], off
	v_lshl_add_u64 v[148:149], s[16:17], 0, v[136:137]
	s_add_i32 m0, s30, 0xe000
	s_nop 0
	global_load_lds_dwordx4 v[148:149], off
	s_waitcnt vmcnt(8)
	s_waitcnt lgkmcnt(0)
	s_barrier
	v_mfma_f32_16x16x32_bf16 v[124:127], v[144:147], v[184:187], v[124:127]
	v_mfma_f32_16x16x32_bf16 v[120:123], v[160:163], v[184:187], v[120:123]
	v_mfma_f32_16x16x32_bf16 v[116:119], v[144:147], v[192:195], v[116:119]
	v_mfma_f32_16x16x32_bf16 v[112:115], v[160:163], v[192:195], v[112:115]
	v_mfma_f32_16x16x32_bf16 v[92:95], v[144:147], v[200:203], v[92:95]
	v_mfma_f32_16x16x32_bf16 v[88:91], v[160:163], v[200:203], v[88:91]
	v_mfma_f32_16x16x32_bf16 v[84:87], v[144:147], v[208:211], v[84:87]
	v_mfma_f32_16x16x32_bf16 v[80:83], v[160:163], v[208:211], v[80:83]
	v_mfma_f32_16x16x32_bf16 v[124:127], v[156:159], v[188:191], v[124:127]
	v_mfma_f32_16x16x32_bf16 v[120:123], v[164:167], v[188:191], v[120:123]
	v_mfma_f32_16x16x32_bf16 v[116:119], v[156:159], v[196:199], v[116:119]
	v_mfma_f32_16x16x32_bf16 v[112:115], v[164:167], v[196:199], v[112:115]
	v_mfma_f32_16x16x32_bf16 v[92:95], v[156:159], v[204:207], v[92:95]
	v_mfma_f32_16x16x32_bf16 v[88:91], v[164:167], v[204:207], v[88:91]
	v_mfma_f32_16x16x32_bf16 v[84:87], v[156:159], v[212:215], v[84:87]
	v_mfma_f32_16x16x32_bf16 v[80:83], v[164:167], v[212:215], v[80:83]
	v_mfma_f32_16x16x32_bf16 v[108:111], v[168:171], v[184:187], v[108:111]
	v_mfma_f32_16x16x32_bf16 v[104:107], v[176:179], v[184:187], v[104:107]
	v_mfma_f32_16x16x32_bf16 v[100:103], v[168:171], v[192:195], v[100:103]
	v_mfma_f32_16x16x32_bf16 v[96:99], v[176:179], v[192:195], v[96:99]
	v_mfma_f32_16x16x32_bf16 v[76:79], v[168:171], v[200:203], v[76:79]
	v_mfma_f32_16x16x32_bf16 v[72:75], v[176:179], v[200:203], v[72:75]
	v_mfma_f32_16x16x32_bf16 v[68:71], v[168:171], v[208:211], v[68:71]
	v_mfma_f32_16x16x32_bf16 v[64:67], v[176:179], v[208:211], v[64:67]
	v_mfma_f32_16x16x32_bf16 v[108:111], v[172:175], v[188:191], v[108:111]
	v_mfma_f32_16x16x32_bf16 v[104:107], v[180:183], v[188:191], v[104:107]
	v_mfma_f32_16x16x32_bf16 v[100:103], v[172:175], v[196:199], v[100:103]
	v_mfma_f32_16x16x32_bf16 v[96:99], v[180:183], v[196:199], v[96:99]
	v_mfma_f32_16x16x32_bf16 v[76:79], v[172:175], v[204:207], v[76:79]
	v_mfma_f32_16x16x32_bf16 v[72:75], v[180:183], v[204:207], v[72:75]
	v_mfma_f32_16x16x32_bf16 v[68:71], v[172:175], v[212:215], v[68:71]
	v_mfma_f32_16x16x32_bf16 v[64:67], v[180:183], v[212:215], v[64:67]
	s_barrier
	ds_read_b128 v[184:187], v155 offset:16384
	ds_read_b128 v[188:191], v155 offset:17408
	ds_read_b128 v[192:195], v155 offset:18432
	ds_read_b128 v[196:199], v155 offset:19456
	ds_read_b128 v[200:203], v155 offset:20480
	ds_read_b128 v[204:207], v155 offset:21504
	ds_read_b128 v[208:211], v155 offset:22528
	ds_read_b128 v[212:215], v155 offset:23552
	s_add_i32 s16, s40, s29
	s_mov_b32 m0, s16
	v_lshl_add_u64 v[148:149], s[20:21], 0, v[130:131]
	global_load_lds_dwordx4 v[148:149], off
	s_add_i32 m0, s16, 0x2000
	s_add_u32 s16, s20, 0x160000
	v_lshl_add_u64 v[216:217], s[20:21], 0, v[134:135]
	s_addc_u32 s17, s21, 0
	s_add_i32 s49, s41, s29
	global_load_lds_dwordx4 v[216:217], off
	v_lshl_add_u64 v[218:219], s[16:17], 0, v[130:131]
	s_mov_b32 m0, s49
	v_lshl_add_u64 v[220:221], s[22:23], 0, v[132:133]
	global_load_lds_dwordx4 v[218:219], off
	v_lshl_add_u64 v[218:219], s[16:17], 0, v[134:135]
	s_add_i32 m0, s49, 0x2000
	s_nop 0
	global_load_lds_dwordx4 v[218:219], off
	v_lshl_add_u64 v[218:219], s[22:23], 0, v[128:129]
	s_mov_b32 m0, s30
	s_nop 0
	global_load_lds_dwordx4 v[218:219], off
	s_mov_b32 m0, s31
	s_nop 0
	global_load_lds_dwordx4 v[220:221], off
	s_waitcnt vmcnt(8)
	s_waitcnt lgkmcnt(0)
	s_barrier
; #define PG8_STAGE(bufoff, gbase, voff) do { _Pragma("unroll") for (int _i = 0; _i < 2; ++_i) \
;         __builtin_amdgcn_global_load_lds((const unsigned*)((const char*)(gbase) + (voff)[_i]), (PG8_LAS unsigned*)(lds + (bufoff) + ldsw + _i * 8192), 16, 0, 0); } while (0)
; #define PG8_LDA(dst, b, h) do { _Pragma("unroll") for (int m = 0; m < 4; ++m) _Pragma("unroll") for (int k = 0; k < 2; ++k) dst[m][k] = *(const PG8_LAS bf16x8*)(lds + PG8_SA(b, h) + aoff + m * 2048 + k * 1024); } while (0)
; #define PG8_LDB(dst, b, h) do { _Pragma("unroll") for (int n = 0; n < 2; ++n) _Pragma("unroll") for (int k = 0; k < 2; ++k) dst[n][k] = *(const PG8_LAS bf16x8*)(lds + PG8_SB(b, h) + boff + n * 2048 + k * 1024); } while (0)
; #define PG8_MMA(ai, bj, At, Bt) do { __builtin_amdgcn_s_setprio(1); _Pragma("unroll") for (int m = 0; m < 4; ++m) _Pragma("unroll") for (int n = 0; n < 2; ++n) _Pragma("unroll") for (int k = 0; k < 2; ++k) \
;         acc[ai][bj][m][n] = __builtin_amdgcn_mfma_f32_16x16x32_bf16(Bt[n][k], At[m][k], acc[ai][bj][m][n], 0, 0, 0); __builtin_amdgcn_s_setprio(0); } while (0)
; #define PG8_WAIT_V(n) asm volatile("s_waitcnt vmcnt(" #n ")" ::: "memory")
; #define PG8_WAIT_L(n) asm volatile("s_waitcnt lgkmcnt(" #n ")" ::: "memory")
; #define PG8_BAR __builtin_amdgcn_s_barrier()
; #define PG8_SCHED __builtin_amdgcn_sched_barrier(0)
; template <class Epi, class Sched, bool ALIGN_EPI = false, bool SP2 = false>
; __device__ __forceinline__ void gemm_phase(PG8_LAS unsigned char* lds, const Gemm g, const Sched& S, const Epi& E, const int wv0) {
;     ...
;             PG8_WAIT_V(8); PG8_WAIT_L(0); PG8_BAR; PG8_MMA(1, 0, At, B0); PG8_MMA(1, 1, At, B1); PG8_BAR; PG8_SCHED;
;             PG8_LDB(B0, 1, 0); PG8_LDB(B1, 1, 1); PG8_SCHED; PG8_LDA(At, 1, 0); PG8_STAGE(PG8_SA(0, 1), a2 + hstepA, voffA);
;             PG8_WAIT_V(8); PG8_WAIT_L(0); PG8_BAR; PG8_MMA(0, 0, At, B0); PG8_MMA(0, 1, At, B1); PG8_BAR; PG8_SCHED;
	v_mfma_f32_16x16x32_bf16 v[60:63], v[144:147], v[184:187], v[60:63]
	v_mfma_f32_16x16x32_bf16 v[56:59], v[160:163], v[184:187], v[56:59]
	v_mfma_f32_16x16x32_bf16 v[52:55], v[144:147], v[192:195], v[52:55]
	v_mfma_f32_16x16x32_bf16 v[48:51], v[160:163], v[192:195], v[48:51]
	v_mfma_f32_16x16x32_bf16 v[28:31], v[144:147], v[200:203], v[28:31]
	v_mfma_f32_16x16x32_bf16 v[24:27], v[160:163], v[200:203], v[24:27]
	v_mfma_f32_16x16x32_bf16 v[20:23], v[144:147], v[208:211], v[20:23]
	v_mfma_f32_16x16x32_bf16 v[16:19], v[160:163], v[208:211], v[16:19]
	v_mfma_f32_16x16x32_bf16 v[60:63], v[156:159], v[188:191], v[60:63]
	v_mfma_f32_16x16x32_bf16 v[56:59], v[164:167], v[188:191], v[56:59]
	v_mfma_f32_16x16x32_bf16 v[52:55], v[156:159], v[196:199], v[52:55]
	v_mfma_f32_16x16x32_bf16 v[48:51], v[164:167], v[196:199], v[48:51]
	v_mfma_f32_16x16x32_bf16 v[28:31], v[156:159], v[204:207], v[28:31]
	v_mfma_f32_16x16x32_bf16 v[24:27], v[164:167], v[204:207], v[24:27]
	v_mfma_f32_16x16x32_bf16 v[20:23], v[156:159], v[212:215], v[20:23]
	v_mfma_f32_16x16x32_bf16 v[16:19], v[164:167], v[212:215], v[16:19]
	v_mfma_f32_16x16x32_bf16 v[44:47], v[168:171], v[184:187], v[44:47]
	v_mfma_f32_16x16x32_bf16 v[40:43], v[176:179], v[184:187], v[40:43]
	v_mfma_f32_16x16x32_bf16 v[36:39], v[168:171], v[192:195], v[36:39]
	v_mfma_f32_16x16x32_bf16 v[32:35], v[176:179], v[192:195], v[32:35]
	v_mfma_f32_16x16x32_bf16 v[12:15], v[168:171], v[200:203], v[12:15]
	v_mfma_f32_16x16x32_bf16 v[8:11], v[176:179], v[200:203], v[8:11]
	v_mfma_f32_16x16x32_bf16 v[4:7], v[168:171], v[208:211], v[4:7]
	v_mfma_f32_16x16x32_bf16 v[0:3], v[176:179], v[208:211], v[0:3]
	v_mfma_f32_16x16x32_bf16 v[44:47], v[172:175], v[188:191], v[44:47]
	v_mfma_f32_16x16x32_bf16 v[40:43], v[180:183], v[188:191], v[40:43]
	v_mfma_f32_16x16x32_bf16 v[36:39], v[172:175], v[196:199], v[36:39]
	v_mfma_f32_16x16x32_bf16 v[32:35], v[180:183], v[196:199], v[32:35]
	v_mfma_f32_16x16x32_bf16 v[12:15], v[172:175], v[204:207], v[12:15]
	v_mfma_f32_16x16x32_bf16 v[8:11], v[180:183], v[204:207], v[8:11]
	v_mfma_f32_16x16x32_bf16 v[4:7], v[172:175], v[212:215], v[4:7]
	v_mfma_f32_16x16x32_bf16 v[0:3], v[180:183], v[212:215], v[0:3]
	s_barrier
	s_add_i32 s49, 0, 0x18000
	s_add_i32 s50, 0, 0x1c000
	v_add_u32_e32 v164, s49, v151
	v_add_u32_e32 v180, s50, v151
	ds_read_b128 v[144:147], v164
	ds_read_b128 v[156:159], v164 offset:1024
	ds_read_b128 v[160:163], v164 offset:2048
	ds_read_b128 v[164:167], v164 offset:3072
	ds_read_b128 v[168:171], v180
	ds_read_b128 v[172:175], v180 offset:1024
	ds_read_b128 v[176:179], v180 offset:2048
	ds_read_b128 v[180:183], v180 offset:3072
	s_add_u32 s16, s22, 0x160000
	s_addc_u32 s17, s23, 0
	s_mov_b32 m0, s34
	v_lshl_add_u64 v[222:223], s[16:17], 0, v[128:129]
	ds_read_b128 v[184:187], v155 offset:32768
	ds_read_b128 v[188:191], v155 offset:33792
	ds_read_b128 v[192:195], v155 offset:34816
	ds_read_b128 v[196:199], v155 offset:35840
	ds_read_b128 v[200:203], v155 offset:36864
	ds_read_b128 v[204:207], v155 offset:37888
	ds_read_b128 v[208:211], v155 offset:38912
	ds_read_b128 v[212:215], v155 offset:39936
	global_load_lds_dwordx4 v[222:223], off
	v_lshl_add_u64 v[222:223], s[16:17], 0, v[132:133]
	s_mov_b32 m0, s35
	s_nop 0
	global_load_lds_dwordx4 v[222:223], off
	s_waitcnt vmcnt(8)
	s_waitcnt lgkmcnt(0)
	s_barrier
	v_mfma_f32_16x16x32_bf16 v[124:127], v[144:147], v[184:187], v[124:127]
	v_mfma_f32_16x16x32_bf16 v[120:123], v[160:163], v[184:187], v[120:123]
	v_mfma_f32_16x16x32_bf16 v[116:119], v[144:147], v[192:195], v[116:119]
	v_mfma_f32_16x16x32_bf16 v[112:115], v[160:163], v[192:195], v[112:115]
	v_mfma_f32_16x16x32_bf16 v[92:95], v[144:147], v[200:203], v[92:95]
	v_mfma_f32_16x16x32_bf16 v[88:91], v[160:163], v[200:203], v[88:91]
	v_mfma_f32_16x16x32_bf16 v[84:87], v[144:147], v[208:211], v[84:87]
	v_mfma_f32_16x16x32_bf16 v[80:83], v[160:163], v[208:211], v[80:83]
	v_mfma_f32_16x16x32_bf16 v[124:127], v[156:159], v[188:191], v[124:127]
	v_mfma_f32_16x16x32_bf16 v[120:123], v[164:167], v[188:191], v[120:123]
	v_mfma_f32_16x16x32_bf16 v[116:119], v[156:159], v[196:199], v[116:119]
	v_mfma_f32_16x16x32_bf16 v[112:115], v[164:167], v[196:199], v[112:115]
	v_mfma_f32_16x16x32_bf16 v[92:95], v[156:159], v[204:207], v[92:95]
	v_mfma_f32_16x16x32_bf16 v[88:91], v[164:167], v[204:207], v[88:91]
	v_mfma_f32_16x16x32_bf16 v[84:87], v[156:159], v[212:215], v[84:87]
	v_mfma_f32_16x16x32_bf16 v[80:83], v[164:167], v[212:215], v[80:83]
	v_mfma_f32_16x16x32_bf16 v[108:111], v[168:171], v[184:187], v[108:111]
	v_mfma_f32_16x16x32_bf16 v[104:107], v[176:179], v[184:187], v[104:107]
	v_mfma_f32_16x16x32_bf16 v[100:103], v[168:171], v[192:195], v[100:103]
	v_mfma_f32_16x16x32_bf16 v[96:99], v[176:179], v[192:195], v[96:99]
	v_mfma_f32_16x16x32_bf16 v[76:79], v[168:171], v[200:203], v[76:79]
	v_mfma_f32_16x16x32_bf16 v[72:75], v[176:179], v[200:203], v[72:75]
	v_mfma_f32_16x16x32_bf16 v[68:71], v[168:171], v[208:211], v[68:71]
	v_mfma_f32_16x16x32_bf16 v[64:67], v[176:179], v[208:211], v[64:67]
	v_mfma_f32_16x16x32_bf16 v[108:111], v[172:175], v[188:191], v[108:111]
	v_mfma_f32_16x16x32_bf16 v[104:107], v[180:183], v[188:191], v[104:107]
	v_mfma_f32_16x16x32_bf16 v[100:103], v[172:175], v[196:199], v[100:103]
	v_mfma_f32_16x16x32_bf16 v[96:99], v[180:183], v[196:199], v[96:99]
	v_mfma_f32_16x16x32_bf16 v[76:79], v[172:175], v[204:207], v[76:79]
	v_mfma_f32_16x16x32_bf16 v[72:75], v[180:183], v[204:207], v[72:75]
	v_mfma_f32_16x16x32_bf16 v[68:71], v[172:175], v[212:215], v[68:71]
	v_mfma_f32_16x16x32_bf16 v[64:67], v[180:183], v[212:215], v[64:67]
	s_barrier
; #define PG8_STAGE(bufoff, gbase, voff) do { _Pragma("unroll") for (int _i = 0; _i < 2; ++_i) \
;         __builtin_amdgcn_global_load_lds((const unsigned*)((const char*)(gbase) + (voff)[_i]), (PG8_LAS unsigned*)(lds + (bufoff) + ldsw + _i * 8192), 16, 0, 0); } while (0)
; #define PG8_LDA(dst, b, h) do { _Pragma("unroll") for (int m = 0; m < 4; ++m) _Pragma("unroll") for (int k = 0; k < 2; ++k) dst[m][k] = *(const PG8_LAS bf16x8*)(lds + PG8_SA(b, h) + aoff + m * 2048 + k * 1024); } while (0)
; #define PG8_MMA(ai, bj, At, Bt) do { __builtin_amdgcn_s_setprio(1); _Pragma("unroll") for (int m = 0; m < 4; ++m) _Pragma("unroll") for (int n = 0; n < 2; ++n) _Pragma("unroll") for (int k = 0; k < 2; ++k) \
;         acc[ai][bj][m][n] = __builtin_amdgcn_mfma_f32_16x16x32_bf16(Bt[n][k], At[m][k], acc[ai][bj][m][n], 0, 0, 0); __builtin_amdgcn_s_setprio(0); } while (0)
; #define PG8_WAIT_V(n) asm volatile("s_waitcnt vmcnt(" #n ")" ::: "memory")
; #define PG8_WAIT_L(n) asm volatile("s_waitcnt lgkmcnt(" #n ")" ::: "memory")
; #define PG8_BAR __builtin_amdgcn_s_barrier()
; #define PG8_SCHED __builtin_amdgcn_sched_barrier(0)
; template <class Epi, class Sched, bool ALIGN_EPI = false, bool SP2 = false>
; __device__ __forceinline__ void gemm_phase(PG8_LAS unsigned char* lds, const Gemm g, const Sched& S, const Epi& E, const int wv0) {
;     ...
;             PG8_LDA(At, 1, 1); PG8_STAGE(PG8_SB(1, 0), b3, voffB); PG8_STAGE(PG8_SB(1, 1), b3 + hstepB, voffB); PG8_STAGE(PG8_SA(1, 0), a3, voffA);
;             PG8_WAIT_V(8); PG8_WAIT_L(0); PG8_BAR; PG8_MMA(1, 0, At, B0); PG8_MMA(1, 1, At, B1); PG8_BAR; PG8_SCHED;
;     ...
;         if constexpr (ALIGN_EPI) { if (wr == 0) PG8_BAR; }
	ds_read_b128 v[184:187], v155 offset:49152
	ds_read_b128 v[188:191], v155 offset:50176
	ds_read_b128 v[192:195], v155 offset:51200
	ds_read_b128 v[196:199], v155 offset:52224
	ds_read_b128 v[200:203], v155 offset:53248
	ds_read_b128 v[204:207], v155 offset:54272
	ds_read_b128 v[208:211], v155 offset:55296
	ds_read_b128 v[212:215], v155 offset:56320
	s_add_i32 s16, s49, s29
	s_mov_b32 m0, s16
	v_lshl_add_u64 v[148:149], v[148:149], 0, s[8:9]
	global_load_lds_dwordx4 v[148:149], off
	s_add_i32 m0, s16, 0x2000
	s_add_u32 s16, s20, 0x160080
	v_lshl_add_u64 v[148:149], v[216:217], 0, s[8:9]
	s_addc_u32 s17, s21, 0
	s_add_i32 s20, s50, s29
	global_load_lds_dwordx4 v[148:149], off
	v_lshl_add_u64 v[148:149], s[16:17], 0, v[130:131]
	s_mov_b32 m0, s20
	s_nop 0
	global_load_lds_dwordx4 v[148:149], off
	v_lshl_add_u64 v[148:149], s[16:17], 0, v[134:135]
	s_add_i32 m0, s20, 0x2000
	s_nop 0
	global_load_lds_dwordx4 v[148:149], off
	v_lshl_add_u64 v[148:149], v[218:219], 0, s[8:9]
	s_mov_b32 m0, s37
	s_nop 0
	global_load_lds_dwordx4 v[148:149], off
	v_lshl_add_u64 v[148:149], v[220:221], 0, s[8:9]
	s_mov_b32 m0, s38
	s_nop 0
	global_load_lds_dwordx4 v[148:149], off
	s_waitcnt vmcnt(8)
	s_waitcnt lgkmcnt(0)
	s_barrier
	v_mfma_f32_16x16x32_bf16 v[60:63], v[144:147], v[184:187], v[60:63]
	v_mfma_f32_16x16x32_bf16 v[56:59], v[160:163], v[184:187], v[56:59]
	v_mfma_f32_16x16x32_bf16 v[52:55], v[144:147], v[192:195], v[52:55]
	v_mfma_f32_16x16x32_bf16 v[48:51], v[160:163], v[192:195], v[48:51]
	v_mfma_f32_16x16x32_bf16 v[28:31], v[144:147], v[200:203], v[28:31]
	v_mfma_f32_16x16x32_bf16 v[24:27], v[160:163], v[200:203], v[24:27]
	v_mfma_f32_16x16x32_bf16 v[20:23], v[144:147], v[208:211], v[20:23]
	v_mfma_f32_16x16x32_bf16 v[16:19], v[160:163], v[208:211], v[16:19]
	v_mfma_f32_16x16x32_bf16 v[60:63], v[156:159], v[188:191], v[60:63]
	v_mfma_f32_16x16x32_bf16 v[56:59], v[164:167], v[188:191], v[56:59]
	v_mfma_f32_16x16x32_bf16 v[52:55], v[156:159], v[196:199], v[52:55]
	v_mfma_f32_16x16x32_bf16 v[48:51], v[164:167], v[196:199], v[48:51]
	v_mfma_f32_16x16x32_bf16 v[28:31], v[156:159], v[204:207], v[28:31]
	v_mfma_f32_16x16x32_bf16 v[24:27], v[164:167], v[204:207], v[24:27]
	v_mfma_f32_16x16x32_bf16 v[20:23], v[156:159], v[212:215], v[20:23]
	v_mfma_f32_16x16x32_bf16 v[16:19], v[164:167], v[212:215], v[16:19]
	v_mfma_f32_16x16x32_bf16 v[44:47], v[168:171], v[184:187], v[44:47]
	v_mfma_f32_16x16x32_bf16 v[40:43], v[176:179], v[184:187], v[40:43]
	v_mfma_f32_16x16x32_bf16 v[36:39], v[168:171], v[192:195], v[36:39]
	v_mfma_f32_16x16x32_bf16 v[32:35], v[176:179], v[192:195], v[32:35]
	v_mfma_f32_16x16x32_bf16 v[12:15], v[168:171], v[200:203], v[12:15]
	v_mfma_f32_16x16x32_bf16 v[8:11], v[176:179], v[200:203], v[8:11]
	v_mfma_f32_16x16x32_bf16 v[4:7], v[168:171], v[208:211], v[4:7]
	v_mfma_f32_16x16x32_bf16 v[0:3], v[176:179], v[208:211], v[0:3]
	v_mfma_f32_16x16x32_bf16 v[44:47], v[172:175], v[188:191], v[44:47]
	v_mfma_f32_16x16x32_bf16 v[40:43], v[180:183], v[188:191], v[40:43]
	v_mfma_f32_16x16x32_bf16 v[36:39], v[172:175], v[196:199], v[36:39]
	v_mfma_f32_16x16x32_bf16 v[32:35], v[180:183], v[196:199], v[32:35]
	v_mfma_f32_16x16x32_bf16 v[12:15], v[172:175], v[204:207], v[12:15]
	v_mfma_f32_16x16x32_bf16 v[8:11], v[180:183], v[204:207], v[8:11]
	v_mfma_f32_16x16x32_bf16 v[4:7], v[172:175], v[212:215], v[4:7]
	v_mfma_f32_16x16x32_bf16 v[0:3], v[180:183], v[212:215], v[0:3]
	s_barrier
	s_add_i32 s48, s48, 2
	s_add_u32 s46, s46, 0x100
	s_addc_u32 s47, s47, 0
	s_cmpk_gt_u32 s48, 0x55
	s_mov_b64 s[16:17], s[18:19]
	s_cbranch_scc0 .LBB0_1808
	s_and_b64 vcc, exec, s[10:11]
	s_cbranch_vccz .LBB0_1811
	s_barrier
